# residual-GEMM epilogues rewritten by hand (batched loads, counted waits) for both layers; RWKV scan loops hand-written; f32/bf16 precision unchanged
# speedup vs baseline: 1.0438x; 1.0330x over previous
.LBB0_592:
	s_or_b64 exec, exec, s[4:5]
	v_mov_b32_e32 v1, v190
	s_waitcnt lgkmcnt(0)
	s_barrier
	s_nop 0
	v_ashrrev_i32_e32 v0, 6, v1
	v_cmp_lt_i32_e32 vcc, 1, v0
	s_and_saveexec_b64 s[4:5], vcc
	s_xor_b64 s[16:17], exec, s[4:5]
	s_cbranch_execz .LBB0_636
	v_mov_b32_e32 v2, 1
	v_cmp_ne_u32_e32 vcc, 0, v2
	s_and_saveexec_b64 s[18:19], vcc
	s_cbranch_execz .LBB0_635
	v_add_u32_e32 v113, -2, v0
	v_readlane_b32 s2, v240, 10
	v_readfirstlane_b32 s23, v0
	s_movk_i32 s3, 0x1000
	v_mad_u32_u24 v112, s2, 6, v113
	v_cmp_gt_i32_e32 vcc, s3, v112
	s_and_saveexec_b64 s[20:21], vcc
	s_cbranch_execz .LBB0_607
	s_and_b32 s3, s23, 2
	s_cmp_eq_u32 s3, 0
	s_cbranch_scc1 .Lps_done
	s_and_b32 s3, s23, 1
	s_lshr_b32 s4, s23, 2
	s_lshl_b32 s4, s4, 1
	s_add_i32 s3, s3, s4
	s_lshl_b32 s22, s2, 2
	s_add_i32 s22, s22, s3
	v_and_b32_e32 v166, 63, v190
	v_and_b32_e32 v167, 15, v166
	v_lshrrev_b32_e32 v168, 4, v166
	v_and_b32_e32 v169, 1, v167
	v_cmp_ne_u32_e64 s[100:101], 0, v169
	v_and_b32_e32 v171, 2, v167
	v_cmp_ne_u32_e64 s[98:99], 0, v171
	v_and_b32_e32 v169, 3, v167
	s_add_u32 s36, s92, 0x17c24000
	s_addc_u32 s37, s93, 0
	s_and_b32 s37, s37, 0xffff
	s_mov_b32 s38, 0x20000000
	s_mov_b32 s39, 0x20000
	s_add_u32 s40, s92, 0x23c24000
	s_addc_u32 s41, s93, 0
	s_and_b32 s41, s41, 0xffff
	s_mov_b32 s42, 0x20000000
	s_mov_b32 s43, 0x20000
	s_mov_b32 s44, s90
	s_mov_b32 s45, s91
	s_and_b32 s45, s45, 0xffff
	s_mov_b32 s46, 0x10000000
	s_mov_b32 s47, 0x20000
.Lps_item:
	s_cmpk_lt_i32 s22, 0x1000
	s_cbranch_scc0 .Lps_done
	s_and_b32 s3, s22, 3
	s_lshr_b32 s23, s22, 2
	s_bfe_u32 s31, s23, 0x10004
	s_lshr_b32 s25, s23, 5
	s_and_b32 s23, s23, 15
	s_lshl_b32 s24, s25, 1
	s_add_i32 s24, s24, s31
	s_lshl_b32 s24, s24, 4
	s_add_i32 s24, s24, s23
	s_lshl_b32 s24, s24, 14
	s_add_u32 s10, s90, 0x9000000
	s_addc_u32 s11, s91, 0
	s_add_u32 s10, s10, s24
	s_addc_u32 s11, s11, 0
	v_mov_b32_e32 v96, 0
	v_mov_b32_e32 v97, 0
	v_mov_b32_e32 v98, 0
	v_mov_b32_e32 v99, 0
	v_mov_b32_e32 v100, 0
	v_mov_b32_e32 v101, 0
	v_mov_b32_e32 v102, 0
	v_mov_b32_e32 v103, 0
	v_mov_b32_e32 v104, 0
	v_mov_b32_e32 v105, 0
	v_mov_b32_e32 v106, 0
	v_mov_b32_e32 v107, 0
	v_mov_b32_e32 v108, 0
	v_mov_b32_e32 v109, 0
	v_mov_b32_e32 v110, 0
	v_mov_b32_e32 v111, 0
	s_lshl_b32 s24, s23, 8
	v_lshl_add_u32 v159, v167, 4, s24
	s_lshl_b32 s23, s31, 12
	v_add_u32_e32 v161, s23, v159
	s_lshl_b32 s4, s3, 6
	s_add_i32 s4, s4, s24
	v_lshl_add_u32 v170, v168, 4, s4
	v_lshl_add_u32 v164, v169, 2, v170
	v_add_u32_e32 v164, s23, v164
	v_add_u32_e32 v158, 0x4000000, v159
	v_add_u32_e32 v160, 0x8000000, v170
	v_add_u32_e32 v162, 0x8000000, v161
	v_add_u32_e32 v163, 0x10000000, v161
	s_lshl_b32 s4, s3, 12
	v_lshlrev_b32_e32 v166, 10, v168
	v_lshl_add_u32 v166, v167, 4, v166
	v_add_u32_e32 v166, s4, v166
	s_lshl_b32 s30, s25, 8
	s_mul_i32 s8, s31, 0xff
	s_add_i32 s30, s30, s8
	s_lshl_b32 s8, s30, 12
	s_lshl_b32 s9, s30, 13
	s_mov_b32 s24, s9
	s_mul_i32 s25, s31, 0xffffe000
	s_addk_i32 s25, 0x1000
	s_lshl_b32 s30, s25, 1
	buffer_load_dwordx4 v[0:3], v158, s[36:39], s8 offen
	buffer_load_dwordx4 v[12:15], v163, s[40:43], s9 offen
	buffer_load_dwordx4 v[20:23], v160, s[36:39], s8 offen
	buffer_load_dwordx4 v[4:7], v161, s[40:43], s9 offen
	buffer_load_dwordx4 v[8:11], v162, s[40:43], s9 offen
	buffer_load_dwordx4 v[16:19], v159, s[36:39], s8 offen
	s_add_i32 s8, s8, s25
	s_add_i32 s9, s9, s30
	buffer_load_dwordx4 v[24:27], v158, s[36:39], s8 offen
	buffer_load_dwordx4 v[36:39], v163, s[40:43], s9 offen
	buffer_load_dwordx4 v[44:47], v160, s[36:39], s8 offen
	buffer_load_dwordx4 v[28:31], v161, s[40:43], s9 offen
	buffer_load_dwordx4 v[32:35], v162, s[40:43], s9 offen
	buffer_load_dwordx4 v[40:43], v159, s[36:39], s8 offen
	s_add_i32 s8, s8, s25
	s_add_i32 s9, s9, s30
	buffer_load_dwordx4 v[48:51], v158, s[36:39], s8 offen
	buffer_load_dwordx4 v[60:63], v163, s[40:43], s9 offen
	buffer_load_dwordx4 v[68:71], v160, s[36:39], s8 offen
	buffer_load_dwordx4 v[52:55], v161, s[40:43], s9 offen
	buffer_load_dwordx4 v[56:59], v162, s[40:43], s9 offen
	buffer_load_dwordx4 v[64:67], v159, s[36:39], s8 offen
	s_add_i32 s8, s8, s25
	s_add_i32 s9, s9, s30
	buffer_load_dwordx4 v[72:75], v158, s[36:39], s8 offen
	buffer_load_dwordx4 v[84:87], v163, s[40:43], s9 offen
	buffer_load_dwordx4 v[92:95], v160, s[36:39], s8 offen
	buffer_load_dwordx4 v[76:79], v161, s[40:43], s9 offen
	buffer_load_dwordx4 v[80:83], v162, s[40:43], s9 offen
	buffer_load_dwordx4 v[88:91], v159, s[36:39], s8 offen
	s_add_i32 s8, s8, s25
	s_add_i32 s9, s9, s30
	s_movk_i32 s31, 62
	s_waitcnt vmcnt(18)
	v_pk_mul_f32 v[114:115], v[96:97], v[0:1]
	v_pk_mul_f32 v[116:117], v[100:101], v[0:1]
	v_pk_mul_f32 v[118:119], v[104:105], v[0:1]
	v_pk_mul_f32 v[120:121], v[108:109], v[0:1]
	v_pk_fma_f32 v[114:115], v[98:99], v[2:3], v[114:115]
	v_pk_fma_f32 v[116:117], v[102:103], v[2:3], v[116:117]
	v_pk_fma_f32 v[118:119], v[106:107], v[2:3], v[118:119]
	v_pk_fma_f32 v[120:121], v[110:111], v[2:3], v[120:121]
	v_add_f32_e32 v122, v114, v115
	v_add_f32_e32 v123, v116, v117
	v_add_f32_e32 v124, v118, v119
	v_add_f32_e32 v125, v120, v121
	v_add_f32_dpp v122, v122, v122 quad_perm:[1,0,3,2] row_mask:0xf bank_mask:0xf bound_ctrl:1
	v_add_f32_dpp v123, v123, v123 quad_perm:[1,0,3,2] row_mask:0xf bank_mask:0xf bound_ctrl:1
	v_add_f32_dpp v124, v124, v124 quad_perm:[1,0,3,2] row_mask:0xf bank_mask:0xf bound_ctrl:1
	v_add_f32_dpp v125, v125, v125 quad_perm:[1,0,3,2] row_mask:0xf bank_mask:0xf bound_ctrl:1
	v_add_f32_dpp v122, v122, v122 quad_perm:[2,3,0,1] row_mask:0xf bank_mask:0xf bound_ctrl:1
	v_add_f32_dpp v123, v123, v123 quad_perm:[2,3,0,1] row_mask:0xf bank_mask:0xf bound_ctrl:1
	v_add_f32_dpp v124, v124, v124 quad_perm:[2,3,0,1] row_mask:0xf bank_mask:0xf bound_ctrl:1
	v_add_f32_dpp v125, v125, v125 quad_perm:[2,3,0,1] row_mask:0xf bank_mask:0xf bound_ctrl:1
	v_add_f32_dpp v122, v122, v122 row_ror:4 row_mask:0xf bank_mask:0xf bound_ctrl:1
	v_add_f32_dpp v123, v123, v123 row_ror:4 row_mask:0xf bank_mask:0xf bound_ctrl:1
	v_add_f32_dpp v124, v124, v124 row_ror:4 row_mask:0xf bank_mask:0xf bound_ctrl:1
	v_add_f32_dpp v125, v125, v125 row_ror:4 row_mask:0xf bank_mask:0xf bound_ctrl:1
	v_pk_mul_f32 v[126:127], v[20:21], v[12:13] op_sel_hi:[0,1]
	v_pk_mul_f32 v[130:131], v[20:21], v[12:13] op_sel:[1,0]
	v_pk_mul_f32 v[134:135], v[22:23], v[12:13] op_sel_hi:[0,1]
	v_pk_mul_f32 v[138:139], v[22:23], v[12:13] op_sel:[1,0]
	v_pk_mul_f32 v[128:129], v[20:21], v[14:15] op_sel_hi:[0,1]
	v_pk_mul_f32 v[132:133], v[20:21], v[14:15] op_sel:[1,0]
	v_pk_mul_f32 v[136:137], v[22:23], v[14:15] op_sel_hi:[0,1]
	v_pk_mul_f32 v[140:141], v[22:23], v[14:15] op_sel:[1,0]
	v_pk_fma_f32 v[126:127], v[96:97], v[4:5], v[126:127]
	v_pk_fma_f32 v[130:131], v[100:101], v[4:5], v[130:131]
	v_pk_fma_f32 v[134:135], v[104:105], v[4:5], v[134:135]
	v_pk_fma_f32 v[138:139], v[108:109], v[4:5], v[138:139]
	v_add_f32_dpp v122, v122, v122 row_ror:8 row_mask:0xf bank_mask:0xf bound_ctrl:1
	v_add_f32_dpp v123, v123, v123 row_ror:8 row_mask:0xf bank_mask:0xf bound_ctrl:1
	v_add_f32_dpp v124, v124, v124 row_ror:8 row_mask:0xf bank_mask:0xf bound_ctrl:1
	v_add_f32_dpp v125, v125, v125 row_ror:8 row_mask:0xf bank_mask:0xf bound_ctrl:1
	v_pk_fma_f32 v[128:129], v[98:99], v[6:7], v[128:129]
	v_pk_fma_f32 v[132:133], v[102:103], v[6:7], v[132:133]
	v_pk_fma_f32 v[136:137], v[106:107], v[6:7], v[136:137]
	v_pk_fma_f32 v[140:141], v[110:111], v[6:7], v[140:141]
	v_pk_fma_f32 v[96:97], v[8:9], v[122:123], v[126:127] op_sel_hi:[1,0,1] neg_lo:[0,1,0] neg_hi:[0,1,0]
	v_pk_fma_f32 v[100:101], v[8:9], v[122:123], v[130:131] op_sel:[0,1,0] neg_lo:[0,1,0] neg_hi:[0,1,0]
	v_pk_fma_f32 v[104:105], v[8:9], v[124:125], v[134:135] op_sel_hi:[1,0,1] neg_lo:[0,1,0] neg_hi:[0,1,0]
	v_pk_fma_f32 v[108:109], v[8:9], v[124:125], v[138:139] op_sel:[0,1,0] neg_lo:[0,1,0] neg_hi:[0,1,0]
	v_pk_fma_f32 v[98:99], v[10:11], v[122:123], v[128:129] op_sel_hi:[1,0,1] neg_lo:[0,1,0] neg_hi:[0,1,0]
	v_pk_fma_f32 v[102:103], v[10:11], v[122:123], v[132:133] op_sel:[0,1,0] neg_lo:[0,1,0] neg_hi:[0,1,0]
	v_pk_fma_f32 v[106:107], v[10:11], v[124:125], v[136:137] op_sel_hi:[1,0,1] neg_lo:[0,1,0] neg_hi:[0,1,0]
	v_pk_fma_f32 v[110:111], v[10:11], v[124:125], v[140:141] op_sel:[0,1,0] neg_lo:[0,1,0] neg_hi:[0,1,0]
	v_pk_mul_f32 v[142:143], v[96:97], v[16:17]
	v_pk_mul_f32 v[144:145], v[100:101], v[16:17]
	v_pk_mul_f32 v[146:147], v[104:105], v[16:17]
	v_pk_mul_f32 v[148:149], v[108:109], v[16:17]
	v_pk_fma_f32 v[142:143], v[98:99], v[18:19], v[142:143]
	v_pk_fma_f32 v[144:145], v[102:103], v[18:19], v[144:145]
	v_pk_fma_f32 v[146:147], v[106:107], v[18:19], v[146:147]
	v_pk_fma_f32 v[148:149], v[110:111], v[18:19], v[148:149]
	v_add_f32_e32 v150, v142, v143
	v_add_f32_e32 v151, v144, v145
	v_add_f32_e32 v152, v146, v147
	v_add_f32_e32 v153, v148, v149
	v_cndmask_b32_e64 v154, v150, v151, s[100:101]
	v_cndmask_b32_e64 v155, v151, v150, s[100:101]
	v_cndmask_b32_e64 v156, v152, v153, s[100:101]
	v_cndmask_b32_e64 v157, v153, v152, s[100:101]
	v_add_f32_dpp v154, v155, v154 quad_perm:[1,0,3,2] row_mask:0xf bank_mask:0xf bound_ctrl:1
	buffer_load_dwordx4 v[0:3], v158, s[36:39], s8 offen
	v_add_f32_dpp v156, v157, v156 quad_perm:[1,0,3,2] row_mask:0xf bank_mask:0xf bound_ctrl:1
	v_cndmask_b32_e64 v155, v154, v156, s[98:99]
	v_cndmask_b32_e64 v157, v156, v154, s[98:99]
	buffer_load_dwordx4 v[12:15], v163, s[40:43], s9 offen
	buffer_load_dwordx4 v[20:23], v160, s[36:39], s8 offen
	v_add_f32_dpp v155, v157, v155 quad_perm:[2,3,0,1] row_mask:0xf bank_mask:0xf bound_ctrl:1
	buffer_load_dwordx4 v[4:7], v161, s[40:43], s9 offen
	buffer_load_dwordx4 v[8:11], v162, s[40:43], s9 offen
	v_add_f32_dpp v155, v155, v155 row_ror:4 row_mask:0xf bank_mask:0xf bound_ctrl:1
	buffer_load_dwordx4 v[16:19], v159, s[36:39], s8 offen
	s_add_i32 s8, s8, s25
	v_add_f32_dpp v155, v155, v155 row_ror:8 row_mask:0xf bank_mask:0xf bound_ctrl:1
	s_add_i32 s9, s9, s30
	s_nop 1
.Lps_loop:
	s_waitcnt vmcnt(18)
	v_pk_mul_f32 v[114:115], v[96:97], v[24:25]
	v_pk_mul_f32 v[116:117], v[100:101], v[24:25]
	v_pk_mul_f32 v[118:119], v[104:105], v[24:25]
	v_pk_mul_f32 v[120:121], v[108:109], v[24:25]
	v_pk_fma_f32 v[114:115], v[98:99], v[26:27], v[114:115]
	v_pk_fma_f32 v[116:117], v[102:103], v[26:27], v[116:117]
	v_pk_fma_f32 v[118:119], v[106:107], v[26:27], v[118:119]
	v_pk_fma_f32 v[120:121], v[110:111], v[26:27], v[120:121]
	v_add_f32_e32 v122, v114, v115
	v_add_f32_e32 v123, v116, v117
	v_add_f32_e32 v124, v118, v119
	v_add_f32_e32 v125, v120, v121
	v_add_f32_dpp v122, v122, v122 quad_perm:[1,0,3,2] row_mask:0xf bank_mask:0xf bound_ctrl:1
	v_add_f32_dpp v123, v123, v123 quad_perm:[1,0,3,2] row_mask:0xf bank_mask:0xf bound_ctrl:1
	v_add_f32_dpp v124, v124, v124 quad_perm:[1,0,3,2] row_mask:0xf bank_mask:0xf bound_ctrl:1
	v_add_f32_dpp v125, v125, v125 quad_perm:[1,0,3,2] row_mask:0xf bank_mask:0xf bound_ctrl:1
	v_add_f32_dpp v122, v122, v122 quad_perm:[2,3,0,1] row_mask:0xf bank_mask:0xf bound_ctrl:1
	v_add_f32_dpp v123, v123, v123 quad_perm:[2,3,0,1] row_mask:0xf bank_mask:0xf bound_ctrl:1
	v_add_f32_dpp v124, v124, v124 quad_perm:[2,3,0,1] row_mask:0xf bank_mask:0xf bound_ctrl:1
	v_add_f32_dpp v125, v125, v125 quad_perm:[2,3,0,1] row_mask:0xf bank_mask:0xf bound_ctrl:1
	v_add_f32_dpp v122, v122, v122 row_ror:4 row_mask:0xf bank_mask:0xf bound_ctrl:1
	v_add_f32_dpp v123, v123, v123 row_ror:4 row_mask:0xf bank_mask:0xf bound_ctrl:1
	v_add_f32_dpp v124, v124, v124 row_ror:4 row_mask:0xf bank_mask:0xf bound_ctrl:1
	v_add_f32_dpp v125, v125, v125 row_ror:4 row_mask:0xf bank_mask:0xf bound_ctrl:1
	v_pk_mul_f32 v[126:127], v[44:45], v[36:37] op_sel_hi:[0,1]
	v_pk_mul_f32 v[130:131], v[44:45], v[36:37] op_sel:[1,0]
	v_pk_mul_f32 v[134:135], v[46:47], v[36:37] op_sel_hi:[0,1]
	v_pk_mul_f32 v[138:139], v[46:47], v[36:37] op_sel:[1,0]
	v_pk_mul_f32 v[128:129], v[44:45], v[38:39] op_sel_hi:[0,1]
	v_pk_mul_f32 v[132:133], v[44:45], v[38:39] op_sel:[1,0]
	v_pk_mul_f32 v[136:137], v[46:47], v[38:39] op_sel_hi:[0,1]
	v_pk_mul_f32 v[140:141], v[46:47], v[38:39] op_sel:[1,0]
	v_pk_fma_f32 v[126:127], v[96:97], v[28:29], v[126:127]
	v_pk_fma_f32 v[130:131], v[100:101], v[28:29], v[130:131]
	v_pk_fma_f32 v[134:135], v[104:105], v[28:29], v[134:135]
	v_pk_fma_f32 v[138:139], v[108:109], v[28:29], v[138:139]
	v_add_f32_dpp v122, v122, v122 row_ror:8 row_mask:0xf bank_mask:0xf bound_ctrl:1
	v_add_f32_dpp v123, v123, v123 row_ror:8 row_mask:0xf bank_mask:0xf bound_ctrl:1
	v_add_f32_dpp v124, v124, v124 row_ror:8 row_mask:0xf bank_mask:0xf bound_ctrl:1
	v_add_f32_dpp v125, v125, v125 row_ror:8 row_mask:0xf bank_mask:0xf bound_ctrl:1
	buffer_store_dword v155, v164, s[44:47], s24 offen
	v_pk_fma_f32 v[128:129], v[98:99], v[30:31], v[128:129]
	v_pk_fma_f32 v[132:133], v[102:103], v[30:31], v[132:133]
	v_pk_fma_f32 v[136:137], v[106:107], v[30:31], v[136:137]
	v_pk_fma_f32 v[140:141], v[110:111], v[30:31], v[140:141]
	v_pk_fma_f32 v[96:97], v[32:33], v[122:123], v[126:127] op_sel_hi:[1,0,1] neg_lo:[0,1,0] neg_hi:[0,1,0]
	v_pk_fma_f32 v[100:101], v[32:33], v[122:123], v[130:131] op_sel:[0,1,0] neg_lo:[0,1,0] neg_hi:[0,1,0]
	v_pk_fma_f32 v[104:105], v[32:33], v[124:125], v[134:135] op_sel_hi:[1,0,1] neg_lo:[0,1,0] neg_hi:[0,1,0]
	v_pk_fma_f32 v[108:109], v[32:33], v[124:125], v[138:139] op_sel:[0,1,0] neg_lo:[0,1,0] neg_hi:[0,1,0]
	v_pk_fma_f32 v[98:99], v[34:35], v[122:123], v[128:129] op_sel_hi:[1,0,1] neg_lo:[0,1,0] neg_hi:[0,1,0]
	v_pk_fma_f32 v[102:103], v[34:35], v[122:123], v[132:133] op_sel:[0,1,0] neg_lo:[0,1,0] neg_hi:[0,1,0]
	v_pk_fma_f32 v[106:107], v[34:35], v[124:125], v[136:137] op_sel_hi:[1,0,1] neg_lo:[0,1,0] neg_hi:[0,1,0]
	v_pk_fma_f32 v[110:111], v[34:35], v[124:125], v[140:141] op_sel:[0,1,0] neg_lo:[0,1,0] neg_hi:[0,1,0]
	v_pk_mul_f32 v[142:143], v[96:97], v[40:41]
	v_pk_mul_f32 v[144:145], v[100:101], v[40:41]
	v_pk_mul_f32 v[146:147], v[104:105], v[40:41]
	v_pk_mul_f32 v[148:149], v[108:109], v[40:41]
	v_pk_fma_f32 v[142:143], v[98:99], v[42:43], v[142:143]
	v_pk_fma_f32 v[144:145], v[102:103], v[42:43], v[144:145]
	v_pk_fma_f32 v[146:147], v[106:107], v[42:43], v[146:147]
	v_pk_fma_f32 v[148:149], v[110:111], v[42:43], v[148:149]
	buffer_load_dwordx4 v[24:27], v158, s[36:39], s8 offen
	buffer_load_dwordx4 v[36:39], v163, s[40:43], s9 offen
	v_add_f32_e32 v150, v142, v143
	v_add_f32_e32 v151, v144, v145
	v_add_f32_e32 v152, v146, v147
	v_add_f32_e32 v153, v148, v149
	buffer_load_dwordx4 v[44:47], v160, s[36:39], s8 offen
	v_cndmask_b32_e64 v154, v150, v151, s[100:101]
	v_cndmask_b32_e64 v155, v151, v150, s[100:101]
	v_cndmask_b32_e64 v156, v152, v153, s[100:101]
	v_cndmask_b32_e64 v157, v153, v152, s[100:101]
	buffer_load_dwordx4 v[28:31], v161, s[40:43], s9 offen
	buffer_load_dwordx4 v[32:35], v162, s[40:43], s9 offen
	buffer_load_dwordx4 v[40:43], v159, s[36:39], s8 offen
	s_waitcnt vmcnt(19)
	v_pk_mul_f32 v[114:115], v[96:97], v[48:49]
	v_pk_mul_f32 v[116:117], v[100:101], v[48:49]
	v_pk_mul_f32 v[118:119], v[104:105], v[48:49]
	v_pk_mul_f32 v[120:121], v[108:109], v[48:49]
	v_pk_fma_f32 v[114:115], v[98:99], v[50:51], v[114:115]
	v_pk_fma_f32 v[116:117], v[102:103], v[50:51], v[116:117]
	v_pk_fma_f32 v[118:119], v[106:107], v[50:51], v[118:119]
	v_pk_fma_f32 v[120:121], v[110:111], v[50:51], v[120:121]
	v_add_f32_dpp v154, v155, v154 quad_perm:[1,0,3,2] row_mask:0xf bank_mask:0xf bound_ctrl:1
	v_add_f32_dpp v156, v157, v156 quad_perm:[1,0,3,2] row_mask:0xf bank_mask:0xf bound_ctrl:1
	v_cndmask_b32_e64 v155, v154, v156, s[98:99]
	v_cndmask_b32_e64 v157, v156, v154, s[98:99]
	v_add_f32_e32 v122, v114, v115
	v_add_f32_e32 v123, v116, v117
	v_add_f32_e32 v124, v118, v119
	v_add_f32_e32 v125, v120, v121
	v_add_f32_dpp v155, v157, v155 quad_perm:[2,3,0,1] row_mask:0xf bank_mask:0xf bound_ctrl:1
	v_add_f32_dpp v122, v122, v122 quad_perm:[1,0,3,2] row_mask:0xf bank_mask:0xf bound_ctrl:1
	v_add_f32_dpp v123, v123, v123 quad_perm:[1,0,3,2] row_mask:0xf bank_mask:0xf bound_ctrl:1
	v_add_f32_dpp v124, v124, v124 quad_perm:[1,0,3,2] row_mask:0xf bank_mask:0xf bound_ctrl:1
	v_add_f32_dpp v125, v125, v125 quad_perm:[1,0,3,2] row_mask:0xf bank_mask:0xf bound_ctrl:1
	v_add_f32_dpp v155, v155, v155 row_ror:4 row_mask:0xf bank_mask:0xf bound_ctrl:1
	v_add_f32_dpp v122, v122, v122 quad_perm:[2,3,0,1] row_mask:0xf bank_mask:0xf bound_ctrl:1
	v_add_f32_dpp v123, v123, v123 quad_perm:[2,3,0,1] row_mask:0xf bank_mask:0xf bound_ctrl:1
	v_add_f32_dpp v124, v124, v124 quad_perm:[2,3,0,1] row_mask:0xf bank_mask:0xf bound_ctrl:1
	v_add_f32_dpp v125, v125, v125 quad_perm:[2,3,0,1] row_mask:0xf bank_mask:0xf bound_ctrl:1
	v_add_f32_dpp v155, v155, v155 row_ror:8 row_mask:0xf bank_mask:0xf bound_ctrl:1
	v_add_f32_dpp v122, v122, v122 row_ror:4 row_mask:0xf bank_mask:0xf bound_ctrl:1
	v_add_f32_dpp v123, v123, v123 row_ror:4 row_mask:0xf bank_mask:0xf bound_ctrl:1
	v_add_f32_dpp v124, v124, v124 row_ror:4 row_mask:0xf bank_mask:0xf bound_ctrl:1
	v_add_f32_dpp v125, v125, v125 row_ror:4 row_mask:0xf bank_mask:0xf bound_ctrl:1
	v_pk_mul_f32 v[126:127], v[68:69], v[60:61] op_sel_hi:[0,1]
	v_pk_mul_f32 v[130:131], v[68:69], v[60:61] op_sel:[1,0]
	v_pk_mul_f32 v[134:135], v[70:71], v[60:61] op_sel_hi:[0,1]
	v_pk_mul_f32 v[138:139], v[70:71], v[60:61] op_sel:[1,0]
	s_add_i32 s24, s24, s30
	v_pk_mul_f32 v[128:129], v[68:69], v[62:63] op_sel_hi:[0,1]
	v_pk_mul_f32 v[132:133], v[68:69], v[62:63] op_sel:[1,0]
	v_pk_mul_f32 v[136:137], v[70:71], v[62:63] op_sel_hi:[0,1]
	v_pk_mul_f32 v[140:141], v[70:71], v[62:63] op_sel:[1,0]
	v_pk_fma_f32 v[126:127], v[96:97], v[52:53], v[126:127]
	v_pk_fma_f32 v[130:131], v[100:101], v[52:53], v[130:131]
	v_pk_fma_f32 v[134:135], v[104:105], v[52:53], v[134:135]
	v_pk_fma_f32 v[138:139], v[108:109], v[52:53], v[138:139]
	v_add_f32_dpp v122, v122, v122 row_ror:8 row_mask:0xf bank_mask:0xf bound_ctrl:1
	v_add_f32_dpp v123, v123, v123 row_ror:8 row_mask:0xf bank_mask:0xf bound_ctrl:1
	v_add_f32_dpp v124, v124, v124 row_ror:8 row_mask:0xf bank_mask:0xf bound_ctrl:1
	v_add_f32_dpp v125, v125, v125 row_ror:8 row_mask:0xf bank_mask:0xf bound_ctrl:1
	buffer_store_dword v155, v164, s[44:47], s24 offen
	v_pk_fma_f32 v[128:129], v[98:99], v[54:55], v[128:129]
	v_pk_fma_f32 v[132:133], v[102:103], v[54:55], v[132:133]
	v_pk_fma_f32 v[136:137], v[106:107], v[54:55], v[136:137]
	v_pk_fma_f32 v[140:141], v[110:111], v[54:55], v[140:141]
	v_pk_fma_f32 v[96:97], v[56:57], v[122:123], v[126:127] op_sel_hi:[1,0,1] neg_lo:[0,1,0] neg_hi:[0,1,0]
	v_pk_fma_f32 v[100:101], v[56:57], v[122:123], v[130:131] op_sel:[0,1,0] neg_lo:[0,1,0] neg_hi:[0,1,0]
	v_pk_fma_f32 v[104:105], v[56:57], v[124:125], v[134:135] op_sel_hi:[1,0,1] neg_lo:[0,1,0] neg_hi:[0,1,0]
	v_pk_fma_f32 v[108:109], v[56:57], v[124:125], v[138:139] op_sel:[0,1,0] neg_lo:[0,1,0] neg_hi:[0,1,0]
	v_pk_fma_f32 v[98:99], v[58:59], v[122:123], v[128:129] op_sel_hi:[1,0,1] neg_lo:[0,1,0] neg_hi:[0,1,0]
	v_pk_fma_f32 v[102:103], v[58:59], v[122:123], v[132:133] op_sel:[0,1,0] neg_lo:[0,1,0] neg_hi:[0,1,0]
	v_pk_fma_f32 v[106:107], v[58:59], v[124:125], v[136:137] op_sel_hi:[1,0,1] neg_lo:[0,1,0] neg_hi:[0,1,0]
	v_pk_fma_f32 v[110:111], v[58:59], v[124:125], v[140:141] op_sel:[0,1,0] neg_lo:[0,1,0] neg_hi:[0,1,0]
	v_pk_mul_f32 v[142:143], v[96:97], v[64:65]
	v_pk_mul_f32 v[144:145], v[100:101], v[64:65]
	v_pk_mul_f32 v[146:147], v[104:105], v[64:65]
	v_pk_mul_f32 v[148:149], v[108:109], v[64:65]
	s_add_i32 s8, s8, s25
	s_add_i32 s9, s9, s30
	v_pk_fma_f32 v[142:143], v[98:99], v[66:67], v[142:143]
	v_pk_fma_f32 v[144:145], v[102:103], v[66:67], v[144:145]
	v_pk_fma_f32 v[146:147], v[106:107], v[66:67], v[146:147]
	v_pk_fma_f32 v[148:149], v[110:111], v[66:67], v[148:149]
	buffer_load_dwordx4 v[48:51], v158, s[36:39], s8 offen
	buffer_load_dwordx4 v[60:63], v163, s[40:43], s9 offen
	v_add_f32_e32 v150, v142, v143
	v_add_f32_e32 v151, v144, v145
	v_add_f32_e32 v152, v146, v147
	v_add_f32_e32 v153, v148, v149
	buffer_load_dwordx4 v[68:71], v160, s[36:39], s8 offen
	v_cndmask_b32_e64 v154, v150, v151, s[100:101]
	v_cndmask_b32_e64 v155, v151, v150, s[100:101]
	v_cndmask_b32_e64 v156, v152, v153, s[100:101]
	v_cndmask_b32_e64 v157, v153, v152, s[100:101]
	buffer_load_dwordx4 v[52:55], v161, s[40:43], s9 offen
	buffer_load_dwordx4 v[56:59], v162, s[40:43], s9 offen
	buffer_load_dwordx4 v[64:67], v159, s[36:39], s8 offen
	s_waitcnt vmcnt(20)
	v_pk_mul_f32 v[114:115], v[96:97], v[72:73]
	v_pk_mul_f32 v[116:117], v[100:101], v[72:73]
	v_pk_mul_f32 v[118:119], v[104:105], v[72:73]
	v_pk_mul_f32 v[120:121], v[108:109], v[72:73]
	v_pk_fma_f32 v[114:115], v[98:99], v[74:75], v[114:115]
	v_pk_fma_f32 v[116:117], v[102:103], v[74:75], v[116:117]
	v_pk_fma_f32 v[118:119], v[106:107], v[74:75], v[118:119]
	v_pk_fma_f32 v[120:121], v[110:111], v[74:75], v[120:121]
	v_add_f32_dpp v154, v155, v154 quad_perm:[1,0,3,2] row_mask:0xf bank_mask:0xf bound_ctrl:1
	v_add_f32_dpp v156, v157, v156 quad_perm:[1,0,3,2] row_mask:0xf bank_mask:0xf bound_ctrl:1
	v_cndmask_b32_e64 v155, v154, v156, s[98:99]
	v_cndmask_b32_e64 v157, v156, v154, s[98:99]
	v_add_f32_e32 v122, v114, v115
	v_add_f32_e32 v123, v116, v117
	v_add_f32_e32 v124, v118, v119
	v_add_f32_e32 v125, v120, v121
	v_add_f32_dpp v155, v157, v155 quad_perm:[2,3,0,1] row_mask:0xf bank_mask:0xf bound_ctrl:1
	v_add_f32_dpp v122, v122, v122 quad_perm:[1,0,3,2] row_mask:0xf bank_mask:0xf bound_ctrl:1
	v_add_f32_dpp v123, v123, v123 quad_perm:[1,0,3,2] row_mask:0xf bank_mask:0xf bound_ctrl:1
	v_add_f32_dpp v124, v124, v124 quad_perm:[1,0,3,2] row_mask:0xf bank_mask:0xf bound_ctrl:1
	v_add_f32_dpp v125, v125, v125 quad_perm:[1,0,3,2] row_mask:0xf bank_mask:0xf bound_ctrl:1
	v_add_f32_dpp v155, v155, v155 row_ror:4 row_mask:0xf bank_mask:0xf bound_ctrl:1
	v_add_f32_dpp v122, v122, v122 quad_perm:[2,3,0,1] row_mask:0xf bank_mask:0xf bound_ctrl:1
	v_add_f32_dpp v123, v123, v123 quad_perm:[2,3,0,1] row_mask:0xf bank_mask:0xf bound_ctrl:1
	v_add_f32_dpp v124, v124, v124 quad_perm:[2,3,0,1] row_mask:0xf bank_mask:0xf bound_ctrl:1
	v_add_f32_dpp v125, v125, v125 quad_perm:[2,3,0,1] row_mask:0xf bank_mask:0xf bound_ctrl:1
	v_add_f32_dpp v155, v155, v155 row_ror:8 row_mask:0xf bank_mask:0xf bound_ctrl:1
	v_add_f32_dpp v122, v122, v122 row_ror:4 row_mask:0xf bank_mask:0xf bound_ctrl:1
	v_add_f32_dpp v123, v123, v123 row_ror:4 row_mask:0xf bank_mask:0xf bound_ctrl:1
	v_add_f32_dpp v124, v124, v124 row_ror:4 row_mask:0xf bank_mask:0xf bound_ctrl:1
	v_add_f32_dpp v125, v125, v125 row_ror:4 row_mask:0xf bank_mask:0xf bound_ctrl:1
	v_pk_mul_f32 v[126:127], v[92:93], v[84:85] op_sel_hi:[0,1]
	v_pk_mul_f32 v[130:131], v[92:93], v[84:85] op_sel:[1,0]
	v_pk_mul_f32 v[134:135], v[94:95], v[84:85] op_sel_hi:[0,1]
	v_pk_mul_f32 v[138:139], v[94:95], v[84:85] op_sel:[1,0]
	s_add_i32 s24, s24, s30
	v_pk_mul_f32 v[128:129], v[92:93], v[86:87] op_sel_hi:[0,1]
	v_pk_mul_f32 v[132:133], v[92:93], v[86:87] op_sel:[1,0]
	v_pk_mul_f32 v[136:137], v[94:95], v[86:87] op_sel_hi:[0,1]
	v_pk_mul_f32 v[140:141], v[94:95], v[86:87] op_sel:[1,0]
	v_pk_fma_f32 v[126:127], v[96:97], v[76:77], v[126:127]
	v_pk_fma_f32 v[130:131], v[100:101], v[76:77], v[130:131]
	v_pk_fma_f32 v[134:135], v[104:105], v[76:77], v[134:135]
	v_pk_fma_f32 v[138:139], v[108:109], v[76:77], v[138:139]
	v_add_f32_dpp v122, v122, v122 row_ror:8 row_mask:0xf bank_mask:0xf bound_ctrl:1
	v_add_f32_dpp v123, v123, v123 row_ror:8 row_mask:0xf bank_mask:0xf bound_ctrl:1
	v_add_f32_dpp v124, v124, v124 row_ror:8 row_mask:0xf bank_mask:0xf bound_ctrl:1
	v_add_f32_dpp v125, v125, v125 row_ror:8 row_mask:0xf bank_mask:0xf bound_ctrl:1
	buffer_store_dword v155, v164, s[44:47], s24 offen
	v_pk_fma_f32 v[128:129], v[98:99], v[78:79], v[128:129]
	v_pk_fma_f32 v[132:133], v[102:103], v[78:79], v[132:133]
	v_pk_fma_f32 v[136:137], v[106:107], v[78:79], v[136:137]
	v_pk_fma_f32 v[140:141], v[110:111], v[78:79], v[140:141]
	v_pk_fma_f32 v[96:97], v[80:81], v[122:123], v[126:127] op_sel_hi:[1,0,1] neg_lo:[0,1,0] neg_hi:[0,1,0]
	v_pk_fma_f32 v[100:101], v[80:81], v[122:123], v[130:131] op_sel:[0,1,0] neg_lo:[0,1,0] neg_hi:[0,1,0]
	v_pk_fma_f32 v[104:105], v[80:81], v[124:125], v[134:135] op_sel_hi:[1,0,1] neg_lo:[0,1,0] neg_hi:[0,1,0]
	v_pk_fma_f32 v[108:109], v[80:81], v[124:125], v[138:139] op_sel:[0,1,0] neg_lo:[0,1,0] neg_hi:[0,1,0]
	v_pk_fma_f32 v[98:99], v[82:83], v[122:123], v[128:129] op_sel_hi:[1,0,1] neg_lo:[0,1,0] neg_hi:[0,1,0]
	v_pk_fma_f32 v[102:103], v[82:83], v[122:123], v[132:133] op_sel:[0,1,0] neg_lo:[0,1,0] neg_hi:[0,1,0]
	v_pk_fma_f32 v[106:107], v[82:83], v[124:125], v[136:137] op_sel_hi:[1,0,1] neg_lo:[0,1,0] neg_hi:[0,1,0]
	v_pk_fma_f32 v[110:111], v[82:83], v[124:125], v[140:141] op_sel:[0,1,0] neg_lo:[0,1,0] neg_hi:[0,1,0]
	v_pk_mul_f32 v[142:143], v[96:97], v[88:89]
	v_pk_mul_f32 v[144:145], v[100:101], v[88:89]
	v_pk_mul_f32 v[146:147], v[104:105], v[88:89]
	v_pk_mul_f32 v[148:149], v[108:109], v[88:89]
	s_add_i32 s8, s8, s25
	s_add_i32 s9, s9, s30
	v_pk_fma_f32 v[142:143], v[98:99], v[90:91], v[142:143]
	v_pk_fma_f32 v[144:145], v[102:103], v[90:91], v[144:145]
	v_pk_fma_f32 v[146:147], v[106:107], v[90:91], v[146:147]
	v_pk_fma_f32 v[148:149], v[110:111], v[90:91], v[148:149]
	buffer_load_dwordx4 v[72:75], v158, s[36:39], s8 offen
	buffer_load_dwordx4 v[84:87], v163, s[40:43], s9 offen
	buffer_load_dwordx4 v[92:95], v160, s[36:39], s8 offen
	buffer_load_dwordx4 v[76:79], v161, s[40:43], s9 offen
	buffer_load_dwordx4 v[80:83], v162, s[40:43], s9 offen
	buffer_load_dwordx4 v[88:91], v159, s[36:39], s8 offen
	s_waitcnt vmcnt(21)
	v_pk_mul_f32 v[114:115], v[96:97], v[0:1]
	v_pk_mul_f32 v[116:117], v[100:101], v[0:1]
	v_pk_mul_f32 v[118:119], v[104:105], v[0:1]
	v_pk_mul_f32 v[120:121], v[108:109], v[0:1]
	v_pk_fma_f32 v[114:115], v[98:99], v[2:3], v[114:115]
	v_pk_fma_f32 v[116:117], v[102:103], v[2:3], v[116:117]
	v_pk_fma_f32 v[118:119], v[106:107], v[2:3], v[118:119]
	v_pk_fma_f32 v[120:121], v[110:111], v[2:3], v[120:121]
	v_add_f32_e32 v122, v114, v115
	v_add_f32_e32 v123, v116, v117
	v_add_f32_e32 v124, v118, v119
	v_add_f32_e32 v125, v120, v121
	v_add_f32_e32 v150, v142, v143
	v_add_f32_e32 v151, v144, v145
	v_add_f32_e32 v152, v146, v147
	v_add_f32_e32 v153, v148, v149
	v_cndmask_b32_e64 v154, v150, v151, s[100:101]
	v_cndmask_b32_e64 v155, v151, v150, s[100:101]
	v_cndmask_b32_e64 v156, v152, v153, s[100:101]
	v_cndmask_b32_e64 v157, v153, v152, s[100:101]
	v_add_f32_dpp v122, v122, v122 quad_perm:[1,0,3,2] row_mask:0xf bank_mask:0xf bound_ctrl:1
	v_add_f32_dpp v123, v123, v123 quad_perm:[1,0,3,2] row_mask:0xf bank_mask:0xf bound_ctrl:1
	v_add_f32_dpp v124, v124, v124 quad_perm:[1,0,3,2] row_mask:0xf bank_mask:0xf bound_ctrl:1
	v_add_f32_dpp v125, v125, v125 quad_perm:[1,0,3,2] row_mask:0xf bank_mask:0xf bound_ctrl:1
	v_add_f32_dpp v154, v155, v154 quad_perm:[1,0,3,2] row_mask:0xf bank_mask:0xf bound_ctrl:1
	v_add_f32_dpp v156, v157, v156 quad_perm:[1,0,3,2] row_mask:0xf bank_mask:0xf bound_ctrl:1
	v_add_f32_dpp v122, v122, v122 quad_perm:[2,3,0,1] row_mask:0xf bank_mask:0xf bound_ctrl:1
	v_add_f32_dpp v123, v123, v123 quad_perm:[2,3,0,1] row_mask:0xf bank_mask:0xf bound_ctrl:1
	v_add_f32_dpp v124, v124, v124 quad_perm:[2,3,0,1] row_mask:0xf bank_mask:0xf bound_ctrl:1
	v_add_f32_dpp v125, v125, v125 quad_perm:[2,3,0,1] row_mask:0xf bank_mask:0xf bound_ctrl:1
	v_cndmask_b32_e64 v155, v154, v156, s[98:99]
	v_cndmask_b32_e64 v157, v156, v154, s[98:99]
	v_add_f32_dpp v122, v122, v122 row_ror:4 row_mask:0xf bank_mask:0xf bound_ctrl:1
	v_add_f32_dpp v123, v123, v123 row_ror:4 row_mask:0xf bank_mask:0xf bound_ctrl:1
	v_add_f32_dpp v124, v124, v124 row_ror:4 row_mask:0xf bank_mask:0xf bound_ctrl:1
	v_add_f32_dpp v125, v125, v125 row_ror:4 row_mask:0xf bank_mask:0xf bound_ctrl:1
	v_pk_mul_f32 v[126:127], v[20:21], v[12:13] op_sel_hi:[0,1]
	v_pk_mul_f32 v[130:131], v[20:21], v[12:13] op_sel:[1,0]
	v_pk_mul_f32 v[134:135], v[22:23], v[12:13] op_sel_hi:[0,1]
	v_pk_mul_f32 v[138:139], v[22:23], v[12:13] op_sel:[1,0]
	v_add_f32_dpp v155, v157, v155 quad_perm:[2,3,0,1] row_mask:0xf bank_mask:0xf bound_ctrl:1
	v_pk_mul_f32 v[128:129], v[20:21], v[14:15] op_sel_hi:[0,1]
	v_pk_mul_f32 v[132:133], v[20:21], v[14:15] op_sel:[1,0]
	v_pk_mul_f32 v[136:137], v[22:23], v[14:15] op_sel_hi:[0,1]
	v_pk_mul_f32 v[140:141], v[22:23], v[14:15] op_sel:[1,0]
	v_pk_fma_f32 v[126:127], v[96:97], v[4:5], v[126:127]
	v_pk_fma_f32 v[130:131], v[100:101], v[4:5], v[130:131]
	v_pk_fma_f32 v[134:135], v[104:105], v[4:5], v[134:135]
	v_pk_fma_f32 v[138:139], v[108:109], v[4:5], v[138:139]
	v_add_f32_dpp v122, v122, v122 row_ror:8 row_mask:0xf bank_mask:0xf bound_ctrl:1
	v_add_f32_dpp v123, v123, v123 row_ror:8 row_mask:0xf bank_mask:0xf bound_ctrl:1
	v_add_f32_dpp v124, v124, v124 row_ror:8 row_mask:0xf bank_mask:0xf bound_ctrl:1
	v_add_f32_dpp v125, v125, v125 row_ror:8 row_mask:0xf bank_mask:0xf bound_ctrl:1
	v_add_f32_dpp v155, v155, v155 row_ror:4 row_mask:0xf bank_mask:0xf bound_ctrl:1
	v_pk_fma_f32 v[128:129], v[98:99], v[6:7], v[128:129]
	v_pk_fma_f32 v[132:133], v[102:103], v[6:7], v[132:133]
	v_pk_fma_f32 v[136:137], v[106:107], v[6:7], v[136:137]
	v_pk_fma_f32 v[140:141], v[110:111], v[6:7], v[140:141]
	v_pk_fma_f32 v[96:97], v[8:9], v[122:123], v[126:127] op_sel_hi:[1,0,1] neg_lo:[0,1,0] neg_hi:[0,1,0]
	v_pk_fma_f32 v[100:101], v[8:9], v[122:123], v[130:131] op_sel:[0,1,0] neg_lo:[0,1,0] neg_hi:[0,1,0]
	v_pk_fma_f32 v[104:105], v[8:9], v[124:125], v[134:135] op_sel_hi:[1,0,1] neg_lo:[0,1,0] neg_hi:[0,1,0]
	v_pk_fma_f32 v[108:109], v[8:9], v[124:125], v[138:139] op_sel:[0,1,0] neg_lo:[0,1,0] neg_hi:[0,1,0]
	v_pk_fma_f32 v[98:99], v[10:11], v[122:123], v[128:129] op_sel_hi:[1,0,1] neg_lo:[0,1,0] neg_hi:[0,1,0]
	v_pk_fma_f32 v[102:103], v[10:11], v[122:123], v[132:133] op_sel:[0,1,0] neg_lo:[0,1,0] neg_hi:[0,1,0]
	v_pk_fma_f32 v[106:107], v[10:11], v[124:125], v[136:137] op_sel_hi:[1,0,1] neg_lo:[0,1,0] neg_hi:[0,1,0]
	v_pk_fma_f32 v[110:111], v[10:11], v[124:125], v[140:141] op_sel:[0,1,0] neg_lo:[0,1,0] neg_hi:[0,1,0]
	v_pk_mul_f32 v[142:143], v[96:97], v[16:17]
	v_pk_mul_f32 v[144:145], v[100:101], v[16:17]
	v_pk_mul_f32 v[146:147], v[104:105], v[16:17]
	v_pk_mul_f32 v[148:149], v[108:109], v[16:17]
	v_add_f32_dpp v155, v155, v155 row_ror:8 row_mask:0xf bank_mask:0xf bound_ctrl:1
	s_add_i32 s24, s24, s30
	v_pk_fma_f32 v[142:143], v[98:99], v[18:19], v[142:143]
	v_pk_fma_f32 v[144:145], v[102:103], v[18:19], v[144:145]
	v_pk_fma_f32 v[146:147], v[106:107], v[18:19], v[146:147]
	v_pk_fma_f32 v[148:149], v[110:111], v[18:19], v[148:149]
	v_add_f32_e32 v150, v142, v143
	v_add_f32_e32 v151, v144, v145
	v_add_f32_e32 v152, v146, v147
	v_add_f32_e32 v153, v148, v149
	buffer_store_dword v155, v164, s[44:47], s24 offen
	v_cndmask_b32_e64 v154, v150, v151, s[100:101]
	v_cndmask_b32_e64 v155, v151, v150, s[100:101]
	v_cndmask_b32_e64 v156, v152, v153, s[100:101]
	v_cndmask_b32_e64 v157, v153, v152, s[100:101]
	v_add_f32_dpp v154, v155, v154 quad_perm:[1,0,3,2] row_mask:0xf bank_mask:0xf bound_ctrl:1
	s_add_i32 s8, s8, s25
	v_add_f32_dpp v156, v157, v156 quad_perm:[1,0,3,2] row_mask:0xf bank_mask:0xf bound_ctrl:1
	v_cndmask_b32_e64 v155, v154, v156, s[98:99]
	v_cndmask_b32_e64 v157, v156, v154, s[98:99]
	s_add_i32 s9, s9, s30
	buffer_load_dwordx4 v[0:3], v158, s[36:39], s8 offen
	v_add_f32_dpp v155, v157, v155 quad_perm:[2,3,0,1] row_mask:0xf bank_mask:0xf bound_ctrl:1
	s_add_i32 s24, s24, s30
	buffer_load_dwordx4 v[12:15], v163, s[40:43], s9 offen
	v_add_f32_dpp v155, v155, v155 row_ror:4 row_mask:0xf bank_mask:0xf bound_ctrl:1
	buffer_load_dwordx4 v[20:23], v160, s[36:39], s8 offen
	buffer_load_dwordx4 v[4:7], v161, s[40:43], s9 offen
	v_add_f32_dpp v155, v155, v155 row_ror:8 row_mask:0xf bank_mask:0xf bound_ctrl:1
	buffer_load_dwordx4 v[8:11], v162, s[40:43], s9 offen
	buffer_load_dwordx4 v[16:19], v159, s[36:39], s8 offen
	s_add_i32 s8, s8, s25
	s_add_i32 s9, s9, s30
	s_add_i32 s31, s31, -1
	s_cmp_lg_u32 s31, 0
	s_cbranch_scc1 .Lps_loop
	s_waitcnt vmcnt(21)
	v_pk_mul_f32 v[114:115], v[96:97], v[24:25]
	v_pk_mul_f32 v[116:117], v[100:101], v[24:25]
	v_pk_mul_f32 v[118:119], v[104:105], v[24:25]
	v_pk_mul_f32 v[120:121], v[108:109], v[24:25]
	v_pk_fma_f32 v[114:115], v[98:99], v[26:27], v[114:115]
	v_pk_fma_f32 v[116:117], v[102:103], v[26:27], v[116:117]
	v_pk_fma_f32 v[118:119], v[106:107], v[26:27], v[118:119]
	v_pk_fma_f32 v[120:121], v[110:111], v[26:27], v[120:121]
	v_add_f32_e32 v122, v114, v115
	v_add_f32_e32 v123, v116, v117
	v_add_f32_e32 v124, v118, v119
	v_add_f32_e32 v125, v120, v121
	v_add_f32_dpp v122, v122, v122 quad_perm:[1,0,3,2] row_mask:0xf bank_mask:0xf bound_ctrl:1
	v_add_f32_dpp v123, v123, v123 quad_perm:[1,0,3,2] row_mask:0xf bank_mask:0xf bound_ctrl:1
	v_add_f32_dpp v124, v124, v124 quad_perm:[1,0,3,2] row_mask:0xf bank_mask:0xf bound_ctrl:1
	v_add_f32_dpp v125, v125, v125 quad_perm:[1,0,3,2] row_mask:0xf bank_mask:0xf bound_ctrl:1
	v_add_f32_dpp v122, v122, v122 quad_perm:[2,3,0,1] row_mask:0xf bank_mask:0xf bound_ctrl:1
	v_add_f32_dpp v123, v123, v123 quad_perm:[2,3,0,1] row_mask:0xf bank_mask:0xf bound_ctrl:1
	v_add_f32_dpp v124, v124, v124 quad_perm:[2,3,0,1] row_mask:0xf bank_mask:0xf bound_ctrl:1
	v_add_f32_dpp v125, v125, v125 quad_perm:[2,3,0,1] row_mask:0xf bank_mask:0xf bound_ctrl:1
	v_add_f32_dpp v122, v122, v122 row_ror:4 row_mask:0xf bank_mask:0xf bound_ctrl:1
	v_add_f32_dpp v123, v123, v123 row_ror:4 row_mask:0xf bank_mask:0xf bound_ctrl:1
	v_add_f32_dpp v124, v124, v124 row_ror:4 row_mask:0xf bank_mask:0xf bound_ctrl:1
	v_add_f32_dpp v125, v125, v125 row_ror:4 row_mask:0xf bank_mask:0xf bound_ctrl:1
	v_pk_mul_f32 v[126:127], v[44:45], v[36:37] op_sel_hi:[0,1]
	v_pk_mul_f32 v[130:131], v[44:45], v[36:37] op_sel:[1,0]
	v_pk_mul_f32 v[134:135], v[46:47], v[36:37] op_sel_hi:[0,1]
	v_pk_mul_f32 v[138:139], v[46:47], v[36:37] op_sel:[1,0]
	v_pk_mul_f32 v[128:129], v[44:45], v[38:39] op_sel_hi:[0,1]
	v_pk_mul_f32 v[132:133], v[44:45], v[38:39] op_sel:[1,0]
	v_pk_mul_f32 v[136:137], v[46:47], v[38:39] op_sel_hi:[0,1]
	v_pk_mul_f32 v[140:141], v[46:47], v[38:39] op_sel:[1,0]
	v_pk_fma_f32 v[126:127], v[96:97], v[28:29], v[126:127]
	v_pk_fma_f32 v[130:131], v[100:101], v[28:29], v[130:131]
	v_pk_fma_f32 v[134:135], v[104:105], v[28:29], v[134:135]
	v_pk_fma_f32 v[138:139], v[108:109], v[28:29], v[138:139]
	v_add_f32_dpp v122, v122, v122 row_ror:8 row_mask:0xf bank_mask:0xf bound_ctrl:1
	v_add_f32_dpp v123, v123, v123 row_ror:8 row_mask:0xf bank_mask:0xf bound_ctrl:1
	v_add_f32_dpp v124, v124, v124 row_ror:8 row_mask:0xf bank_mask:0xf bound_ctrl:1
	v_add_f32_dpp v125, v125, v125 row_ror:8 row_mask:0xf bank_mask:0xf bound_ctrl:1
	buffer_store_dword v155, v164, s[44:47], s24 offen
	v_pk_fma_f32 v[128:129], v[98:99], v[30:31], v[128:129]
	v_pk_fma_f32 v[132:133], v[102:103], v[30:31], v[132:133]
	v_pk_fma_f32 v[136:137], v[106:107], v[30:31], v[136:137]
	v_pk_fma_f32 v[140:141], v[110:111], v[30:31], v[140:141]
	v_pk_fma_f32 v[96:97], v[32:33], v[122:123], v[126:127] op_sel_hi:[1,0,1] neg_lo:[0,1,0] neg_hi:[0,1,0]
	v_pk_fma_f32 v[100:101], v[32:33], v[122:123], v[130:131] op_sel:[0,1,0] neg_lo:[0,1,0] neg_hi:[0,1,0]
	v_pk_fma_f32 v[104:105], v[32:33], v[124:125], v[134:135] op_sel_hi:[1,0,1] neg_lo:[0,1,0] neg_hi:[0,1,0]
	v_pk_fma_f32 v[108:109], v[32:33], v[124:125], v[138:139] op_sel:[0,1,0] neg_lo:[0,1,0] neg_hi:[0,1,0]
	v_pk_fma_f32 v[98:99], v[34:35], v[122:123], v[128:129] op_sel_hi:[1,0,1] neg_lo:[0,1,0] neg_hi:[0,1,0]
	v_pk_fma_f32 v[102:103], v[34:35], v[122:123], v[132:133] op_sel:[0,1,0] neg_lo:[0,1,0] neg_hi:[0,1,0]
	v_pk_fma_f32 v[106:107], v[34:35], v[124:125], v[136:137] op_sel_hi:[1,0,1] neg_lo:[0,1,0] neg_hi:[0,1,0]
	v_pk_fma_f32 v[110:111], v[34:35], v[124:125], v[140:141] op_sel:[0,1,0] neg_lo:[0,1,0] neg_hi:[0,1,0]
	v_pk_mul_f32 v[142:143], v[96:97], v[40:41]
	v_pk_mul_f32 v[144:145], v[100:101], v[40:41]
	v_pk_mul_f32 v[146:147], v[104:105], v[40:41]
	v_pk_mul_f32 v[148:149], v[108:109], v[40:41]
	v_pk_fma_f32 v[142:143], v[98:99], v[42:43], v[142:143]
	v_pk_fma_f32 v[144:145], v[102:103], v[42:43], v[144:145]
	v_pk_fma_f32 v[146:147], v[106:107], v[42:43], v[146:147]
	v_pk_fma_f32 v[148:149], v[110:111], v[42:43], v[148:149]
	buffer_load_dwordx4 v[24:27], v158, s[36:39], s8 offen
	buffer_load_dwordx4 v[36:39], v163, s[40:43], s9 offen
	v_add_f32_e32 v150, v142, v143
	v_add_f32_e32 v151, v144, v145
	v_add_f32_e32 v152, v146, v147
	v_add_f32_e32 v153, v148, v149
	buffer_load_dwordx4 v[44:47], v160, s[36:39], s8 offen
	v_cndmask_b32_e64 v154, v150, v151, s[100:101]
	v_cndmask_b32_e64 v155, v151, v150, s[100:101]
	v_cndmask_b32_e64 v156, v152, v153, s[100:101]
	v_cndmask_b32_e64 v157, v153, v152, s[100:101]
	buffer_load_dwordx4 v[28:31], v161, s[40:43], s9 offen
	buffer_load_dwordx4 v[32:35], v162, s[40:43], s9 offen
	buffer_load_dwordx4 v[40:43], v159, s[36:39], s8 offen
	s_waitcnt vmcnt(21)
	v_pk_mul_f32 v[114:115], v[96:97], v[48:49]
	v_pk_mul_f32 v[116:117], v[100:101], v[48:49]
	v_pk_mul_f32 v[118:119], v[104:105], v[48:49]
	v_pk_mul_f32 v[120:121], v[108:109], v[48:49]
	v_pk_fma_f32 v[114:115], v[98:99], v[50:51], v[114:115]
	v_pk_fma_f32 v[116:117], v[102:103], v[50:51], v[116:117]
	v_pk_fma_f32 v[118:119], v[106:107], v[50:51], v[118:119]
	v_pk_fma_f32 v[120:121], v[110:111], v[50:51], v[120:121]
	v_add_f32_dpp v154, v155, v154 quad_perm:[1,0,3,2] row_mask:0xf bank_mask:0xf bound_ctrl:1
	v_add_f32_dpp v156, v157, v156 quad_perm:[1,0,3,2] row_mask:0xf bank_mask:0xf bound_ctrl:1
	v_cndmask_b32_e64 v155, v154, v156, s[98:99]
	v_cndmask_b32_e64 v157, v156, v154, s[98:99]
	v_add_f32_e32 v122, v114, v115
	v_add_f32_e32 v123, v116, v117
	v_add_f32_e32 v124, v118, v119
	v_add_f32_e32 v125, v120, v121
	v_add_f32_dpp v155, v157, v155 quad_perm:[2,3,0,1] row_mask:0xf bank_mask:0xf bound_ctrl:1
	v_add_f32_dpp v122, v122, v122 quad_perm:[1,0,3,2] row_mask:0xf bank_mask:0xf bound_ctrl:1
	v_add_f32_dpp v123, v123, v123 quad_perm:[1,0,3,2] row_mask:0xf bank_mask:0xf bound_ctrl:1
	v_add_f32_dpp v124, v124, v124 quad_perm:[1,0,3,2] row_mask:0xf bank_mask:0xf bound_ctrl:1
	v_add_f32_dpp v125, v125, v125 quad_perm:[1,0,3,2] row_mask:0xf bank_mask:0xf bound_ctrl:1
	v_add_f32_dpp v155, v155, v155 row_ror:4 row_mask:0xf bank_mask:0xf bound_ctrl:1
	v_add_f32_dpp v122, v122, v122 quad_perm:[2,3,0,1] row_mask:0xf bank_mask:0xf bound_ctrl:1
	v_add_f32_dpp v123, v123, v123 quad_perm:[2,3,0,1] row_mask:0xf bank_mask:0xf bound_ctrl:1
	v_add_f32_dpp v124, v124, v124 quad_perm:[2,3,0,1] row_mask:0xf bank_mask:0xf bound_ctrl:1
	v_add_f32_dpp v125, v125, v125 quad_perm:[2,3,0,1] row_mask:0xf bank_mask:0xf bound_ctrl:1
	v_add_f32_dpp v155, v155, v155 row_ror:8 row_mask:0xf bank_mask:0xf bound_ctrl:1
	v_add_f32_dpp v122, v122, v122 row_ror:4 row_mask:0xf bank_mask:0xf bound_ctrl:1
	v_add_f32_dpp v123, v123, v123 row_ror:4 row_mask:0xf bank_mask:0xf bound_ctrl:1
	v_add_f32_dpp v124, v124, v124 row_ror:4 row_mask:0xf bank_mask:0xf bound_ctrl:1
	v_add_f32_dpp v125, v125, v125 row_ror:4 row_mask:0xf bank_mask:0xf bound_ctrl:1
	v_pk_mul_f32 v[126:127], v[68:69], v[60:61] op_sel_hi:[0,1]
	v_pk_mul_f32 v[130:131], v[68:69], v[60:61] op_sel:[1,0]
	v_pk_mul_f32 v[134:135], v[70:71], v[60:61] op_sel_hi:[0,1]
	v_pk_mul_f32 v[138:139], v[70:71], v[60:61] op_sel:[1,0]
	s_add_i32 s24, s24, s30
	v_pk_mul_f32 v[128:129], v[68:69], v[62:63] op_sel_hi:[0,1]
	v_pk_mul_f32 v[132:133], v[68:69], v[62:63] op_sel:[1,0]
	v_pk_mul_f32 v[136:137], v[70:71], v[62:63] op_sel_hi:[0,1]
	v_pk_mul_f32 v[140:141], v[70:71], v[62:63] op_sel:[1,0]
	v_pk_fma_f32 v[126:127], v[96:97], v[52:53], v[126:127]
	v_pk_fma_f32 v[130:131], v[100:101], v[52:53], v[130:131]
	v_pk_fma_f32 v[134:135], v[104:105], v[52:53], v[134:135]
	v_pk_fma_f32 v[138:139], v[108:109], v[52:53], v[138:139]
	v_add_f32_dpp v122, v122, v122 row_ror:8 row_mask:0xf bank_mask:0xf bound_ctrl:1
	v_add_f32_dpp v123, v123, v123 row_ror:8 row_mask:0xf bank_mask:0xf bound_ctrl:1
	v_add_f32_dpp v124, v124, v124 row_ror:8 row_mask:0xf bank_mask:0xf bound_ctrl:1
	v_add_f32_dpp v125, v125, v125 row_ror:8 row_mask:0xf bank_mask:0xf bound_ctrl:1
	buffer_store_dword v155, v164, s[44:47], s24 offen
	v_pk_fma_f32 v[128:129], v[98:99], v[54:55], v[128:129]
	v_pk_fma_f32 v[132:133], v[102:103], v[54:55], v[132:133]
	v_pk_fma_f32 v[136:137], v[106:107], v[54:55], v[136:137]
	v_pk_fma_f32 v[140:141], v[110:111], v[54:55], v[140:141]
	v_pk_fma_f32 v[96:97], v[56:57], v[122:123], v[126:127] op_sel_hi:[1,0,1] neg_lo:[0,1,0] neg_hi:[0,1,0]
	v_pk_fma_f32 v[100:101], v[56:57], v[122:123], v[130:131] op_sel:[0,1,0] neg_lo:[0,1,0] neg_hi:[0,1,0]
	v_pk_fma_f32 v[104:105], v[56:57], v[124:125], v[134:135] op_sel_hi:[1,0,1] neg_lo:[0,1,0] neg_hi:[0,1,0]
	v_pk_fma_f32 v[108:109], v[56:57], v[124:125], v[138:139] op_sel:[0,1,0] neg_lo:[0,1,0] neg_hi:[0,1,0]
	v_pk_fma_f32 v[98:99], v[58:59], v[122:123], v[128:129] op_sel_hi:[1,0,1] neg_lo:[0,1,0] neg_hi:[0,1,0]
	v_pk_fma_f32 v[102:103], v[58:59], v[122:123], v[132:133] op_sel:[0,1,0] neg_lo:[0,1,0] neg_hi:[0,1,0]
	v_pk_fma_f32 v[106:107], v[58:59], v[124:125], v[136:137] op_sel_hi:[1,0,1] neg_lo:[0,1,0] neg_hi:[0,1,0]
	v_pk_fma_f32 v[110:111], v[58:59], v[124:125], v[140:141] op_sel:[0,1,0] neg_lo:[0,1,0] neg_hi:[0,1,0]
	v_pk_mul_f32 v[142:143], v[96:97], v[64:65]
	v_pk_mul_f32 v[144:145], v[100:101], v[64:65]
	v_pk_mul_f32 v[146:147], v[104:105], v[64:65]
	v_pk_mul_f32 v[148:149], v[108:109], v[64:65]
	s_add_i32 s8, s8, s25
	s_add_i32 s9, s9, s30
	v_pk_fma_f32 v[142:143], v[98:99], v[66:67], v[142:143]
	v_pk_fma_f32 v[144:145], v[102:103], v[66:67], v[144:145]
	v_pk_fma_f32 v[146:147], v[106:107], v[66:67], v[146:147]
	v_pk_fma_f32 v[148:149], v[110:111], v[66:67], v[148:149]
	buffer_load_dwordx4 v[48:51], v158, s[36:39], s8 offen
	buffer_load_dwordx4 v[60:63], v163, s[40:43], s9 offen
	v_add_f32_e32 v150, v142, v143
	v_add_f32_e32 v151, v144, v145
	v_add_f32_e32 v152, v146, v147
	v_add_f32_e32 v153, v148, v149
	buffer_load_dwordx4 v[68:71], v160, s[36:39], s8 offen
	v_cndmask_b32_e64 v154, v150, v151, s[100:101]
	v_cndmask_b32_e64 v155, v151, v150, s[100:101]
	v_cndmask_b32_e64 v156, v152, v153, s[100:101]
	v_cndmask_b32_e64 v157, v153, v152, s[100:101]
	buffer_load_dwordx4 v[52:55], v161, s[40:43], s9 offen
	buffer_load_dwordx4 v[56:59], v162, s[40:43], s9 offen
	buffer_load_dwordx4 v[64:67], v159, s[36:39], s8 offen
	s_waitcnt vmcnt(21)
	v_pk_mul_f32 v[114:115], v[96:97], v[72:73]
	v_pk_mul_f32 v[116:117], v[100:101], v[72:73]
	v_pk_mul_f32 v[118:119], v[104:105], v[72:73]
	v_pk_mul_f32 v[120:121], v[108:109], v[72:73]
	v_pk_fma_f32 v[114:115], v[98:99], v[74:75], v[114:115]
	v_pk_fma_f32 v[116:117], v[102:103], v[74:75], v[116:117]
	v_pk_fma_f32 v[118:119], v[106:107], v[74:75], v[118:119]
	v_pk_fma_f32 v[120:121], v[110:111], v[74:75], v[120:121]
	v_add_f32_dpp v154, v155, v154 quad_perm:[1,0,3,2] row_mask:0xf bank_mask:0xf bound_ctrl:1
	v_add_f32_dpp v156, v157, v156 quad_perm:[1,0,3,2] row_mask:0xf bank_mask:0xf bound_ctrl:1
	v_cndmask_b32_e64 v155, v154, v156, s[98:99]
	v_cndmask_b32_e64 v157, v156, v154, s[98:99]
	v_add_f32_e32 v122, v114, v115
	v_add_f32_e32 v123, v116, v117
	v_add_f32_e32 v124, v118, v119
	v_add_f32_e32 v125, v120, v121
	v_add_f32_dpp v155, v157, v155 quad_perm:[2,3,0,1] row_mask:0xf bank_mask:0xf bound_ctrl:1
	v_add_f32_dpp v122, v122, v122 quad_perm:[1,0,3,2] row_mask:0xf bank_mask:0xf bound_ctrl:1
	v_add_f32_dpp v123, v123, v123 quad_perm:[1,0,3,2] row_mask:0xf bank_mask:0xf bound_ctrl:1
	v_add_f32_dpp v124, v124, v124 quad_perm:[1,0,3,2] row_mask:0xf bank_mask:0xf bound_ctrl:1
	v_add_f32_dpp v125, v125, v125 quad_perm:[1,0,3,2] row_mask:0xf bank_mask:0xf bound_ctrl:1
	v_add_f32_dpp v155, v155, v155 row_ror:4 row_mask:0xf bank_mask:0xf bound_ctrl:1
	v_add_f32_dpp v122, v122, v122 quad_perm:[2,3,0,1] row_mask:0xf bank_mask:0xf bound_ctrl:1
	v_add_f32_dpp v123, v123, v123 quad_perm:[2,3,0,1] row_mask:0xf bank_mask:0xf bound_ctrl:1
	v_add_f32_dpp v124, v124, v124 quad_perm:[2,3,0,1] row_mask:0xf bank_mask:0xf bound_ctrl:1
	v_add_f32_dpp v125, v125, v125 quad_perm:[2,3,0,1] row_mask:0xf bank_mask:0xf bound_ctrl:1
	v_add_f32_dpp v155, v155, v155 row_ror:8 row_mask:0xf bank_mask:0xf bound_ctrl:1
	v_add_f32_dpp v122, v122, v122 row_ror:4 row_mask:0xf bank_mask:0xf bound_ctrl:1
	v_add_f32_dpp v123, v123, v123 row_ror:4 row_mask:0xf bank_mask:0xf bound_ctrl:1
	v_add_f32_dpp v124, v124, v124 row_ror:4 row_mask:0xf bank_mask:0xf bound_ctrl:1
	v_add_f32_dpp v125, v125, v125 row_ror:4 row_mask:0xf bank_mask:0xf bound_ctrl:1
	v_pk_mul_f32 v[126:127], v[92:93], v[84:85] op_sel_hi:[0,1]
	v_pk_mul_f32 v[130:131], v[92:93], v[84:85] op_sel:[1,0]
	v_pk_mul_f32 v[134:135], v[94:95], v[84:85] op_sel_hi:[0,1]
	v_pk_mul_f32 v[138:139], v[94:95], v[84:85] op_sel:[1,0]
	s_add_i32 s24, s24, s30
	v_pk_mul_f32 v[128:129], v[92:93], v[86:87] op_sel_hi:[0,1]
	v_pk_mul_f32 v[132:133], v[92:93], v[86:87] op_sel:[1,0]
	v_pk_mul_f32 v[136:137], v[94:95], v[86:87] op_sel_hi:[0,1]
	v_pk_mul_f32 v[140:141], v[94:95], v[86:87] op_sel:[1,0]
	v_pk_fma_f32 v[126:127], v[96:97], v[76:77], v[126:127]
	v_pk_fma_f32 v[130:131], v[100:101], v[76:77], v[130:131]
	v_pk_fma_f32 v[134:135], v[104:105], v[76:77], v[134:135]
	v_pk_fma_f32 v[138:139], v[108:109], v[76:77], v[138:139]
	v_add_f32_dpp v122, v122, v122 row_ror:8 row_mask:0xf bank_mask:0xf bound_ctrl:1
	v_add_f32_dpp v123, v123, v123 row_ror:8 row_mask:0xf bank_mask:0xf bound_ctrl:1
	v_add_f32_dpp v124, v124, v124 row_ror:8 row_mask:0xf bank_mask:0xf bound_ctrl:1
	v_add_f32_dpp v125, v125, v125 row_ror:8 row_mask:0xf bank_mask:0xf bound_ctrl:1
	buffer_store_dword v155, v164, s[44:47], s24 offen
	v_pk_fma_f32 v[128:129], v[98:99], v[78:79], v[128:129]
	v_pk_fma_f32 v[132:133], v[102:103], v[78:79], v[132:133]
	v_pk_fma_f32 v[136:137], v[106:107], v[78:79], v[136:137]
	v_pk_fma_f32 v[140:141], v[110:111], v[78:79], v[140:141]
	v_pk_fma_f32 v[96:97], v[80:81], v[122:123], v[126:127] op_sel_hi:[1,0,1] neg_lo:[0,1,0] neg_hi:[0,1,0]
	v_pk_fma_f32 v[100:101], v[80:81], v[122:123], v[130:131] op_sel:[0,1,0] neg_lo:[0,1,0] neg_hi:[0,1,0]
	v_pk_fma_f32 v[104:105], v[80:81], v[124:125], v[134:135] op_sel_hi:[1,0,1] neg_lo:[0,1,0] neg_hi:[0,1,0]
	v_pk_fma_f32 v[108:109], v[80:81], v[124:125], v[138:139] op_sel:[0,1,0] neg_lo:[0,1,0] neg_hi:[0,1,0]
	v_pk_fma_f32 v[98:99], v[82:83], v[122:123], v[128:129] op_sel_hi:[1,0,1] neg_lo:[0,1,0] neg_hi:[0,1,0]
	v_pk_fma_f32 v[102:103], v[82:83], v[122:123], v[132:133] op_sel:[0,1,0] neg_lo:[0,1,0] neg_hi:[0,1,0]
	v_pk_fma_f32 v[106:107], v[82:83], v[124:125], v[136:137] op_sel_hi:[1,0,1] neg_lo:[0,1,0] neg_hi:[0,1,0]
	v_pk_fma_f32 v[110:111], v[82:83], v[124:125], v[140:141] op_sel:[0,1,0] neg_lo:[0,1,0] neg_hi:[0,1,0]
	v_pk_mul_f32 v[142:143], v[96:97], v[88:89]
	v_pk_mul_f32 v[144:145], v[100:101], v[88:89]
	v_pk_mul_f32 v[146:147], v[104:105], v[88:89]
	v_pk_mul_f32 v[148:149], v[108:109], v[88:89]
	s_add_i32 s8, s8, s25
	s_add_i32 s9, s9, s30
	v_pk_fma_f32 v[142:143], v[98:99], v[90:91], v[142:143]
	v_pk_fma_f32 v[144:145], v[102:103], v[90:91], v[144:145]
	v_pk_fma_f32 v[146:147], v[106:107], v[90:91], v[146:147]
	v_pk_fma_f32 v[148:149], v[110:111], v[90:91], v[148:149]
	buffer_load_dwordx4 v[72:75], v158, s[36:39], s8 offen
	buffer_load_dwordx4 v[84:87], v163, s[40:43], s9 offen
	buffer_load_dwordx4 v[92:95], v160, s[36:39], s8 offen
	v_add_f32_e32 v150, v142, v143
	v_add_f32_e32 v151, v144, v145
	v_add_f32_e32 v152, v146, v147
	v_add_f32_e32 v153, v148, v149
	buffer_load_dwordx4 v[76:79], v161, s[40:43], s9 offen
	v_cndmask_b32_e64 v154, v150, v151, s[100:101]
	v_cndmask_b32_e64 v155, v151, v150, s[100:101]
	v_cndmask_b32_e64 v156, v152, v153, s[100:101]
	v_cndmask_b32_e64 v157, v153, v152, s[100:101]
	buffer_load_dwordx4 v[80:83], v162, s[40:43], s9 offen
	buffer_load_dwordx4 v[88:91], v159, s[36:39], s8 offen
	s_waitcnt vmcnt(21)
	v_pk_mul_f32 v[114:115], v[96:97], v[0:1]
	v_pk_mul_f32 v[116:117], v[100:101], v[0:1]
	v_pk_mul_f32 v[118:119], v[104:105], v[0:1]
	v_pk_mul_f32 v[120:121], v[108:109], v[0:1]
	v_pk_fma_f32 v[114:115], v[98:99], v[2:3], v[114:115]
	v_pk_fma_f32 v[116:117], v[102:103], v[2:3], v[116:117]
	v_pk_fma_f32 v[118:119], v[106:107], v[2:3], v[118:119]
	v_pk_fma_f32 v[120:121], v[110:111], v[2:3], v[120:121]
	v_add_f32_dpp v154, v155, v154 quad_perm:[1,0,3,2] row_mask:0xf bank_mask:0xf bound_ctrl:1
	v_add_f32_dpp v156, v157, v156 quad_perm:[1,0,3,2] row_mask:0xf bank_mask:0xf bound_ctrl:1
	v_add_f32_e32 v122, v114, v115
	v_add_f32_e32 v123, v116, v117
	v_add_f32_e32 v124, v118, v119
	v_add_f32_e32 v125, v120, v121
	v_cndmask_b32_e64 v155, v154, v156, s[98:99]
	v_cndmask_b32_e64 v157, v156, v154, s[98:99]
	v_add_f32_dpp v122, v122, v122 quad_perm:[1,0,3,2] row_mask:0xf bank_mask:0xf bound_ctrl:1
	v_add_f32_dpp v123, v123, v123 quad_perm:[1,0,3,2] row_mask:0xf bank_mask:0xf bound_ctrl:1
	v_add_f32_dpp v124, v124, v124 quad_perm:[1,0,3,2] row_mask:0xf bank_mask:0xf bound_ctrl:1
	v_add_f32_dpp v125, v125, v125 quad_perm:[1,0,3,2] row_mask:0xf bank_mask:0xf bound_ctrl:1
	v_add_f32_dpp v155, v157, v155 quad_perm:[2,3,0,1] row_mask:0xf bank_mask:0xf bound_ctrl:1
	v_add_f32_dpp v122, v122, v122 quad_perm:[2,3,0,1] row_mask:0xf bank_mask:0xf bound_ctrl:1
	v_add_f32_dpp v123, v123, v123 quad_perm:[2,3,0,1] row_mask:0xf bank_mask:0xf bound_ctrl:1
	v_add_f32_dpp v124, v124, v124 quad_perm:[2,3,0,1] row_mask:0xf bank_mask:0xf bound_ctrl:1
	v_add_f32_dpp v125, v125, v125 quad_perm:[2,3,0,1] row_mask:0xf bank_mask:0xf bound_ctrl:1
	v_add_f32_dpp v155, v155, v155 row_ror:4 row_mask:0xf bank_mask:0xf bound_ctrl:1
	v_add_f32_dpp v122, v122, v122 row_ror:4 row_mask:0xf bank_mask:0xf bound_ctrl:1
	v_add_f32_dpp v123, v123, v123 row_ror:4 row_mask:0xf bank_mask:0xf bound_ctrl:1
	v_add_f32_dpp v124, v124, v124 row_ror:4 row_mask:0xf bank_mask:0xf bound_ctrl:1
	v_add_f32_dpp v125, v125, v125 row_ror:4 row_mask:0xf bank_mask:0xf bound_ctrl:1
	v_pk_mul_f32 v[126:127], v[20:21], v[12:13] op_sel_hi:[0,1]
	v_pk_mul_f32 v[130:131], v[20:21], v[12:13] op_sel:[1,0]
	v_pk_mul_f32 v[134:135], v[22:23], v[12:13] op_sel_hi:[0,1]
	v_pk_mul_f32 v[138:139], v[22:23], v[12:13] op_sel:[1,0]
	v_add_f32_dpp v155, v155, v155 row_ror:8 row_mask:0xf bank_mask:0xf bound_ctrl:1
	s_add_i32 s24, s24, s30
	v_pk_mul_f32 v[128:129], v[20:21], v[14:15] op_sel_hi:[0,1]
	v_pk_mul_f32 v[132:133], v[20:21], v[14:15] op_sel:[1,0]
	v_pk_mul_f32 v[136:137], v[22:23], v[14:15] op_sel_hi:[0,1]
	v_pk_mul_f32 v[140:141], v[22:23], v[14:15] op_sel:[1,0]
	v_pk_fma_f32 v[126:127], v[96:97], v[4:5], v[126:127]
	v_pk_fma_f32 v[130:131], v[100:101], v[4:5], v[130:131]
	v_pk_fma_f32 v[134:135], v[104:105], v[4:5], v[134:135]
	v_pk_fma_f32 v[138:139], v[108:109], v[4:5], v[138:139]
	v_add_f32_dpp v122, v122, v122 row_ror:8 row_mask:0xf bank_mask:0xf bound_ctrl:1
	v_add_f32_dpp v123, v123, v123 row_ror:8 row_mask:0xf bank_mask:0xf bound_ctrl:1
	v_add_f32_dpp v124, v124, v124 row_ror:8 row_mask:0xf bank_mask:0xf bound_ctrl:1
	v_add_f32_dpp v125, v125, v125 row_ror:8 row_mask:0xf bank_mask:0xf bound_ctrl:1
	v_pk_fma_f32 v[128:129], v[98:99], v[6:7], v[128:129]
	v_pk_fma_f32 v[132:133], v[102:103], v[6:7], v[132:133]
	v_pk_fma_f32 v[136:137], v[106:107], v[6:7], v[136:137]
	v_pk_fma_f32 v[140:141], v[110:111], v[6:7], v[140:141]
	v_pk_fma_f32 v[96:97], v[8:9], v[122:123], v[126:127] op_sel_hi:[1,0,1] neg_lo:[0,1,0] neg_hi:[0,1,0]
	v_pk_fma_f32 v[100:101], v[8:9], v[122:123], v[130:131] op_sel:[0,1,0] neg_lo:[0,1,0] neg_hi:[0,1,0]
	v_pk_fma_f32 v[104:105], v[8:9], v[124:125], v[134:135] op_sel_hi:[1,0,1] neg_lo:[0,1,0] neg_hi:[0,1,0]
	v_pk_fma_f32 v[108:109], v[8:9], v[124:125], v[138:139] op_sel:[0,1,0] neg_lo:[0,1,0] neg_hi:[0,1,0]
	buffer_store_dword v155, v164, s[44:47], s24 offen
	v_pk_fma_f32 v[98:99], v[10:11], v[122:123], v[128:129] op_sel_hi:[1,0,1] neg_lo:[0,1,0] neg_hi:[0,1,0]
	v_pk_fma_f32 v[102:103], v[10:11], v[122:123], v[132:133] op_sel:[0,1,0] neg_lo:[0,1,0] neg_hi:[0,1,0]
	v_pk_fma_f32 v[106:107], v[10:11], v[124:125], v[136:137] op_sel_hi:[1,0,1] neg_lo:[0,1,0] neg_hi:[0,1,0]
	v_pk_fma_f32 v[110:111], v[10:11], v[124:125], v[140:141] op_sel:[0,1,0] neg_lo:[0,1,0] neg_hi:[0,1,0]
	v_pk_mul_f32 v[142:143], v[96:97], v[16:17]
	v_pk_mul_f32 v[144:145], v[100:101], v[16:17]
	v_pk_mul_f32 v[146:147], v[104:105], v[16:17]
	v_pk_mul_f32 v[148:149], v[108:109], v[16:17]
	s_waitcnt vmcnt(15)
	v_pk_fma_f32 v[142:143], v[98:99], v[18:19], v[142:143]
	v_pk_fma_f32 v[144:145], v[102:103], v[18:19], v[144:145]
	v_pk_fma_f32 v[146:147], v[106:107], v[18:19], v[146:147]
	v_pk_fma_f32 v[148:149], v[110:111], v[18:19], v[148:149]
	v_pk_mul_f32 v[114:115], v[96:97], v[24:25]
	v_pk_mul_f32 v[116:117], v[100:101], v[24:25]
	v_pk_mul_f32 v[118:119], v[104:105], v[24:25]
	v_pk_mul_f32 v[120:121], v[108:109], v[24:25]
	v_add_f32_e32 v150, v142, v143
	v_add_f32_e32 v151, v144, v145
	v_add_f32_e32 v152, v146, v147
	v_add_f32_e32 v153, v148, v149
	v_pk_fma_f32 v[114:115], v[98:99], v[26:27], v[114:115]
	v_pk_fma_f32 v[116:117], v[102:103], v[26:27], v[116:117]
	v_pk_fma_f32 v[118:119], v[106:107], v[26:27], v[118:119]
	v_pk_fma_f32 v[120:121], v[110:111], v[26:27], v[120:121]
	v_cndmask_b32_e64 v154, v150, v151, s[100:101]
	v_cndmask_b32_e64 v155, v151, v150, s[100:101]
	v_cndmask_b32_e64 v156, v152, v153, s[100:101]
	v_cndmask_b32_e64 v157, v153, v152, s[100:101]
	v_add_f32_e32 v122, v114, v115
	v_add_f32_e32 v123, v116, v117
	v_add_f32_e32 v124, v118, v119
	v_add_f32_e32 v125, v120, v121
	v_add_f32_dpp v154, v155, v154 quad_perm:[1,0,3,2] row_mask:0xf bank_mask:0xf bound_ctrl:1
	v_add_f32_dpp v156, v157, v156 quad_perm:[1,0,3,2] row_mask:0xf bank_mask:0xf bound_ctrl:1
	v_cndmask_b32_e64 v155, v154, v156, s[98:99]
	v_cndmask_b32_e64 v157, v156, v154, s[98:99]
	v_add_f32_dpp v122, v122, v122 quad_perm:[1,0,3,2] row_mask:0xf bank_mask:0xf bound_ctrl:1
	v_add_f32_dpp v123, v123, v123 quad_perm:[1,0,3,2] row_mask:0xf bank_mask:0xf bound_ctrl:1
	v_add_f32_dpp v124, v124, v124 quad_perm:[1,0,3,2] row_mask:0xf bank_mask:0xf bound_ctrl:1
	v_add_f32_dpp v125, v125, v125 quad_perm:[1,0,3,2] row_mask:0xf bank_mask:0xf bound_ctrl:1
	v_add_f32_dpp v155, v157, v155 quad_perm:[2,3,0,1] row_mask:0xf bank_mask:0xf bound_ctrl:1
	v_add_f32_dpp v122, v122, v122 quad_perm:[2,3,0,1] row_mask:0xf bank_mask:0xf bound_ctrl:1
	v_add_f32_dpp v123, v123, v123 quad_perm:[2,3,0,1] row_mask:0xf bank_mask:0xf bound_ctrl:1
	v_add_f32_dpp v124, v124, v124 quad_perm:[2,3,0,1] row_mask:0xf bank_mask:0xf bound_ctrl:1
	v_add_f32_dpp v125, v125, v125 quad_perm:[2,3,0,1] row_mask:0xf bank_mask:0xf bound_ctrl:1
	v_add_f32_dpp v155, v155, v155 row_ror:4 row_mask:0xf bank_mask:0xf bound_ctrl:1
	v_add_f32_dpp v122, v122, v122 row_ror:4 row_mask:0xf bank_mask:0xf bound_ctrl:1
	v_add_f32_dpp v123, v123, v123 row_ror:4 row_mask:0xf bank_mask:0xf bound_ctrl:1
	v_add_f32_dpp v124, v124, v124 row_ror:4 row_mask:0xf bank_mask:0xf bound_ctrl:1
	v_add_f32_dpp v125, v125, v125 row_ror:4 row_mask:0xf bank_mask:0xf bound_ctrl:1
	v_pk_mul_f32 v[126:127], v[44:45], v[36:37] op_sel_hi:[0,1]
	v_pk_mul_f32 v[130:131], v[44:45], v[36:37] op_sel:[1,0]
	v_pk_mul_f32 v[134:135], v[46:47], v[36:37] op_sel_hi:[0,1]
	v_pk_mul_f32 v[138:139], v[46:47], v[36:37] op_sel:[1,0]
	v_pk_mul_f32 v[128:129], v[44:45], v[38:39] op_sel_hi:[0,1]
	v_pk_mul_f32 v[132:133], v[44:45], v[38:39] op_sel:[1,0]
	v_pk_mul_f32 v[136:137], v[46:47], v[38:39] op_sel_hi:[0,1]
	v_pk_mul_f32 v[140:141], v[46:47], v[38:39] op_sel:[1,0]
	v_pk_fma_f32 v[126:127], v[96:97], v[28:29], v[126:127]
	v_pk_fma_f32 v[130:131], v[100:101], v[28:29], v[130:131]
	v_pk_fma_f32 v[134:135], v[104:105], v[28:29], v[134:135]
	v_pk_fma_f32 v[138:139], v[108:109], v[28:29], v[138:139]
	v_add_f32_dpp v155, v155, v155 row_ror:8 row_mask:0xf bank_mask:0xf bound_ctrl:1
	v_add_f32_dpp v122, v122, v122 row_ror:8 row_mask:0xf bank_mask:0xf bound_ctrl:1
	v_add_f32_dpp v123, v123, v123 row_ror:8 row_mask:0xf bank_mask:0xf bound_ctrl:1
	v_add_f32_dpp v124, v124, v124 row_ror:8 row_mask:0xf bank_mask:0xf bound_ctrl:1
	v_add_f32_dpp v125, v125, v125 row_ror:8 row_mask:0xf bank_mask:0xf bound_ctrl:1
	s_add_i32 s24, s24, s30
	v_pk_fma_f32 v[128:129], v[98:99], v[30:31], v[128:129]
	v_pk_fma_f32 v[132:133], v[102:103], v[30:31], v[132:133]
	v_pk_fma_f32 v[136:137], v[106:107], v[30:31], v[136:137]
	v_pk_fma_f32 v[140:141], v[110:111], v[30:31], v[140:141]
	v_pk_fma_f32 v[96:97], v[32:33], v[122:123], v[126:127] op_sel_hi:[1,0,1] neg_lo:[0,1,0] neg_hi:[0,1,0]
	v_pk_fma_f32 v[100:101], v[32:33], v[122:123], v[130:131] op_sel:[0,1,0] neg_lo:[0,1,0] neg_hi:[0,1,0]
	v_pk_fma_f32 v[104:105], v[32:33], v[124:125], v[134:135] op_sel_hi:[1,0,1] neg_lo:[0,1,0] neg_hi:[0,1,0]
	v_pk_fma_f32 v[108:109], v[32:33], v[124:125], v[138:139] op_sel:[0,1,0] neg_lo:[0,1,0] neg_hi:[0,1,0]
	v_pk_fma_f32 v[98:99], v[34:35], v[122:123], v[128:129] op_sel_hi:[1,0,1] neg_lo:[0,1,0] neg_hi:[0,1,0]
	v_pk_fma_f32 v[102:103], v[34:35], v[122:123], v[132:133] op_sel:[0,1,0] neg_lo:[0,1,0] neg_hi:[0,1,0]
	v_pk_fma_f32 v[106:107], v[34:35], v[124:125], v[136:137] op_sel_hi:[1,0,1] neg_lo:[0,1,0] neg_hi:[0,1,0]
	v_pk_fma_f32 v[110:111], v[34:35], v[124:125], v[140:141] op_sel:[0,1,0] neg_lo:[0,1,0] neg_hi:[0,1,0]
	v_pk_mul_f32 v[142:143], v[96:97], v[40:41]
	v_pk_mul_f32 v[144:145], v[100:101], v[40:41]
	v_pk_mul_f32 v[146:147], v[104:105], v[40:41]
	v_pk_mul_f32 v[148:149], v[108:109], v[40:41]
	buffer_store_dword v155, v164, s[44:47], s24 offen
	v_pk_fma_f32 v[142:143], v[98:99], v[42:43], v[142:143]
	v_pk_fma_f32 v[144:145], v[102:103], v[42:43], v[144:145]
	v_pk_fma_f32 v[146:147], v[106:107], v[42:43], v[146:147]
	v_pk_fma_f32 v[148:149], v[110:111], v[42:43], v[148:149]
	s_waitcnt vmcnt(9)
	v_add_f32_e32 v150, v142, v143
	v_add_f32_e32 v151, v144, v145
	v_add_f32_e32 v152, v146, v147
	v_add_f32_e32 v153, v148, v149
	v_pk_mul_f32 v[114:115], v[96:97], v[48:49]
	v_pk_mul_f32 v[116:117], v[100:101], v[48:49]
	v_pk_mul_f32 v[118:119], v[104:105], v[48:49]
	v_pk_mul_f32 v[120:121], v[108:109], v[48:49]
	v_cndmask_b32_e64 v154, v150, v151, s[100:101]
	v_cndmask_b32_e64 v155, v151, v150, s[100:101]
	v_cndmask_b32_e64 v156, v152, v153, s[100:101]
	v_cndmask_b32_e64 v157, v153, v152, s[100:101]
	v_pk_fma_f32 v[114:115], v[98:99], v[50:51], v[114:115]
	v_pk_fma_f32 v[116:117], v[102:103], v[50:51], v[116:117]
	v_pk_fma_f32 v[118:119], v[106:107], v[50:51], v[118:119]
	v_pk_fma_f32 v[120:121], v[110:111], v[50:51], v[120:121]
	v_add_f32_dpp v154, v155, v154 quad_perm:[1,0,3,2] row_mask:0xf bank_mask:0xf bound_ctrl:1
	v_add_f32_dpp v156, v157, v156 quad_perm:[1,0,3,2] row_mask:0xf bank_mask:0xf bound_ctrl:1
	v_add_f32_e32 v122, v114, v115
	v_add_f32_e32 v123, v116, v117
	v_add_f32_e32 v124, v118, v119
	v_add_f32_e32 v125, v120, v121
	v_cndmask_b32_e64 v155, v154, v156, s[98:99]
	v_cndmask_b32_e64 v157, v156, v154, s[98:99]
	v_add_f32_dpp v122, v122, v122 quad_perm:[1,0,3,2] row_mask:0xf bank_mask:0xf bound_ctrl:1
	v_add_f32_dpp v123, v123, v123 quad_perm:[1,0,3,2] row_mask:0xf bank_mask:0xf bound_ctrl:1
	v_add_f32_dpp v124, v124, v124 quad_perm:[1,0,3,2] row_mask:0xf bank_mask:0xf bound_ctrl:1
	v_add_f32_dpp v125, v125, v125 quad_perm:[1,0,3,2] row_mask:0xf bank_mask:0xf bound_ctrl:1
	v_add_f32_dpp v155, v157, v155 quad_perm:[2,3,0,1] row_mask:0xf bank_mask:0xf bound_ctrl:1
	v_add_f32_dpp v122, v122, v122 quad_perm:[2,3,0,1] row_mask:0xf bank_mask:0xf bound_ctrl:1
	v_add_f32_dpp v123, v123, v123 quad_perm:[2,3,0,1] row_mask:0xf bank_mask:0xf bound_ctrl:1
	v_add_f32_dpp v124, v124, v124 quad_perm:[2,3,0,1] row_mask:0xf bank_mask:0xf bound_ctrl:1
	v_add_f32_dpp v125, v125, v125 quad_perm:[2,3,0,1] row_mask:0xf bank_mask:0xf bound_ctrl:1
	v_add_f32_dpp v155, v155, v155 row_ror:4 row_mask:0xf bank_mask:0xf bound_ctrl:1
	v_add_f32_dpp v122, v122, v122 row_ror:4 row_mask:0xf bank_mask:0xf bound_ctrl:1
	v_add_f32_dpp v123, v123, v123 row_ror:4 row_mask:0xf bank_mask:0xf bound_ctrl:1
	v_add_f32_dpp v124, v124, v124 row_ror:4 row_mask:0xf bank_mask:0xf bound_ctrl:1
	v_add_f32_dpp v125, v125, v125 row_ror:4 row_mask:0xf bank_mask:0xf bound_ctrl:1
	v_pk_mul_f32 v[126:127], v[68:69], v[60:61] op_sel_hi:[0,1]
	v_pk_mul_f32 v[130:131], v[68:69], v[60:61] op_sel:[1,0]
	v_pk_mul_f32 v[134:135], v[70:71], v[60:61] op_sel_hi:[0,1]
	v_pk_mul_f32 v[138:139], v[70:71], v[60:61] op_sel:[1,0]
	v_add_f32_dpp v155, v155, v155 row_ror:8 row_mask:0xf bank_mask:0xf bound_ctrl:1
	s_add_i32 s24, s24, s30
	v_pk_mul_f32 v[128:129], v[68:69], v[62:63] op_sel_hi:[0,1]
	v_pk_mul_f32 v[132:133], v[68:69], v[62:63] op_sel:[1,0]
	v_pk_mul_f32 v[136:137], v[70:71], v[62:63] op_sel_hi:[0,1]
	v_pk_mul_f32 v[140:141], v[70:71], v[62:63] op_sel:[1,0]
	v_pk_fma_f32 v[126:127], v[96:97], v[52:53], v[126:127]
	v_pk_fma_f32 v[130:131], v[100:101], v[52:53], v[130:131]
	v_pk_fma_f32 v[134:135], v[104:105], v[52:53], v[134:135]
	v_pk_fma_f32 v[138:139], v[108:109], v[52:53], v[138:139]
	v_add_f32_dpp v122, v122, v122 row_ror:8 row_mask:0xf bank_mask:0xf bound_ctrl:1
	v_add_f32_dpp v123, v123, v123 row_ror:8 row_mask:0xf bank_mask:0xf bound_ctrl:1
	v_add_f32_dpp v124, v124, v124 row_ror:8 row_mask:0xf bank_mask:0xf bound_ctrl:1
	v_add_f32_dpp v125, v125, v125 row_ror:8 row_mask:0xf bank_mask:0xf bound_ctrl:1
	v_pk_fma_f32 v[128:129], v[98:99], v[54:55], v[128:129]
	v_pk_fma_f32 v[132:133], v[102:103], v[54:55], v[132:133]
	v_pk_fma_f32 v[136:137], v[106:107], v[54:55], v[136:137]
	v_pk_fma_f32 v[140:141], v[110:111], v[54:55], v[140:141]
	v_pk_fma_f32 v[96:97], v[56:57], v[122:123], v[126:127] op_sel_hi:[1,0,1] neg_lo:[0,1,0] neg_hi:[0,1,0]
	v_pk_fma_f32 v[100:101], v[56:57], v[122:123], v[130:131] op_sel:[0,1,0] neg_lo:[0,1,0] neg_hi:[0,1,0]
	v_pk_fma_f32 v[104:105], v[56:57], v[124:125], v[134:135] op_sel_hi:[1,0,1] neg_lo:[0,1,0] neg_hi:[0,1,0]
	v_pk_fma_f32 v[108:109], v[56:57], v[124:125], v[138:139] op_sel:[0,1,0] neg_lo:[0,1,0] neg_hi:[0,1,0]
	buffer_store_dword v155, v164, s[44:47], s24 offen
	v_pk_fma_f32 v[98:99], v[58:59], v[122:123], v[128:129] op_sel_hi:[1,0,1] neg_lo:[0,1,0] neg_hi:[0,1,0]
	v_pk_fma_f32 v[102:103], v[58:59], v[122:123], v[132:133] op_sel:[0,1,0] neg_lo:[0,1,0] neg_hi:[0,1,0]
	v_pk_fma_f32 v[106:107], v[58:59], v[124:125], v[136:137] op_sel_hi:[1,0,1] neg_lo:[0,1,0] neg_hi:[0,1,0]
	v_pk_fma_f32 v[110:111], v[58:59], v[124:125], v[140:141] op_sel:[0,1,0] neg_lo:[0,1,0] neg_hi:[0,1,0]
	s_waitcnt vmcnt(3)
	v_pk_mul_f32 v[114:115], v[96:97], v[72:73]
	v_pk_mul_f32 v[116:117], v[100:101], v[72:73]
	v_pk_mul_f32 v[118:119], v[104:105], v[72:73]
	v_pk_mul_f32 v[120:121], v[108:109], v[72:73]
	v_pk_mul_f32 v[142:143], v[96:97], v[64:65]
	v_pk_mul_f32 v[144:145], v[100:101], v[64:65]
	v_pk_mul_f32 v[146:147], v[104:105], v[64:65]
	v_pk_mul_f32 v[148:149], v[108:109], v[64:65]
	v_pk_fma_f32 v[114:115], v[98:99], v[74:75], v[114:115]
	v_pk_fma_f32 v[116:117], v[102:103], v[74:75], v[116:117]
	v_pk_fma_f32 v[118:119], v[106:107], v[74:75], v[118:119]
	v_pk_fma_f32 v[120:121], v[110:111], v[74:75], v[120:121]
	v_pk_fma_f32 v[142:143], v[98:99], v[66:67], v[142:143]
	v_pk_fma_f32 v[144:145], v[102:103], v[66:67], v[144:145]
	v_pk_fma_f32 v[146:147], v[106:107], v[66:67], v[146:147]
	v_pk_fma_f32 v[148:149], v[110:111], v[66:67], v[148:149]
	v_add_f32_e32 v122, v114, v115
	v_add_f32_e32 v123, v116, v117
	v_add_f32_e32 v124, v118, v119
	v_add_f32_e32 v125, v120, v121
	v_add_f32_e32 v150, v142, v143
	v_add_f32_e32 v151, v144, v145
	v_add_f32_e32 v152, v146, v147
	v_add_f32_e32 v153, v148, v149
	v_cndmask_b32_e64 v154, v150, v151, s[100:101]
	v_cndmask_b32_e64 v155, v151, v150, s[100:101]
	v_cndmask_b32_e64 v156, v152, v153, s[100:101]
	v_cndmask_b32_e64 v157, v153, v152, s[100:101]
	v_add_f32_dpp v122, v122, v122 quad_perm:[1,0,3,2] row_mask:0xf bank_mask:0xf bound_ctrl:1
	v_add_f32_dpp v123, v123, v123 quad_perm:[1,0,3,2] row_mask:0xf bank_mask:0xf bound_ctrl:1
	v_add_f32_dpp v124, v124, v124 quad_perm:[1,0,3,2] row_mask:0xf bank_mask:0xf bound_ctrl:1
	v_add_f32_dpp v125, v125, v125 quad_perm:[1,0,3,2] row_mask:0xf bank_mask:0xf bound_ctrl:1
	v_add_f32_dpp v154, v155, v154 quad_perm:[1,0,3,2] row_mask:0xf bank_mask:0xf bound_ctrl:1
	v_add_f32_dpp v156, v157, v156 quad_perm:[1,0,3,2] row_mask:0xf bank_mask:0xf bound_ctrl:1
	v_add_f32_dpp v122, v122, v122 quad_perm:[2,3,0,1] row_mask:0xf bank_mask:0xf bound_ctrl:1
	v_add_f32_dpp v123, v123, v123 quad_perm:[2,3,0,1] row_mask:0xf bank_mask:0xf bound_ctrl:1
	v_add_f32_dpp v124, v124, v124 quad_perm:[2,3,0,1] row_mask:0xf bank_mask:0xf bound_ctrl:1
	v_add_f32_dpp v125, v125, v125 quad_perm:[2,3,0,1] row_mask:0xf bank_mask:0xf bound_ctrl:1
	v_cndmask_b32_e64 v155, v154, v156, s[98:99]
	v_cndmask_b32_e64 v157, v156, v154, s[98:99]
	v_add_f32_dpp v122, v122, v122 row_ror:4 row_mask:0xf bank_mask:0xf bound_ctrl:1
	v_add_f32_dpp v123, v123, v123 row_ror:4 row_mask:0xf bank_mask:0xf bound_ctrl:1
	v_add_f32_dpp v124, v124, v124 row_ror:4 row_mask:0xf bank_mask:0xf bound_ctrl:1
	v_add_f32_dpp v125, v125, v125 row_ror:4 row_mask:0xf bank_mask:0xf bound_ctrl:1
	v_pk_mul_f32 v[126:127], v[92:93], v[84:85] op_sel_hi:[0,1]
	v_pk_mul_f32 v[130:131], v[92:93], v[84:85] op_sel:[1,0]
	v_pk_mul_f32 v[134:135], v[94:95], v[84:85] op_sel_hi:[0,1]
	v_pk_mul_f32 v[138:139], v[94:95], v[84:85] op_sel:[1,0]
	v_add_f32_dpp v155, v157, v155 quad_perm:[2,3,0,1] row_mask:0xf bank_mask:0xf bound_ctrl:1
	v_pk_mul_f32 v[128:129], v[92:93], v[86:87] op_sel_hi:[0,1]
	v_pk_mul_f32 v[132:133], v[92:93], v[86:87] op_sel:[1,0]
	v_pk_mul_f32 v[136:137], v[94:95], v[86:87] op_sel_hi:[0,1]
	v_pk_mul_f32 v[140:141], v[94:95], v[86:87] op_sel:[1,0]
	v_pk_fma_f32 v[126:127], v[96:97], v[76:77], v[126:127]
	v_pk_fma_f32 v[130:131], v[100:101], v[76:77], v[130:131]
	v_pk_fma_f32 v[134:135], v[104:105], v[76:77], v[134:135]
	v_pk_fma_f32 v[138:139], v[108:109], v[76:77], v[138:139]
	v_add_f32_dpp v122, v122, v122 row_ror:8 row_mask:0xf bank_mask:0xf bound_ctrl:1
	v_add_f32_dpp v123, v123, v123 row_ror:8 row_mask:0xf bank_mask:0xf bound_ctrl:1
	v_add_f32_dpp v124, v124, v124 row_ror:8 row_mask:0xf bank_mask:0xf bound_ctrl:1
	v_add_f32_dpp v125, v125, v125 row_ror:8 row_mask:0xf bank_mask:0xf bound_ctrl:1
	v_add_f32_dpp v155, v155, v155 row_ror:4 row_mask:0xf bank_mask:0xf bound_ctrl:1
	v_pk_fma_f32 v[128:129], v[98:99], v[78:79], v[128:129]
	v_pk_fma_f32 v[132:133], v[102:103], v[78:79], v[132:133]
	v_pk_fma_f32 v[136:137], v[106:107], v[78:79], v[136:137]
	v_pk_fma_f32 v[140:141], v[110:111], v[78:79], v[140:141]
	v_pk_fma_f32 v[96:97], v[80:81], v[122:123], v[126:127] op_sel_hi:[1,0,1] neg_lo:[0,1,0] neg_hi:[0,1,0]
	v_pk_fma_f32 v[100:101], v[80:81], v[122:123], v[130:131] op_sel:[0,1,0] neg_lo:[0,1,0] neg_hi:[0,1,0]
	v_pk_fma_f32 v[104:105], v[80:81], v[124:125], v[134:135] op_sel_hi:[1,0,1] neg_lo:[0,1,0] neg_hi:[0,1,0]
	v_pk_fma_f32 v[108:109], v[80:81], v[124:125], v[138:139] op_sel:[0,1,0] neg_lo:[0,1,0] neg_hi:[0,1,0]
	v_pk_fma_f32 v[98:99], v[82:83], v[122:123], v[128:129] op_sel_hi:[1,0,1] neg_lo:[0,1,0] neg_hi:[0,1,0]
	v_pk_fma_f32 v[102:103], v[82:83], v[122:123], v[132:133] op_sel:[0,1,0] neg_lo:[0,1,0] neg_hi:[0,1,0]
	v_pk_fma_f32 v[106:107], v[82:83], v[124:125], v[136:137] op_sel_hi:[1,0,1] neg_lo:[0,1,0] neg_hi:[0,1,0]
	v_pk_fma_f32 v[110:111], v[82:83], v[124:125], v[140:141] op_sel:[0,1,0] neg_lo:[0,1,0] neg_hi:[0,1,0]
	v_pk_mul_f32 v[142:143], v[96:97], v[88:89]
	v_pk_mul_f32 v[144:145], v[100:101], v[88:89]
	v_pk_mul_f32 v[146:147], v[104:105], v[88:89]
	v_pk_mul_f32 v[148:149], v[108:109], v[88:89]
	v_add_f32_dpp v155, v155, v155 row_ror:8 row_mask:0xf bank_mask:0xf bound_ctrl:1
	s_add_i32 s24, s24, s30
	v_pk_fma_f32 v[142:143], v[98:99], v[90:91], v[142:143]
	v_pk_fma_f32 v[144:145], v[102:103], v[90:91], v[144:145]
	v_pk_fma_f32 v[146:147], v[106:107], v[90:91], v[146:147]
	v_pk_fma_f32 v[148:149], v[110:111], v[90:91], v[148:149]
	v_add_f32_e32 v150, v142, v143
	v_add_f32_e32 v151, v144, v145
	v_add_f32_e32 v152, v146, v147
	v_add_f32_e32 v153, v148, v149
	buffer_store_dword v155, v164, s[44:47], s24 offen
	v_cndmask_b32_e64 v154, v150, v151, s[100:101]
	v_cndmask_b32_e64 v155, v151, v150, s[100:101]
	v_cndmask_b32_e64 v156, v152, v153, s[100:101]
	v_cndmask_b32_e64 v157, v153, v152, s[100:101]
	v_add_f32_dpp v154, v155, v154 quad_perm:[1,0,3,2] row_mask:0xf bank_mask:0xf bound_ctrl:1
	s_add_i32 s8, s8, s25
	v_add_f32_dpp v156, v157, v156 quad_perm:[1,0,3,2] row_mask:0xf bank_mask:0xf bound_ctrl:1
	v_cndmask_b32_e64 v155, v154, v156, s[98:99]
	v_cndmask_b32_e64 v157, v156, v154, s[98:99]
	s_add_i32 s9, s9, s30
	s_add_i32 s24, s24, s30
	v_add_f32_dpp v155, v157, v155 quad_perm:[2,3,0,1] row_mask:0xf bank_mask:0xf bound_ctrl:1
	s_nop 0
	s_nop 0
	v_add_f32_dpp v155, v155, v155 row_ror:4 row_mask:0xf bank_mask:0xf bound_ctrl:1
	s_nop 0
	s_nop 0
	v_add_f32_dpp v155, v155, v155 row_ror:8 row_mask:0xf bank_mask:0xf bound_ctrl:1
	buffer_store_dword v155, v164, s[44:47], s24 offen
	s_add_i32 s24, s24, s30
	s_nop 1
	global_store_dwordx4 v166, v[96:99], s[10:11] offset:0
	global_store_dwordx4 v166, v[100:103], s[10:11] offset:256
	global_store_dwordx4 v166, v[104:107], s[10:11] offset:512
	global_store_dwordx4 v166, v[108:111], s[10:11] offset:768
	s_lshl_b32 s3, s94, 2
	s_add_i32 s22, s22, s3
	s_branch .Lps_item
.Lps_done:
.LBB0_607:
	s_or_b64 exec, exec, s[20:21]
	s_load_dword s3, s[84:85], 0x10
	s_load_dword s6, s[84:85], 0x0
	s_movk_i32 s4, 0x4100
	s_waitcnt vmcnt(17)
	v_mul_lo_u32 v39, v113, s4
	v_mov_b32_e32 v0, v190
	s_waitcnt lgkmcnt(0)
	s_lshr_b32 s3, s3, 16
	s_cmp_lg_u32 s3, 0
	s_cselect_b64 s[4:5], -1, 0
	s_cmp_lg_u64 s[4:5], 0
	s_addc_u32 s3, s6, 0
	s_mul_i32 s10, s3, 6
	s_movk_i32 s3, 0x400
	v_cmp_gt_i32_e64 s[4:5], s3, v112
	v_lshlrev_b32_e32 v38, 6, v112
	s_and_saveexec_b64 s[6:7], s[4:5]
	s_cbranch_execz .LBB0_610
	v_and_b32_e32 v4, 63, v0
	v_bfe_u32 v5, v0, 4, 2
	v_lshlrev_b32_e32 v0, 4, v0
	v_readlane_b32 s36, v241, 35
	v_and_b32_e32 v2, 0xf0, v0
	v_mov_b32_e32 v3, 0
	v_readlane_b32 s38, v241, 37
	v_readlane_b32 s39, v241, 38
	s_add_u32 s8, s92, 0x1380000
	v_lshl_add_u32 v6, v4, 2, v39
	v_lshl_add_u64 v[0:1], s[38:39], 0, v[2:3]
	v_mul_u32_u24_e32 v3, 0x104, v5
	v_add3_u32 v7, v39, v3, v2
	s_addc_u32 s9, s93, 0
	v_lshlrev_b32_e32 v8, 6, v112
	s_lshl_b32 s3, s10, 6
	s_mov_b64 s[20:21], 0
	v_add_u32_e32 v9, 0x410, v7
	v_add_u32_e32 v10, 0x418, v7
	v_add_u32_e32 v11, 0x820, v7
	v_add_u32_e32 v12, 0x828, v7
	v_add_u32_e32 v13, 0xc30, v7
	v_add_u32_e32 v14, 0xc38, v7
	v_add_u32_e32 v15, 0x1040, v7
	v_add_u32_e32 v16, 0x1048, v7
	v_add_u32_e32 v17, 0x1450, v7
	v_add_u32_e32 v18, 0x1458, v7
	v_add_u32_e32 v19, 0x1860, v7
	v_add_u32_e32 v20, 0x1868, v7
	v_add_u32_e32 v21, 0x1c70, v7
	v_add_u32_e32 v22, 0x1c78, v7
	v_add_u32_e32 v23, 0x2080, v7
	v_add_u32_e32 v24, 0x2088, v7
	v_add_u32_e32 v25, 0x2490, v7
	v_add_u32_e32 v26, 0x2498, v7
	v_add_u32_e32 v27, 0x28a0, v7
	v_add_u32_e32 v28, 0x28a8, v7
	v_add_u32_e32 v29, 0x2cb0, v7
	v_add_u32_e32 v30, 0x2cb8, v7
	v_add_u32_e32 v31, 0x30c0, v7
	v_add_u32_e32 v32, 0x30c8, v7
	v_add_u32_e32 v33, 0x34d0, v7
	v_add_u32_e32 v34, 0x34d8, v7
	v_add_u32_e32 v35, 0x38e0, v7
	v_add_u32_e32 v36, 0x38e8, v7
	v_add_u32_e32 v37, 0x3cf0, v7
	s_waitcnt vmcnt(16)
	v_add_u32_e32 v40, 0x3cf8, v7
	s_movk_i32 s11, 0x7fff
	s_mov_b32 s22, 0xffff0000
	s_movk_i32 s23, 0x3ff
	v_add_u32_e32 v41, 0x400, v6
	v_add_u32_e32 v42, 0x800, v6
	v_add_u32_e32 v43, 0xc00, v6
	v_add_u32_e32 v44, 0x1000, v6
	v_add_u32_e32 v45, 0x1400, v6
	v_add_u32_e32 v46, 0x1800, v6
	v_add_u32_e32 v47, 0x1c00, v6
	s_waitcnt vmcnt(14)
	v_add_u32_e32 v48, 0x2000, v6
	v_add_u32_e32 v49, 0x2400, v6
	v_add_u32_e32 v50, 0x2800, v6
	v_add_u32_e32 v51, 0x2c00, v6
	s_waitcnt vmcnt(13)
	v_add_u32_e32 v52, 0x3000, v6
	v_add_u32_e32 v53, 0x3400, v6
	v_add_u32_e32 v54, 0x3800, v6
	v_add_u32_e32 v55, 0x3c00, v6
	s_waitcnt vmcnt(12)
	v_mov_b32_e32 v56, v112
	v_readlane_b32 s37, v241, 36
	v_readlane_b32 s40, v241, 39
	v_readlane_b32 s41, v241, 40
	v_readlane_b32 s42, v241, 41
	v_readlane_b32 s43, v241, 42
	v_readlane_b32 s44, v241, 43
	v_readlane_b32 s45, v241, 44
	v_readlane_b32 s46, v241, 45
	v_readlane_b32 s47, v241, 46
	v_readlane_b32 s48, v241, 47
	v_readlane_b32 s49, v241, 48
	v_readlane_b32 s50, v241, 49
	v_readlane_b32 s51, v241, 50

.LBB0_636:
	s_andn2_saveexec_b64 s[10:11], s[16:17]
	s_cbranch_execz .LBB0_676
	s_setprio 3
	v_readlane_b32 s2, v240, 10
	v_readfirstlane_b32 s3, v0
	v_and_b32_e32 v224, 63, v190
	v_and_b32_e32 v225, 15, v224
	v_lshrrev_b32_e32 v226, 4, v224
	v_and_b32_e32 v227, 1, v225
	v_cmp_ne_u32_e64 s[100:101], 0, v227
	s_lshl_b32 s2, s2, 1
	s_add_i32 s2, s2, s3
	s_add_u32 s36, s92, 0x17c24000
	s_addc_u32 s37, s93, 0
	s_and_b32 s37, s37, 0xffff
	s_mov_b32 s38, 0x20000000
	s_mov_b32 s39, 0x20000
	s_add_u32 s40, s92, 0x23c24000
	s_addc_u32 s41, s93, 0
	s_and_b32 s41, s41, 0xffff
	s_mov_b32 s42, 0x20000000
	s_mov_b32 s43, 0x20000
	s_mov_b32 s44, s90
	s_mov_b32 s45, s91
	s_and_b32 s45, s45, 0xffff
	s_mov_b32 s46, 0x10000000
	s_mov_b32 s47, 0x20000
.Lss_item:
	s_cmpk_lt_i32 s2, 0x200
	s_cbranch_scc0 .Lss_done
	s_and_b32 s3, s2, 7
	s_lshr_b32 s99, s2, 3
	s_bfe_u32 s98, s99, 0x10004
	s_lshr_b32 s25, s99, 5
	s_and_b32 s99, s99, 15
	s_lshl_b32 s24, s25, 1
	s_add_i32 s24, s24, s98
	s_lshl_b32 s24, s24, 4
	s_add_i32 s24, s24, s99
	s_lshl_b32 s24, s24, 14
	v_readlane_b32 s8, v241, 27
	v_readlane_b32 s9, v241, 28
	s_add_u32 s8, s8, s24
	s_addc_u32 s9, s9, 0
	s_lshl_b32 s24, s3, 11
	v_lshlrev_b32_e32 v224, 9, v226
	v_lshl_add_u32 v224, v225, 4, v224
	v_add_u32_e32 v224, s24, v224
	s_nop 0
	global_load_dwordx4 v[176:179], v224, s[8:9]
	global_load_dwordx4 v[180:183], v224, s[8:9] offset:256
	s_lshl_b32 s24, s99, 8
	v_lshl_add_u32 v217, v225, 4, s24
	s_lshl_b32 s99, s98, 12
	v_add_u32_e32 v219, s99, v217
	s_lshl_b32 s3, s3, 5
	s_add_i32 s3, s3, s24
	v_lshl_add_u32 v228, v226, 3, s3
	v_lshl_add_u32 v222, v227, 2, v228
	v_add_u32_e32 v222, s99, v222
	v_add_u32_e32 v216, 0x4000000, v217
	v_add_u32_e32 v218, 0x8000000, v228
	v_add_u32_e32 v220, 0x8000000, v219
	v_add_u32_e32 v221, 0x10000000, v219
	s_lshl_b32 s30, s25, 12
	s_addk_i32 s30, 0x2000
	s_mul_i32 s8, s98, 0xfff
	s_add_i32 s30, s30, s8
	s_lshl_b32 s8, s30, 12
	s_lshl_b32 s9, s30, 13
	s_mov_b32 s24, s9
	s_mul_i32 s25, s98, 0xffffe000
	s_addk_i32 s25, 0x1000
	s_lshl_b32 s30, s25, 1
	buffer_load_dwordx4 v[0:3], v216, s[36:39], s8 offen
	buffer_load_dwordx4 v[12:15], v221, s[40:43], s9 offen
	buffer_load_dwordx2 v[20:21], v218, s[36:39], s8 offen
	buffer_load_dwordx4 v[4:7], v219, s[40:43], s9 offen
	buffer_load_dwordx4 v[8:11], v220, s[40:43], s9 offen
	buffer_load_dwordx4 v[16:19], v217, s[36:39], s8 offen
	s_add_i32 s8, s8, s25
	s_add_i32 s9, s9, s30
	buffer_load_dwordx4 v[22:25], v216, s[36:39], s8 offen
	buffer_load_dwordx4 v[34:37], v221, s[40:43], s9 offen
	buffer_load_dwordx2 v[42:43], v218, s[36:39], s8 offen
	buffer_load_dwordx4 v[26:29], v219, s[40:43], s9 offen
	buffer_load_dwordx4 v[30:33], v220, s[40:43], s9 offen
	buffer_load_dwordx4 v[38:41], v217, s[36:39], s8 offen
	s_add_i32 s8, s8, s25
	s_add_i32 s9, s9, s30
	buffer_load_dwordx4 v[44:47], v216, s[36:39], s8 offen
	buffer_load_dwordx4 v[56:59], v221, s[40:43], s9 offen
	buffer_load_dwordx2 v[64:65], v218, s[36:39], s8 offen
	buffer_load_dwordx4 v[48:51], v219, s[40:43], s9 offen
	buffer_load_dwordx4 v[52:55], v220, s[40:43], s9 offen
	buffer_load_dwordx4 v[60:63], v217, s[36:39], s8 offen
	s_add_i32 s8, s8, s25
	s_add_i32 s9, s9, s30
	buffer_load_dwordx4 v[66:69], v216, s[36:39], s8 offen
	buffer_load_dwordx4 v[78:81], v221, s[40:43], s9 offen
	buffer_load_dwordx2 v[86:87], v218, s[36:39], s8 offen
	buffer_load_dwordx4 v[70:73], v219, s[40:43], s9 offen
	buffer_load_dwordx4 v[74:77], v220, s[40:43], s9 offen
	buffer_load_dwordx4 v[82:85], v217, s[36:39], s8 offen
	s_add_i32 s8, s8, s25
	s_add_i32 s9, s9, s30
	buffer_load_dwordx4 v[88:91], v216, s[36:39], s8 offen
	buffer_load_dwordx4 v[100:103], v221, s[40:43], s9 offen
	buffer_load_dwordx2 v[108:109], v218, s[36:39], s8 offen
	buffer_load_dwordx4 v[92:95], v219, s[40:43], s9 offen
	buffer_load_dwordx4 v[96:99], v220, s[40:43], s9 offen
	buffer_load_dwordx4 v[104:107], v217, s[36:39], s8 offen
	s_add_i32 s8, s8, s25
	s_add_i32 s9, s9, s30
	buffer_load_dwordx4 v[110:113], v216, s[36:39], s8 offen
	buffer_load_dwordx4 v[122:125], v221, s[40:43], s9 offen
	buffer_load_dwordx2 v[130:131], v218, s[36:39], s8 offen
	buffer_load_dwordx4 v[114:117], v219, s[40:43], s9 offen
	buffer_load_dwordx4 v[118:121], v220, s[40:43], s9 offen
	buffer_load_dwordx4 v[126:129], v217, s[36:39], s8 offen
	s_add_i32 s8, s8, s25
	s_add_i32 s9, s9, s30
	buffer_load_dwordx4 v[132:135], v216, s[36:39], s8 offen
	buffer_load_dwordx4 v[144:147], v221, s[40:43], s9 offen
	buffer_load_dwordx2 v[152:153], v218, s[36:39], s8 offen
	buffer_load_dwordx4 v[136:139], v219, s[40:43], s9 offen
	buffer_load_dwordx4 v[140:143], v220, s[40:43], s9 offen
	buffer_load_dwordx4 v[148:151], v217, s[36:39], s8 offen
	s_add_i32 s8, s8, s25
	s_add_i32 s9, s9, s30
	buffer_load_dwordx4 v[154:157], v216, s[36:39], s8 offen
	buffer_load_dwordx4 v[166:169], v221, s[40:43], s9 offen
	buffer_load_dwordx2 v[174:175], v218, s[36:39], s8 offen
	buffer_load_dwordx4 v[158:161], v219, s[40:43], s9 offen
	buffer_load_dwordx4 v[162:165], v220, s[40:43], s9 offen
	buffer_load_dwordx4 v[170:173], v217, s[36:39], s8 offen
	s_add_i32 s8, s8, s25
	s_add_i32 s9, s9, s30
	s_movk_i32 s98, 510
	s_waitcnt vmcnt(42)
	v_pk_mul_f32 v[192:193], v[176:177], v[0:1]
	v_pk_mul_f32 v[194:195], v[180:181], v[0:1]
	v_pk_fma_f32 v[192:193], v[178:179], v[2:3], v[192:193]
	v_pk_fma_f32 v[194:195], v[182:183], v[2:3], v[194:195]
	v_add_f32_e32 v196, v192, v193
	v_add_f32_e32 v197, v194, v195
	v_pk_mul_f32 v[198:199], v[20:21], v[12:13] op_sel_hi:[0,1]
	v_add_f32_dpp v196, v196, v196 quad_perm:[1,0,3,2] row_mask:0xf bank_mask:0xf bound_ctrl:1
	v_add_f32_dpp v197, v197, v197 quad_perm:[1,0,3,2] row_mask:0xf bank_mask:0xf bound_ctrl:1
	v_pk_mul_f32 v[202:203], v[20:21], v[12:13] op_sel:[1,0]
	v_add_f32_dpp v196, v196, v196 quad_perm:[2,3,0,1] row_mask:0xf bank_mask:0xf bound_ctrl:1
	v_add_f32_dpp v197, v197, v197 quad_perm:[2,3,0,1] row_mask:0xf bank_mask:0xf bound_ctrl:1
	v_pk_mul_f32 v[200:201], v[20:21], v[14:15] op_sel_hi:[0,1]
	v_add_f32_dpp v196, v196, v196 row_ror:4 row_mask:0xf bank_mask:0xf bound_ctrl:1
	v_add_f32_dpp v197, v197, v197 row_ror:4 row_mask:0xf bank_mask:0xf bound_ctrl:1
	v_pk_mul_f32 v[204:205], v[20:21], v[14:15] op_sel:[1,0]
	v_pk_fma_f32 v[198:199], v[176:177], v[4:5], v[198:199]
	v_pk_fma_f32 v[202:203], v[180:181], v[4:5], v[202:203]
	v_add_f32_dpp v196, v196, v196 row_ror:8 row_mask:0xf bank_mask:0xf bound_ctrl:1
	v_add_f32_dpp v197, v197, v197 row_ror:8 row_mask:0xf bank_mask:0xf bound_ctrl:1
	v_pk_fma_f32 v[200:201], v[178:179], v[6:7], v[200:201]
	v_pk_fma_f32 v[204:205], v[182:183], v[6:7], v[204:205]
	v_pk_fma_f32 v[176:177], v[8:9], v[196:197], v[198:199] op_sel_hi:[1,0,1] neg_lo:[0,1,0] neg_hi:[0,1,0]
	v_pk_fma_f32 v[180:181], v[8:9], v[196:197], v[202:203] op_sel:[0,1,0] neg_lo:[0,1,0] neg_hi:[0,1,0]
	v_pk_fma_f32 v[178:179], v[10:11], v[196:197], v[200:201] op_sel_hi:[1,0,1] neg_lo:[0,1,0] neg_hi:[0,1,0]
	v_pk_fma_f32 v[182:183], v[10:11], v[196:197], v[204:205] op_sel:[0,1,0] neg_lo:[0,1,0] neg_hi:[0,1,0]
	v_pk_mul_f32 v[206:207], v[176:177], v[16:17]
	v_pk_mul_f32 v[208:209], v[180:181], v[16:17]
	v_pk_fma_f32 v[206:207], v[178:179], v[18:19], v[206:207]
	v_pk_fma_f32 v[208:209], v[182:183], v[18:19], v[208:209]
	v_add_f32_e32 v210, v206, v207
	v_add_f32_e32 v211, v208, v209
	v_cndmask_b32_e64 v212, v210, v211, s[100:101]
	v_cndmask_b32_e64 v213, v211, v210, s[100:101]
	buffer_load_dwordx4 v[0:3], v216, s[36:39], s8 offen
	buffer_load_dwordx4 v[12:15], v221, s[40:43], s9 offen
	v_add_f32_dpp v212, v213, v212 quad_perm:[1,0,3,2] row_mask:0xf bank_mask:0xf bound_ctrl:1
	buffer_load_dwordx2 v[20:21], v218, s[36:39], s8 offen
	buffer_load_dwordx4 v[4:7], v219, s[40:43], s9 offen
	v_add_f32_dpp v212, v212, v212 quad_perm:[2,3,0,1] row_mask:0xf bank_mask:0xf bound_ctrl:1
	buffer_load_dwordx4 v[8:11], v220, s[40:43], s9 offen
	buffer_load_dwordx4 v[16:19], v217, s[36:39], s8 offen
	v_add_f32_dpp v212, v212, v212 row_ror:4 row_mask:0xf bank_mask:0xf bound_ctrl:1
	s_add_i32 s8, s8, s25
	s_add_i32 s9, s9, s30
	v_add_f32_dpp v212, v212, v212 row_ror:8 row_mask:0xf bank_mask:0xf bound_ctrl:1
	s_nop 1
.Lss_loop:
	s_waitcnt vmcnt(42)
	v_pk_mul_f32 v[192:193], v[176:177], v[22:23]
	v_pk_mul_f32 v[194:195], v[180:181], v[22:23]
	v_pk_fma_f32 v[192:193], v[178:179], v[24:25], v[192:193]
	v_pk_fma_f32 v[194:195], v[182:183], v[24:25], v[194:195]
	v_add_f32_e32 v196, v192, v193
	v_add_f32_e32 v197, v194, v195
	v_pk_mul_f32 v[198:199], v[42:43], v[34:35] op_sel_hi:[0,1]
	v_add_f32_dpp v196, v196, v196 quad_perm:[1,0,3,2] row_mask:0xf bank_mask:0xf bound_ctrl:1
	v_add_f32_dpp v197, v197, v197 quad_perm:[1,0,3,2] row_mask:0xf bank_mask:0xf bound_ctrl:1
	v_pk_mul_f32 v[202:203], v[42:43], v[34:35] op_sel:[1,0]
	v_add_f32_dpp v196, v196, v196 quad_perm:[2,3,0,1] row_mask:0xf bank_mask:0xf bound_ctrl:1
	v_add_f32_dpp v197, v197, v197 quad_perm:[2,3,0,1] row_mask:0xf bank_mask:0xf bound_ctrl:1
	v_pk_mul_f32 v[200:201], v[42:43], v[36:37] op_sel_hi:[0,1]
	v_add_f32_dpp v196, v196, v196 row_ror:4 row_mask:0xf bank_mask:0xf bound_ctrl:1
	v_add_f32_dpp v197, v197, v197 row_ror:4 row_mask:0xf bank_mask:0xf bound_ctrl:1
	v_pk_mul_f32 v[204:205], v[42:43], v[36:37] op_sel:[1,0]
	v_pk_fma_f32 v[198:199], v[176:177], v[26:27], v[198:199]
	v_pk_fma_f32 v[202:203], v[180:181], v[26:27], v[202:203]
	v_add_f32_dpp v196, v196, v196 row_ror:8 row_mask:0xf bank_mask:0xf bound_ctrl:1
	v_add_f32_dpp v197, v197, v197 row_ror:8 row_mask:0xf bank_mask:0xf bound_ctrl:1
	buffer_store_dword v212, v222, s[44:47], s24 offen
	v_pk_fma_f32 v[200:201], v[178:179], v[28:29], v[200:201]
	v_pk_fma_f32 v[204:205], v[182:183], v[28:29], v[204:205]
	v_pk_fma_f32 v[176:177], v[30:31], v[196:197], v[198:199] op_sel_hi:[1,0,1] neg_lo:[0,1,0] neg_hi:[0,1,0]
	v_pk_fma_f32 v[180:181], v[30:31], v[196:197], v[202:203] op_sel:[0,1,0] neg_lo:[0,1,0] neg_hi:[0,1,0]
	v_pk_fma_f32 v[178:179], v[32:33], v[196:197], v[200:201] op_sel_hi:[1,0,1] neg_lo:[0,1,0] neg_hi:[0,1,0]
	v_pk_fma_f32 v[182:183], v[32:33], v[196:197], v[204:205] op_sel:[0,1,0] neg_lo:[0,1,0] neg_hi:[0,1,0]
	v_pk_mul_f32 v[206:207], v[176:177], v[38:39]
	v_pk_mul_f32 v[208:209], v[180:181], v[38:39]
	v_pk_fma_f32 v[206:207], v[178:179], v[40:41], v[206:207]
	v_pk_fma_f32 v[208:209], v[182:183], v[40:41], v[208:209]
	buffer_load_dwordx4 v[22:25], v216, s[36:39], s8 offen
	buffer_load_dwordx4 v[34:37], v221, s[40:43], s9 offen
	buffer_load_dwordx2 v[42:43], v218, s[36:39], s8 offen
	v_add_f32_e32 v210, v206, v207
	v_add_f32_e32 v211, v208, v209
	buffer_load_dwordx4 v[26:29], v219, s[40:43], s9 offen
	v_cndmask_b32_e64 v212, v210, v211, s[100:101]
	v_cndmask_b32_e64 v213, v211, v210, s[100:101]
	buffer_load_dwordx4 v[30:33], v220, s[40:43], s9 offen
	buffer_load_dwordx4 v[38:41], v217, s[36:39], s8 offen
	s_waitcnt vmcnt(43)
	v_pk_mul_f32 v[192:193], v[176:177], v[44:45]
	v_pk_mul_f32 v[194:195], v[180:181], v[44:45]
	v_pk_fma_f32 v[192:193], v[178:179], v[46:47], v[192:193]
	v_pk_fma_f32 v[194:195], v[182:183], v[46:47], v[194:195]
	v_add_f32_dpp v212, v213, v212 quad_perm:[1,0,3,2] row_mask:0xf bank_mask:0xf bound_ctrl:1
	v_add_f32_e32 v196, v192, v193
	v_add_f32_e32 v197, v194, v195
	v_add_f32_dpp v212, v212, v212 quad_perm:[2,3,0,1] row_mask:0xf bank_mask:0xf bound_ctrl:1
	v_add_f32_dpp v196, v196, v196 quad_perm:[1,0,3,2] row_mask:0xf bank_mask:0xf bound_ctrl:1
	v_add_f32_dpp v197, v197, v197 quad_perm:[1,0,3,2] row_mask:0xf bank_mask:0xf bound_ctrl:1
	v_add_f32_dpp v212, v212, v212 row_ror:4 row_mask:0xf bank_mask:0xf bound_ctrl:1
	v_add_f32_dpp v196, v196, v196 quad_perm:[2,3,0,1] row_mask:0xf bank_mask:0xf bound_ctrl:1
	v_add_f32_dpp v197, v197, v197 quad_perm:[2,3,0,1] row_mask:0xf bank_mask:0xf bound_ctrl:1
	v_add_f32_dpp v212, v212, v212 row_ror:8 row_mask:0xf bank_mask:0xf bound_ctrl:1
	v_add_f32_dpp v196, v196, v196 row_ror:4 row_mask:0xf bank_mask:0xf bound_ctrl:1
	v_add_f32_dpp v197, v197, v197 row_ror:4 row_mask:0xf bank_mask:0xf bound_ctrl:1
	v_pk_mul_f32 v[198:199], v[64:65], v[56:57] op_sel_hi:[0,1]
	v_pk_mul_f32 v[202:203], v[64:65], v[56:57] op_sel:[1,0]
	s_add_i32 s24, s24, s30
	v_pk_mul_f32 v[200:201], v[64:65], v[58:59] op_sel_hi:[0,1]
	v_pk_mul_f32 v[204:205], v[64:65], v[58:59] op_sel:[1,0]
	v_pk_fma_f32 v[198:199], v[176:177], v[48:49], v[198:199]
	v_pk_fma_f32 v[202:203], v[180:181], v[48:49], v[202:203]
	v_add_f32_dpp v196, v196, v196 row_ror:8 row_mask:0xf bank_mask:0xf bound_ctrl:1
	v_add_f32_dpp v197, v197, v197 row_ror:8 row_mask:0xf bank_mask:0xf bound_ctrl:1
	buffer_store_dword v212, v222, s[44:47], s24 offen
	v_pk_fma_f32 v[200:201], v[178:179], v[50:51], v[200:201]
	v_pk_fma_f32 v[204:205], v[182:183], v[50:51], v[204:205]
	v_pk_fma_f32 v[176:177], v[52:53], v[196:197], v[198:199] op_sel_hi:[1,0,1] neg_lo:[0,1,0] neg_hi:[0,1,0]
	v_pk_fma_f32 v[180:181], v[52:53], v[196:197], v[202:203] op_sel:[0,1,0] neg_lo:[0,1,0] neg_hi:[0,1,0]
	v_pk_fma_f32 v[178:179], v[54:55], v[196:197], v[200:201] op_sel_hi:[1,0,1] neg_lo:[0,1,0] neg_hi:[0,1,0]
	v_pk_fma_f32 v[182:183], v[54:55], v[196:197], v[204:205] op_sel:[0,1,0] neg_lo:[0,1,0] neg_hi:[0,1,0]
	v_pk_mul_f32 v[206:207], v[176:177], v[60:61]
	v_pk_mul_f32 v[208:209], v[180:181], v[60:61]
	s_add_i32 s8, s8, s25
	s_add_i32 s9, s9, s30
	v_pk_fma_f32 v[206:207], v[178:179], v[62:63], v[206:207]
	v_pk_fma_f32 v[208:209], v[182:183], v[62:63], v[208:209]
	buffer_load_dwordx4 v[44:47], v216, s[36:39], s8 offen
	buffer_load_dwordx4 v[56:59], v221, s[40:43], s9 offen
	buffer_load_dwordx2 v[64:65], v218, s[36:39], s8 offen
	v_add_f32_e32 v210, v206, v207
	v_add_f32_e32 v211, v208, v209
	buffer_load_dwordx4 v[48:51], v219, s[40:43], s9 offen
	v_cndmask_b32_e64 v212, v210, v211, s[100:101]
	v_cndmask_b32_e64 v213, v211, v210, s[100:101]
	buffer_load_dwordx4 v[52:55], v220, s[40:43], s9 offen
	buffer_load_dwordx4 v[60:63], v217, s[36:39], s8 offen
	s_waitcnt vmcnt(44)
	v_pk_mul_f32 v[192:193], v[176:177], v[66:67]
	v_pk_mul_f32 v[194:195], v[180:181], v[66:67]
	v_pk_fma_f32 v[192:193], v[178:179], v[68:69], v[192:193]
	v_pk_fma_f32 v[194:195], v[182:183], v[68:69], v[194:195]
	v_add_f32_dpp v212, v213, v212 quad_perm:[1,0,3,2] row_mask:0xf bank_mask:0xf bound_ctrl:1
	v_add_f32_e32 v196, v192, v193
	v_add_f32_e32 v197, v194, v195
	v_add_f32_dpp v212, v212, v212 quad_perm:[2,3,0,1] row_mask:0xf bank_mask:0xf bound_ctrl:1
	v_add_f32_dpp v196, v196, v196 quad_perm:[1,0,3,2] row_mask:0xf bank_mask:0xf bound_ctrl:1
	v_add_f32_dpp v197, v197, v197 quad_perm:[1,0,3,2] row_mask:0xf bank_mask:0xf bound_ctrl:1
	v_add_f32_dpp v212, v212, v212 row_ror:4 row_mask:0xf bank_mask:0xf bound_ctrl:1
	v_add_f32_dpp v196, v196, v196 quad_perm:[2,3,0,1] row_mask:0xf bank_mask:0xf bound_ctrl:1
	v_add_f32_dpp v197, v197, v197 quad_perm:[2,3,0,1] row_mask:0xf bank_mask:0xf bound_ctrl:1
	v_add_f32_dpp v212, v212, v212 row_ror:8 row_mask:0xf bank_mask:0xf bound_ctrl:1
	v_add_f32_dpp v196, v196, v196 row_ror:4 row_mask:0xf bank_mask:0xf bound_ctrl:1
	v_add_f32_dpp v197, v197, v197 row_ror:4 row_mask:0xf bank_mask:0xf bound_ctrl:1
	v_pk_mul_f32 v[198:199], v[86:87], v[78:79] op_sel_hi:[0,1]
	v_pk_mul_f32 v[202:203], v[86:87], v[78:79] op_sel:[1,0]
	s_add_i32 s24, s24, s30
	v_pk_mul_f32 v[200:201], v[86:87], v[80:81] op_sel_hi:[0,1]
	v_pk_mul_f32 v[204:205], v[86:87], v[80:81] op_sel:[1,0]
	v_pk_fma_f32 v[198:199], v[176:177], v[70:71], v[198:199]
	v_pk_fma_f32 v[202:203], v[180:181], v[70:71], v[202:203]
	v_add_f32_dpp v196, v196, v196 row_ror:8 row_mask:0xf bank_mask:0xf bound_ctrl:1
	v_add_f32_dpp v197, v197, v197 row_ror:8 row_mask:0xf bank_mask:0xf bound_ctrl:1
	buffer_store_dword v212, v222, s[44:47], s24 offen
	v_pk_fma_f32 v[200:201], v[178:179], v[72:73], v[200:201]
	v_pk_fma_f32 v[204:205], v[182:183], v[72:73], v[204:205]
	v_pk_fma_f32 v[176:177], v[74:75], v[196:197], v[198:199] op_sel_hi:[1,0,1] neg_lo:[0,1,0] neg_hi:[0,1,0]
	v_pk_fma_f32 v[180:181], v[74:75], v[196:197], v[202:203] op_sel:[0,1,0] neg_lo:[0,1,0] neg_hi:[0,1,0]
	v_pk_fma_f32 v[178:179], v[76:77], v[196:197], v[200:201] op_sel_hi:[1,0,1] neg_lo:[0,1,0] neg_hi:[0,1,0]
	v_pk_fma_f32 v[182:183], v[76:77], v[196:197], v[204:205] op_sel:[0,1,0] neg_lo:[0,1,0] neg_hi:[0,1,0]
	v_pk_mul_f32 v[206:207], v[176:177], v[82:83]
	v_pk_mul_f32 v[208:209], v[180:181], v[82:83]
	s_add_i32 s8, s8, s25
	s_add_i32 s9, s9, s30
	v_pk_fma_f32 v[206:207], v[178:179], v[84:85], v[206:207]
	v_pk_fma_f32 v[208:209], v[182:183], v[84:85], v[208:209]
	buffer_load_dwordx4 v[66:69], v216, s[36:39], s8 offen
	buffer_load_dwordx4 v[78:81], v221, s[40:43], s9 offen
	buffer_load_dwordx2 v[86:87], v218, s[36:39], s8 offen
	v_add_f32_e32 v210, v206, v207
	v_add_f32_e32 v211, v208, v209
	buffer_load_dwordx4 v[70:73], v219, s[40:43], s9 offen
	v_cndmask_b32_e64 v212, v210, v211, s[100:101]
	v_cndmask_b32_e64 v213, v211, v210, s[100:101]
	buffer_load_dwordx4 v[74:77], v220, s[40:43], s9 offen
	buffer_load_dwordx4 v[82:85], v217, s[36:39], s8 offen
	s_waitcnt vmcnt(45)
	v_pk_mul_f32 v[192:193], v[176:177], v[88:89]
	v_pk_mul_f32 v[194:195], v[180:181], v[88:89]
	v_pk_fma_f32 v[192:193], v[178:179], v[90:91], v[192:193]
	v_pk_fma_f32 v[194:195], v[182:183], v[90:91], v[194:195]
	v_add_f32_dpp v212, v213, v212 quad_perm:[1,0,3,2] row_mask:0xf bank_mask:0xf bound_ctrl:1
	v_add_f32_e32 v196, v192, v193
	v_add_f32_e32 v197, v194, v195
	v_add_f32_dpp v212, v212, v212 quad_perm:[2,3,0,1] row_mask:0xf bank_mask:0xf bound_ctrl:1
	v_add_f32_dpp v196, v196, v196 quad_perm:[1,0,3,2] row_mask:0xf bank_mask:0xf bound_ctrl:1
	v_add_f32_dpp v197, v197, v197 quad_perm:[1,0,3,2] row_mask:0xf bank_mask:0xf bound_ctrl:1
	v_add_f32_dpp v212, v212, v212 row_ror:4 row_mask:0xf bank_mask:0xf bound_ctrl:1
	v_add_f32_dpp v196, v196, v196 quad_perm:[2,3,0,1] row_mask:0xf bank_mask:0xf bound_ctrl:1
	v_add_f32_dpp v197, v197, v197 quad_perm:[2,3,0,1] row_mask:0xf bank_mask:0xf bound_ctrl:1
	v_add_f32_dpp v212, v212, v212 row_ror:8 row_mask:0xf bank_mask:0xf bound_ctrl:1
	v_add_f32_dpp v196, v196, v196 row_ror:4 row_mask:0xf bank_mask:0xf bound_ctrl:1
	v_add_f32_dpp v197, v197, v197 row_ror:4 row_mask:0xf bank_mask:0xf bound_ctrl:1
	v_pk_mul_f32 v[198:199], v[108:109], v[100:101] op_sel_hi:[0,1]
	v_pk_mul_f32 v[202:203], v[108:109], v[100:101] op_sel:[1,0]
	s_add_i32 s24, s24, s30
	v_pk_mul_f32 v[200:201], v[108:109], v[102:103] op_sel_hi:[0,1]
	v_pk_mul_f32 v[204:205], v[108:109], v[102:103] op_sel:[1,0]
	v_pk_fma_f32 v[198:199], v[176:177], v[92:93], v[198:199]
	v_pk_fma_f32 v[202:203], v[180:181], v[92:93], v[202:203]
	v_add_f32_dpp v196, v196, v196 row_ror:8 row_mask:0xf bank_mask:0xf bound_ctrl:1
	v_add_f32_dpp v197, v197, v197 row_ror:8 row_mask:0xf bank_mask:0xf bound_ctrl:1
	buffer_store_dword v212, v222, s[44:47], s24 offen
	v_pk_fma_f32 v[200:201], v[178:179], v[94:95], v[200:201]
	v_pk_fma_f32 v[204:205], v[182:183], v[94:95], v[204:205]
	v_pk_fma_f32 v[176:177], v[96:97], v[196:197], v[198:199] op_sel_hi:[1,0,1] neg_lo:[0,1,0] neg_hi:[0,1,0]
	v_pk_fma_f32 v[180:181], v[96:97], v[196:197], v[202:203] op_sel:[0,1,0] neg_lo:[0,1,0] neg_hi:[0,1,0]
	v_pk_fma_f32 v[178:179], v[98:99], v[196:197], v[200:201] op_sel_hi:[1,0,1] neg_lo:[0,1,0] neg_hi:[0,1,0]
	v_pk_fma_f32 v[182:183], v[98:99], v[196:197], v[204:205] op_sel:[0,1,0] neg_lo:[0,1,0] neg_hi:[0,1,0]
	v_pk_mul_f32 v[206:207], v[176:177], v[104:105]
	v_pk_mul_f32 v[208:209], v[180:181], v[104:105]
	s_add_i32 s8, s8, s25
	s_add_i32 s9, s9, s30
	v_pk_fma_f32 v[206:207], v[178:179], v[106:107], v[206:207]
	v_pk_fma_f32 v[208:209], v[182:183], v[106:107], v[208:209]
	buffer_load_dwordx4 v[88:91], v216, s[36:39], s8 offen
	buffer_load_dwordx4 v[100:103], v221, s[40:43], s9 offen
	buffer_load_dwordx2 v[108:109], v218, s[36:39], s8 offen
	v_add_f32_e32 v210, v206, v207
	v_add_f32_e32 v211, v208, v209
	buffer_load_dwordx4 v[92:95], v219, s[40:43], s9 offen
	v_cndmask_b32_e64 v212, v210, v211, s[100:101]
	v_cndmask_b32_e64 v213, v211, v210, s[100:101]
	buffer_load_dwordx4 v[96:99], v220, s[40:43], s9 offen
	buffer_load_dwordx4 v[104:107], v217, s[36:39], s8 offen
	s_waitcnt vmcnt(46)
	v_pk_mul_f32 v[192:193], v[176:177], v[110:111]
	v_pk_mul_f32 v[194:195], v[180:181], v[110:111]
	v_pk_fma_f32 v[192:193], v[178:179], v[112:113], v[192:193]
	v_pk_fma_f32 v[194:195], v[182:183], v[112:113], v[194:195]
	v_add_f32_dpp v212, v213, v212 quad_perm:[1,0,3,2] row_mask:0xf bank_mask:0xf bound_ctrl:1
	v_add_f32_e32 v196, v192, v193
	v_add_f32_e32 v197, v194, v195
	v_add_f32_dpp v212, v212, v212 quad_perm:[2,3,0,1] row_mask:0xf bank_mask:0xf bound_ctrl:1
	v_add_f32_dpp v196, v196, v196 quad_perm:[1,0,3,2] row_mask:0xf bank_mask:0xf bound_ctrl:1
	v_add_f32_dpp v197, v197, v197 quad_perm:[1,0,3,2] row_mask:0xf bank_mask:0xf bound_ctrl:1
	v_add_f32_dpp v212, v212, v212 row_ror:4 row_mask:0xf bank_mask:0xf bound_ctrl:1
	v_add_f32_dpp v196, v196, v196 quad_perm:[2,3,0,1] row_mask:0xf bank_mask:0xf bound_ctrl:1
	v_add_f32_dpp v197, v197, v197 quad_perm:[2,3,0,1] row_mask:0xf bank_mask:0xf bound_ctrl:1
	v_add_f32_dpp v212, v212, v212 row_ror:8 row_mask:0xf bank_mask:0xf bound_ctrl:1
	v_add_f32_dpp v196, v196, v196 row_ror:4 row_mask:0xf bank_mask:0xf bound_ctrl:1
	v_add_f32_dpp v197, v197, v197 row_ror:4 row_mask:0xf bank_mask:0xf bound_ctrl:1
	v_pk_mul_f32 v[198:199], v[130:131], v[122:123] op_sel_hi:[0,1]
	v_pk_mul_f32 v[202:203], v[130:131], v[122:123] op_sel:[1,0]
	s_add_i32 s24, s24, s30
	v_pk_mul_f32 v[200:201], v[130:131], v[124:125] op_sel_hi:[0,1]
	v_pk_mul_f32 v[204:205], v[130:131], v[124:125] op_sel:[1,0]
	v_pk_fma_f32 v[198:199], v[176:177], v[114:115], v[198:199]
	v_pk_fma_f32 v[202:203], v[180:181], v[114:115], v[202:203]
	v_add_f32_dpp v196, v196, v196 row_ror:8 row_mask:0xf bank_mask:0xf bound_ctrl:1
	v_add_f32_dpp v197, v197, v197 row_ror:8 row_mask:0xf bank_mask:0xf bound_ctrl:1
	buffer_store_dword v212, v222, s[44:47], s24 offen
	v_pk_fma_f32 v[200:201], v[178:179], v[116:117], v[200:201]
	v_pk_fma_f32 v[204:205], v[182:183], v[116:117], v[204:205]
	v_pk_fma_f32 v[176:177], v[118:119], v[196:197], v[198:199] op_sel_hi:[1,0,1] neg_lo:[0,1,0] neg_hi:[0,1,0]
	v_pk_fma_f32 v[180:181], v[118:119], v[196:197], v[202:203] op_sel:[0,1,0] neg_lo:[0,1,0] neg_hi:[0,1,0]
	v_pk_fma_f32 v[178:179], v[120:121], v[196:197], v[200:201] op_sel_hi:[1,0,1] neg_lo:[0,1,0] neg_hi:[0,1,0]
	v_pk_fma_f32 v[182:183], v[120:121], v[196:197], v[204:205] op_sel:[0,1,0] neg_lo:[0,1,0] neg_hi:[0,1,0]
	v_pk_mul_f32 v[206:207], v[176:177], v[126:127]
	v_pk_mul_f32 v[208:209], v[180:181], v[126:127]
	s_add_i32 s8, s8, s25
	s_add_i32 s9, s9, s30
	v_pk_fma_f32 v[206:207], v[178:179], v[128:129], v[206:207]
	v_pk_fma_f32 v[208:209], v[182:183], v[128:129], v[208:209]
	buffer_load_dwordx4 v[110:113], v216, s[36:39], s8 offen
	buffer_load_dwordx4 v[122:125], v221, s[40:43], s9 offen
	buffer_load_dwordx2 v[130:131], v218, s[36:39], s8 offen
	v_add_f32_e32 v210, v206, v207
	v_add_f32_e32 v211, v208, v209
	buffer_load_dwordx4 v[114:117], v219, s[40:43], s9 offen
	v_cndmask_b32_e64 v212, v210, v211, s[100:101]
	v_cndmask_b32_e64 v213, v211, v210, s[100:101]
	buffer_load_dwordx4 v[118:121], v220, s[40:43], s9 offen
	buffer_load_dwordx4 v[126:129], v217, s[36:39], s8 offen
	s_waitcnt vmcnt(47)
	v_pk_mul_f32 v[192:193], v[176:177], v[132:133]
	v_pk_mul_f32 v[194:195], v[180:181], v[132:133]
	v_pk_fma_f32 v[192:193], v[178:179], v[134:135], v[192:193]
	v_pk_fma_f32 v[194:195], v[182:183], v[134:135], v[194:195]
	v_add_f32_dpp v212, v213, v212 quad_perm:[1,0,3,2] row_mask:0xf bank_mask:0xf bound_ctrl:1
	v_add_f32_e32 v196, v192, v193
	v_add_f32_e32 v197, v194, v195
	v_add_f32_dpp v212, v212, v212 quad_perm:[2,3,0,1] row_mask:0xf bank_mask:0xf bound_ctrl:1
	v_add_f32_dpp v196, v196, v196 quad_perm:[1,0,3,2] row_mask:0xf bank_mask:0xf bound_ctrl:1
	v_add_f32_dpp v197, v197, v197 quad_perm:[1,0,3,2] row_mask:0xf bank_mask:0xf bound_ctrl:1
	v_add_f32_dpp v212, v212, v212 row_ror:4 row_mask:0xf bank_mask:0xf bound_ctrl:1
	v_add_f32_dpp v196, v196, v196 quad_perm:[2,3,0,1] row_mask:0xf bank_mask:0xf bound_ctrl:1
	v_add_f32_dpp v197, v197, v197 quad_perm:[2,3,0,1] row_mask:0xf bank_mask:0xf bound_ctrl:1
	v_add_f32_dpp v212, v212, v212 row_ror:8 row_mask:0xf bank_mask:0xf bound_ctrl:1
	v_add_f32_dpp v196, v196, v196 row_ror:4 row_mask:0xf bank_mask:0xf bound_ctrl:1
	v_add_f32_dpp v197, v197, v197 row_ror:4 row_mask:0xf bank_mask:0xf bound_ctrl:1
	v_pk_mul_f32 v[198:199], v[152:153], v[144:145] op_sel_hi:[0,1]
	v_pk_mul_f32 v[202:203], v[152:153], v[144:145] op_sel:[1,0]
	s_add_i32 s24, s24, s30
	v_pk_mul_f32 v[200:201], v[152:153], v[146:147] op_sel_hi:[0,1]
	v_pk_mul_f32 v[204:205], v[152:153], v[146:147] op_sel:[1,0]
	v_pk_fma_f32 v[198:199], v[176:177], v[136:137], v[198:199]
	v_pk_fma_f32 v[202:203], v[180:181], v[136:137], v[202:203]
	v_add_f32_dpp v196, v196, v196 row_ror:8 row_mask:0xf bank_mask:0xf bound_ctrl:1
	v_add_f32_dpp v197, v197, v197 row_ror:8 row_mask:0xf bank_mask:0xf bound_ctrl:1
	buffer_store_dword v212, v222, s[44:47], s24 offen
	v_pk_fma_f32 v[200:201], v[178:179], v[138:139], v[200:201]
	v_pk_fma_f32 v[204:205], v[182:183], v[138:139], v[204:205]
	v_pk_fma_f32 v[176:177], v[140:141], v[196:197], v[198:199] op_sel_hi:[1,0,1] neg_lo:[0,1,0] neg_hi:[0,1,0]
	v_pk_fma_f32 v[180:181], v[140:141], v[196:197], v[202:203] op_sel:[0,1,0] neg_lo:[0,1,0] neg_hi:[0,1,0]
	v_pk_fma_f32 v[178:179], v[142:143], v[196:197], v[200:201] op_sel_hi:[1,0,1] neg_lo:[0,1,0] neg_hi:[0,1,0]
	v_pk_fma_f32 v[182:183], v[142:143], v[196:197], v[204:205] op_sel:[0,1,0] neg_lo:[0,1,0] neg_hi:[0,1,0]
	v_pk_mul_f32 v[206:207], v[176:177], v[148:149]
	v_pk_mul_f32 v[208:209], v[180:181], v[148:149]
	s_add_i32 s8, s8, s25
	s_add_i32 s9, s9, s30
	v_pk_fma_f32 v[206:207], v[178:179], v[150:151], v[206:207]
	v_pk_fma_f32 v[208:209], v[182:183], v[150:151], v[208:209]
	buffer_load_dwordx4 v[132:135], v216, s[36:39], s8 offen
	buffer_load_dwordx4 v[144:147], v221, s[40:43], s9 offen
	buffer_load_dwordx2 v[152:153], v218, s[36:39], s8 offen
	v_add_f32_e32 v210, v206, v207
	v_add_f32_e32 v211, v208, v209
	buffer_load_dwordx4 v[136:139], v219, s[40:43], s9 offen
	v_cndmask_b32_e64 v212, v210, v211, s[100:101]
	v_cndmask_b32_e64 v213, v211, v210, s[100:101]
	buffer_load_dwordx4 v[140:143], v220, s[40:43], s9 offen
	buffer_load_dwordx4 v[148:151], v217, s[36:39], s8 offen
	s_waitcnt vmcnt(48)
	v_pk_mul_f32 v[192:193], v[176:177], v[154:155]
	v_pk_mul_f32 v[194:195], v[180:181], v[154:155]
	v_pk_fma_f32 v[192:193], v[178:179], v[156:157], v[192:193]
	v_pk_fma_f32 v[194:195], v[182:183], v[156:157], v[194:195]
	v_add_f32_dpp v212, v213, v212 quad_perm:[1,0,3,2] row_mask:0xf bank_mask:0xf bound_ctrl:1
	v_add_f32_e32 v196, v192, v193
	v_add_f32_e32 v197, v194, v195
	v_add_f32_dpp v212, v212, v212 quad_perm:[2,3,0,1] row_mask:0xf bank_mask:0xf bound_ctrl:1
	v_add_f32_dpp v196, v196, v196 quad_perm:[1,0,3,2] row_mask:0xf bank_mask:0xf bound_ctrl:1
	v_add_f32_dpp v197, v197, v197 quad_perm:[1,0,3,2] row_mask:0xf bank_mask:0xf bound_ctrl:1
	v_add_f32_dpp v212, v212, v212 row_ror:4 row_mask:0xf bank_mask:0xf bound_ctrl:1
	v_add_f32_dpp v196, v196, v196 quad_perm:[2,3,0,1] row_mask:0xf bank_mask:0xf bound_ctrl:1
	v_add_f32_dpp v197, v197, v197 quad_perm:[2,3,0,1] row_mask:0xf bank_mask:0xf bound_ctrl:1
	v_add_f32_dpp v212, v212, v212 row_ror:8 row_mask:0xf bank_mask:0xf bound_ctrl:1
	v_add_f32_dpp v196, v196, v196 row_ror:4 row_mask:0xf bank_mask:0xf bound_ctrl:1
	v_add_f32_dpp v197, v197, v197 row_ror:4 row_mask:0xf bank_mask:0xf bound_ctrl:1
	v_pk_mul_f32 v[198:199], v[174:175], v[166:167] op_sel_hi:[0,1]
	v_pk_mul_f32 v[202:203], v[174:175], v[166:167] op_sel:[1,0]
	s_add_i32 s24, s24, s30
	v_pk_mul_f32 v[200:201], v[174:175], v[168:169] op_sel_hi:[0,1]
	v_pk_mul_f32 v[204:205], v[174:175], v[168:169] op_sel:[1,0]
	v_pk_fma_f32 v[198:199], v[176:177], v[158:159], v[198:199]
	v_pk_fma_f32 v[202:203], v[180:181], v[158:159], v[202:203]
	v_add_f32_dpp v196, v196, v196 row_ror:8 row_mask:0xf bank_mask:0xf bound_ctrl:1
	v_add_f32_dpp v197, v197, v197 row_ror:8 row_mask:0xf bank_mask:0xf bound_ctrl:1
	buffer_store_dword v212, v222, s[44:47], s24 offen
	v_pk_fma_f32 v[200:201], v[178:179], v[160:161], v[200:201]
	v_pk_fma_f32 v[204:205], v[182:183], v[160:161], v[204:205]
	v_pk_fma_f32 v[176:177], v[162:163], v[196:197], v[198:199] op_sel_hi:[1,0,1] neg_lo:[0,1,0] neg_hi:[0,1,0]
	v_pk_fma_f32 v[180:181], v[162:163], v[196:197], v[202:203] op_sel:[0,1,0] neg_lo:[0,1,0] neg_hi:[0,1,0]
	v_pk_fma_f32 v[178:179], v[164:165], v[196:197], v[200:201] op_sel_hi:[1,0,1] neg_lo:[0,1,0] neg_hi:[0,1,0]
	v_pk_fma_f32 v[182:183], v[164:165], v[196:197], v[204:205] op_sel:[0,1,0] neg_lo:[0,1,0] neg_hi:[0,1,0]
	v_pk_mul_f32 v[206:207], v[176:177], v[170:171]
	v_pk_mul_f32 v[208:209], v[180:181], v[170:171]
	s_add_i32 s8, s8, s25
	s_add_i32 s9, s9, s30
	v_pk_fma_f32 v[206:207], v[178:179], v[172:173], v[206:207]
	v_pk_fma_f32 v[208:209], v[182:183], v[172:173], v[208:209]
	buffer_load_dwordx4 v[154:157], v216, s[36:39], s8 offen
	buffer_load_dwordx4 v[166:169], v221, s[40:43], s9 offen
	buffer_load_dwordx2 v[174:175], v218, s[36:39], s8 offen
	buffer_load_dwordx4 v[158:161], v219, s[40:43], s9 offen
	buffer_load_dwordx4 v[162:165], v220, s[40:43], s9 offen
	buffer_load_dwordx4 v[170:173], v217, s[36:39], s8 offen
	s_waitcnt vmcnt(49)
	v_pk_mul_f32 v[192:193], v[176:177], v[0:1]
	v_pk_mul_f32 v[194:195], v[180:181], v[0:1]
	v_pk_fma_f32 v[192:193], v[178:179], v[2:3], v[192:193]
	v_pk_fma_f32 v[194:195], v[182:183], v[2:3], v[194:195]
	v_add_f32_e32 v196, v192, v193
	v_add_f32_e32 v197, v194, v195
	v_add_f32_e32 v210, v206, v207
	v_add_f32_e32 v211, v208, v209
	v_add_f32_dpp v196, v196, v196 quad_perm:[1,0,3,2] row_mask:0xf bank_mask:0xf bound_ctrl:1
	v_add_f32_dpp v197, v197, v197 quad_perm:[1,0,3,2] row_mask:0xf bank_mask:0xf bound_ctrl:1
	v_cndmask_b32_e64 v212, v210, v211, s[100:101]
	v_cndmask_b32_e64 v213, v211, v210, s[100:101]
	v_add_f32_dpp v196, v196, v196 quad_perm:[2,3,0,1] row_mask:0xf bank_mask:0xf bound_ctrl:1
	v_add_f32_dpp v197, v197, v197 quad_perm:[2,3,0,1] row_mask:0xf bank_mask:0xf bound_ctrl:1
	v_add_f32_dpp v212, v213, v212 quad_perm:[1,0,3,2] row_mask:0xf bank_mask:0xf bound_ctrl:1
	v_add_f32_dpp v196, v196, v196 row_ror:4 row_mask:0xf bank_mask:0xf bound_ctrl:1
	v_add_f32_dpp v197, v197, v197 row_ror:4 row_mask:0xf bank_mask:0xf bound_ctrl:1
	v_pk_mul_f32 v[198:199], v[20:21], v[12:13] op_sel_hi:[0,1]
	v_pk_mul_f32 v[202:203], v[20:21], v[12:13] op_sel:[1,0]
	v_add_f32_dpp v212, v212, v212 quad_perm:[2,3,0,1] row_mask:0xf bank_mask:0xf bound_ctrl:1
	v_pk_mul_f32 v[200:201], v[20:21], v[14:15] op_sel_hi:[0,1]
	v_pk_mul_f32 v[204:205], v[20:21], v[14:15] op_sel:[1,0]
	v_pk_fma_f32 v[198:199], v[176:177], v[4:5], v[198:199]
	v_pk_fma_f32 v[202:203], v[180:181], v[4:5], v[202:203]
	v_add_f32_dpp v196, v196, v196 row_ror:8 row_mask:0xf bank_mask:0xf bound_ctrl:1
	v_add_f32_dpp v197, v197, v197 row_ror:8 row_mask:0xf bank_mask:0xf bound_ctrl:1
	v_add_f32_dpp v212, v212, v212 row_ror:4 row_mask:0xf bank_mask:0xf bound_ctrl:1
	v_pk_fma_f32 v[200:201], v[178:179], v[6:7], v[200:201]
	v_pk_fma_f32 v[204:205], v[182:183], v[6:7], v[204:205]
	v_pk_fma_f32 v[176:177], v[8:9], v[196:197], v[198:199] op_sel_hi:[1,0,1] neg_lo:[0,1,0] neg_hi:[0,1,0]
	v_pk_fma_f32 v[180:181], v[8:9], v[196:197], v[202:203] op_sel:[0,1,0] neg_lo:[0,1,0] neg_hi:[0,1,0]
	v_pk_fma_f32 v[178:179], v[10:11], v[196:197], v[200:201] op_sel_hi:[1,0,1] neg_lo:[0,1,0] neg_hi:[0,1,0]
	v_pk_fma_f32 v[182:183], v[10:11], v[196:197], v[204:205] op_sel:[0,1,0] neg_lo:[0,1,0] neg_hi:[0,1,0]
	v_pk_mul_f32 v[206:207], v[176:177], v[16:17]
	v_pk_mul_f32 v[208:209], v[180:181], v[16:17]
	v_add_f32_dpp v212, v212, v212 row_ror:8 row_mask:0xf bank_mask:0xf bound_ctrl:1
	s_add_i32 s24, s24, s30
	v_pk_fma_f32 v[206:207], v[178:179], v[18:19], v[206:207]
	v_pk_fma_f32 v[208:209], v[182:183], v[18:19], v[208:209]
	v_add_f32_e32 v210, v206, v207
	v_add_f32_e32 v211, v208, v209
	buffer_store_dword v212, v222, s[44:47], s24 offen
	v_cndmask_b32_e64 v212, v210, v211, s[100:101]
	v_cndmask_b32_e64 v213, v211, v210, s[100:101]
	s_add_i32 s8, s8, s25
	s_add_i32 s9, s9, s30
	v_add_f32_dpp v212, v213, v212 quad_perm:[1,0,3,2] row_mask:0xf bank_mask:0xf bound_ctrl:1
	buffer_load_dwordx4 v[0:3], v216, s[36:39], s8 offen
	s_add_i32 s24, s24, s30
	v_add_f32_dpp v212, v212, v212 quad_perm:[2,3,0,1] row_mask:0xf bank_mask:0xf bound_ctrl:1
	buffer_load_dwordx4 v[12:15], v221, s[40:43], s9 offen
	buffer_load_dwordx2 v[20:21], v218, s[36:39], s8 offen
	v_add_f32_dpp v212, v212, v212 row_ror:4 row_mask:0xf bank_mask:0xf bound_ctrl:1
	buffer_load_dwordx4 v[4:7], v219, s[40:43], s9 offen
	buffer_load_dwordx4 v[8:11], v220, s[40:43], s9 offen
	v_add_f32_dpp v212, v212, v212 row_ror:8 row_mask:0xf bank_mask:0xf bound_ctrl:1
	buffer_load_dwordx4 v[16:19], v217, s[36:39], s8 offen
	s_add_i32 s8, s8, s25
	s_add_i32 s9, s9, s30
	s_add_i32 s98, s98, -1
	s_cmp_lg_u32 s98, 0
	s_cbranch_scc1 .Lss_loop
	s_waitcnt vmcnt(49)
	v_pk_mul_f32 v[192:193], v[176:177], v[22:23]
	v_pk_mul_f32 v[194:195], v[180:181], v[22:23]
	v_pk_fma_f32 v[192:193], v[178:179], v[24:25], v[192:193]
	v_pk_fma_f32 v[194:195], v[182:183], v[24:25], v[194:195]
	v_add_f32_e32 v196, v192, v193
	v_add_f32_e32 v197, v194, v195
	v_pk_mul_f32 v[198:199], v[42:43], v[34:35] op_sel_hi:[0,1]
	v_add_f32_dpp v196, v196, v196 quad_perm:[1,0,3,2] row_mask:0xf bank_mask:0xf bound_ctrl:1
	v_add_f32_dpp v197, v197, v197 quad_perm:[1,0,3,2] row_mask:0xf bank_mask:0xf bound_ctrl:1
	v_pk_mul_f32 v[202:203], v[42:43], v[34:35] op_sel:[1,0]
	v_add_f32_dpp v196, v196, v196 quad_perm:[2,3,0,1] row_mask:0xf bank_mask:0xf bound_ctrl:1
	v_add_f32_dpp v197, v197, v197 quad_perm:[2,3,0,1] row_mask:0xf bank_mask:0xf bound_ctrl:1
	v_pk_mul_f32 v[200:201], v[42:43], v[36:37] op_sel_hi:[0,1]
	v_add_f32_dpp v196, v196, v196 row_ror:4 row_mask:0xf bank_mask:0xf bound_ctrl:1
	v_add_f32_dpp v197, v197, v197 row_ror:4 row_mask:0xf bank_mask:0xf bound_ctrl:1
	v_pk_mul_f32 v[204:205], v[42:43], v[36:37] op_sel:[1,0]
	v_pk_fma_f32 v[198:199], v[176:177], v[26:27], v[198:199]
	v_pk_fma_f32 v[202:203], v[180:181], v[26:27], v[202:203]
	v_add_f32_dpp v196, v196, v196 row_ror:8 row_mask:0xf bank_mask:0xf bound_ctrl:1
	v_add_f32_dpp v197, v197, v197 row_ror:8 row_mask:0xf bank_mask:0xf bound_ctrl:1
	buffer_store_dword v212, v222, s[44:47], s24 offen
	v_pk_fma_f32 v[200:201], v[178:179], v[28:29], v[200:201]
	v_pk_fma_f32 v[204:205], v[182:183], v[28:29], v[204:205]
	v_pk_fma_f32 v[176:177], v[30:31], v[196:197], v[198:199] op_sel_hi:[1,0,1] neg_lo:[0,1,0] neg_hi:[0,1,0]
	v_pk_fma_f32 v[180:181], v[30:31], v[196:197], v[202:203] op_sel:[0,1,0] neg_lo:[0,1,0] neg_hi:[0,1,0]
	v_pk_fma_f32 v[178:179], v[32:33], v[196:197], v[200:201] op_sel_hi:[1,0,1] neg_lo:[0,1,0] neg_hi:[0,1,0]
	v_pk_fma_f32 v[182:183], v[32:33], v[196:197], v[204:205] op_sel:[0,1,0] neg_lo:[0,1,0] neg_hi:[0,1,0]
	v_pk_mul_f32 v[206:207], v[176:177], v[38:39]
	v_pk_mul_f32 v[208:209], v[180:181], v[38:39]
	v_pk_fma_f32 v[206:207], v[178:179], v[40:41], v[206:207]
	v_pk_fma_f32 v[208:209], v[182:183], v[40:41], v[208:209]
	buffer_load_dwordx4 v[22:25], v216, s[36:39], s8 offen
	buffer_load_dwordx4 v[34:37], v221, s[40:43], s9 offen
	buffer_load_dwordx2 v[42:43], v218, s[36:39], s8 offen
	v_add_f32_e32 v210, v206, v207
	v_add_f32_e32 v211, v208, v209
	buffer_load_dwordx4 v[26:29], v219, s[40:43], s9 offen
	v_cndmask_b32_e64 v212, v210, v211, s[100:101]
	v_cndmask_b32_e64 v213, v211, v210, s[100:101]
	buffer_load_dwordx4 v[30:33], v220, s[40:43], s9 offen
	buffer_load_dwordx4 v[38:41], v217, s[36:39], s8 offen
	s_waitcnt vmcnt(49)
	v_pk_mul_f32 v[192:193], v[176:177], v[44:45]
	v_pk_mul_f32 v[194:195], v[180:181], v[44:45]
	v_pk_fma_f32 v[192:193], v[178:179], v[46:47], v[192:193]
	v_pk_fma_f32 v[194:195], v[182:183], v[46:47], v[194:195]
	v_add_f32_dpp v212, v213, v212 quad_perm:[1,0,3,2] row_mask:0xf bank_mask:0xf bound_ctrl:1
	v_add_f32_e32 v196, v192, v193
	v_add_f32_e32 v197, v194, v195
	v_add_f32_dpp v212, v212, v212 quad_perm:[2,3,0,1] row_mask:0xf bank_mask:0xf bound_ctrl:1
	v_add_f32_dpp v196, v196, v196 quad_perm:[1,0,3,2] row_mask:0xf bank_mask:0xf bound_ctrl:1
	v_add_f32_dpp v197, v197, v197 quad_perm:[1,0,3,2] row_mask:0xf bank_mask:0xf bound_ctrl:1
	v_add_f32_dpp v212, v212, v212 row_ror:4 row_mask:0xf bank_mask:0xf bound_ctrl:1
	v_add_f32_dpp v196, v196, v196 quad_perm:[2,3,0,1] row_mask:0xf bank_mask:0xf bound_ctrl:1
	v_add_f32_dpp v197, v197, v197 quad_perm:[2,3,0,1] row_mask:0xf bank_mask:0xf bound_ctrl:1
	v_add_f32_dpp v212, v212, v212 row_ror:8 row_mask:0xf bank_mask:0xf bound_ctrl:1
	v_add_f32_dpp v196, v196, v196 row_ror:4 row_mask:0xf bank_mask:0xf bound_ctrl:1
	v_add_f32_dpp v197, v197, v197 row_ror:4 row_mask:0xf bank_mask:0xf bound_ctrl:1
	v_pk_mul_f32 v[198:199], v[64:65], v[56:57] op_sel_hi:[0,1]
	v_pk_mul_f32 v[202:203], v[64:65], v[56:57] op_sel:[1,0]
	s_add_i32 s24, s24, s30
	v_pk_mul_f32 v[200:201], v[64:65], v[58:59] op_sel_hi:[0,1]
	v_pk_mul_f32 v[204:205], v[64:65], v[58:59] op_sel:[1,0]
	v_pk_fma_f32 v[198:199], v[176:177], v[48:49], v[198:199]
	v_pk_fma_f32 v[202:203], v[180:181], v[48:49], v[202:203]
	v_add_f32_dpp v196, v196, v196 row_ror:8 row_mask:0xf bank_mask:0xf bound_ctrl:1
	v_add_f32_dpp v197, v197, v197 row_ror:8 row_mask:0xf bank_mask:0xf bound_ctrl:1
	buffer_store_dword v212, v222, s[44:47], s24 offen
	v_pk_fma_f32 v[200:201], v[178:179], v[50:51], v[200:201]
	v_pk_fma_f32 v[204:205], v[182:183], v[50:51], v[204:205]
	v_pk_fma_f32 v[176:177], v[52:53], v[196:197], v[198:199] op_sel_hi:[1,0,1] neg_lo:[0,1,0] neg_hi:[0,1,0]
	v_pk_fma_f32 v[180:181], v[52:53], v[196:197], v[202:203] op_sel:[0,1,0] neg_lo:[0,1,0] neg_hi:[0,1,0]
	v_pk_fma_f32 v[178:179], v[54:55], v[196:197], v[200:201] op_sel_hi:[1,0,1] neg_lo:[0,1,0] neg_hi:[0,1,0]
	v_pk_fma_f32 v[182:183], v[54:55], v[196:197], v[204:205] op_sel:[0,1,0] neg_lo:[0,1,0] neg_hi:[0,1,0]
	v_pk_mul_f32 v[206:207], v[176:177], v[60:61]
	v_pk_mul_f32 v[208:209], v[180:181], v[60:61]
	s_add_i32 s8, s8, s25
	s_add_i32 s9, s9, s30
	v_pk_fma_f32 v[206:207], v[178:179], v[62:63], v[206:207]
	v_pk_fma_f32 v[208:209], v[182:183], v[62:63], v[208:209]
	buffer_load_dwordx4 v[44:47], v216, s[36:39], s8 offen
	buffer_load_dwordx4 v[56:59], v221, s[40:43], s9 offen
	buffer_load_dwordx2 v[64:65], v218, s[36:39], s8 offen
	v_add_f32_e32 v210, v206, v207
	v_add_f32_e32 v211, v208, v209
	buffer_load_dwordx4 v[48:51], v219, s[40:43], s9 offen
	v_cndmask_b32_e64 v212, v210, v211, s[100:101]
	v_cndmask_b32_e64 v213, v211, v210, s[100:101]
	buffer_load_dwordx4 v[52:55], v220, s[40:43], s9 offen
	buffer_load_dwordx4 v[60:63], v217, s[36:39], s8 offen
	s_waitcnt vmcnt(49)
	v_pk_mul_f32 v[192:193], v[176:177], v[66:67]
	v_pk_mul_f32 v[194:195], v[180:181], v[66:67]
	v_pk_fma_f32 v[192:193], v[178:179], v[68:69], v[192:193]
	v_pk_fma_f32 v[194:195], v[182:183], v[68:69], v[194:195]
	v_add_f32_dpp v212, v213, v212 quad_perm:[1,0,3,2] row_mask:0xf bank_mask:0xf bound_ctrl:1
	v_add_f32_e32 v196, v192, v193
	v_add_f32_e32 v197, v194, v195
	v_add_f32_dpp v212, v212, v212 quad_perm:[2,3,0,1] row_mask:0xf bank_mask:0xf bound_ctrl:1
	v_add_f32_dpp v196, v196, v196 quad_perm:[1,0,3,2] row_mask:0xf bank_mask:0xf bound_ctrl:1
	v_add_f32_dpp v197, v197, v197 quad_perm:[1,0,3,2] row_mask:0xf bank_mask:0xf bound_ctrl:1
	v_add_f32_dpp v212, v212, v212 row_ror:4 row_mask:0xf bank_mask:0xf bound_ctrl:1
	v_add_f32_dpp v196, v196, v196 quad_perm:[2,3,0,1] row_mask:0xf bank_mask:0xf bound_ctrl:1
	v_add_f32_dpp v197, v197, v197 quad_perm:[2,3,0,1] row_mask:0xf bank_mask:0xf bound_ctrl:1
	v_add_f32_dpp v212, v212, v212 row_ror:8 row_mask:0xf bank_mask:0xf bound_ctrl:1
	v_add_f32_dpp v196, v196, v196 row_ror:4 row_mask:0xf bank_mask:0xf bound_ctrl:1
	v_add_f32_dpp v197, v197, v197 row_ror:4 row_mask:0xf bank_mask:0xf bound_ctrl:1
	v_pk_mul_f32 v[198:199], v[86:87], v[78:79] op_sel_hi:[0,1]
	v_pk_mul_f32 v[202:203], v[86:87], v[78:79] op_sel:[1,0]
	s_add_i32 s24, s24, s30
	v_pk_mul_f32 v[200:201], v[86:87], v[80:81] op_sel_hi:[0,1]
	v_pk_mul_f32 v[204:205], v[86:87], v[80:81] op_sel:[1,0]
	v_pk_fma_f32 v[198:199], v[176:177], v[70:71], v[198:199]
	v_pk_fma_f32 v[202:203], v[180:181], v[70:71], v[202:203]
	v_add_f32_dpp v196, v196, v196 row_ror:8 row_mask:0xf bank_mask:0xf bound_ctrl:1
	v_add_f32_dpp v197, v197, v197 row_ror:8 row_mask:0xf bank_mask:0xf bound_ctrl:1
	buffer_store_dword v212, v222, s[44:47], s24 offen
	v_pk_fma_f32 v[200:201], v[178:179], v[72:73], v[200:201]
	v_pk_fma_f32 v[204:205], v[182:183], v[72:73], v[204:205]
	v_pk_fma_f32 v[176:177], v[74:75], v[196:197], v[198:199] op_sel_hi:[1,0,1] neg_lo:[0,1,0] neg_hi:[0,1,0]
	v_pk_fma_f32 v[180:181], v[74:75], v[196:197], v[202:203] op_sel:[0,1,0] neg_lo:[0,1,0] neg_hi:[0,1,0]
	v_pk_fma_f32 v[178:179], v[76:77], v[196:197], v[200:201] op_sel_hi:[1,0,1] neg_lo:[0,1,0] neg_hi:[0,1,0]
	v_pk_fma_f32 v[182:183], v[76:77], v[196:197], v[204:205] op_sel:[0,1,0] neg_lo:[0,1,0] neg_hi:[0,1,0]
	v_pk_mul_f32 v[206:207], v[176:177], v[82:83]
	v_pk_mul_f32 v[208:209], v[180:181], v[82:83]
	s_add_i32 s8, s8, s25
	s_add_i32 s9, s9, s30
	v_pk_fma_f32 v[206:207], v[178:179], v[84:85], v[206:207]
	v_pk_fma_f32 v[208:209], v[182:183], v[84:85], v[208:209]
	buffer_load_dwordx4 v[66:69], v216, s[36:39], s8 offen
	buffer_load_dwordx4 v[78:81], v221, s[40:43], s9 offen
	buffer_load_dwordx2 v[86:87], v218, s[36:39], s8 offen
	v_add_f32_e32 v210, v206, v207
	v_add_f32_e32 v211, v208, v209
	buffer_load_dwordx4 v[70:73], v219, s[40:43], s9 offen
	v_cndmask_b32_e64 v212, v210, v211, s[100:101]
	v_cndmask_b32_e64 v213, v211, v210, s[100:101]
	buffer_load_dwordx4 v[74:77], v220, s[40:43], s9 offen
	buffer_load_dwordx4 v[82:85], v217, s[36:39], s8 offen
	s_waitcnt vmcnt(49)
	v_pk_mul_f32 v[192:193], v[176:177], v[88:89]
	v_pk_mul_f32 v[194:195], v[180:181], v[88:89]
	v_pk_fma_f32 v[192:193], v[178:179], v[90:91], v[192:193]
	v_pk_fma_f32 v[194:195], v[182:183], v[90:91], v[194:195]
	v_add_f32_dpp v212, v213, v212 quad_perm:[1,0,3,2] row_mask:0xf bank_mask:0xf bound_ctrl:1
	v_add_f32_e32 v196, v192, v193
	v_add_f32_e32 v197, v194, v195
	v_add_f32_dpp v212, v212, v212 quad_perm:[2,3,0,1] row_mask:0xf bank_mask:0xf bound_ctrl:1
	v_add_f32_dpp v196, v196, v196 quad_perm:[1,0,3,2] row_mask:0xf bank_mask:0xf bound_ctrl:1
	v_add_f32_dpp v197, v197, v197 quad_perm:[1,0,3,2] row_mask:0xf bank_mask:0xf bound_ctrl:1
	v_add_f32_dpp v212, v212, v212 row_ror:4 row_mask:0xf bank_mask:0xf bound_ctrl:1
	v_add_f32_dpp v196, v196, v196 quad_perm:[2,3,0,1] row_mask:0xf bank_mask:0xf bound_ctrl:1
	v_add_f32_dpp v197, v197, v197 quad_perm:[2,3,0,1] row_mask:0xf bank_mask:0xf bound_ctrl:1
	v_add_f32_dpp v212, v212, v212 row_ror:8 row_mask:0xf bank_mask:0xf bound_ctrl:1
	v_add_f32_dpp v196, v196, v196 row_ror:4 row_mask:0xf bank_mask:0xf bound_ctrl:1
	v_add_f32_dpp v197, v197, v197 row_ror:4 row_mask:0xf bank_mask:0xf bound_ctrl:1
	v_pk_mul_f32 v[198:199], v[108:109], v[100:101] op_sel_hi:[0,1]
	v_pk_mul_f32 v[202:203], v[108:109], v[100:101] op_sel:[1,0]
	s_add_i32 s24, s24, s30
	v_pk_mul_f32 v[200:201], v[108:109], v[102:103] op_sel_hi:[0,1]
	v_pk_mul_f32 v[204:205], v[108:109], v[102:103] op_sel:[1,0]
	v_pk_fma_f32 v[198:199], v[176:177], v[92:93], v[198:199]
	v_pk_fma_f32 v[202:203], v[180:181], v[92:93], v[202:203]
	v_add_f32_dpp v196, v196, v196 row_ror:8 row_mask:0xf bank_mask:0xf bound_ctrl:1
	v_add_f32_dpp v197, v197, v197 row_ror:8 row_mask:0xf bank_mask:0xf bound_ctrl:1
	buffer_store_dword v212, v222, s[44:47], s24 offen
	v_pk_fma_f32 v[200:201], v[178:179], v[94:95], v[200:201]
	v_pk_fma_f32 v[204:205], v[182:183], v[94:95], v[204:205]
	v_pk_fma_f32 v[176:177], v[96:97], v[196:197], v[198:199] op_sel_hi:[1,0,1] neg_lo:[0,1,0] neg_hi:[0,1,0]
	v_pk_fma_f32 v[180:181], v[96:97], v[196:197], v[202:203] op_sel:[0,1,0] neg_lo:[0,1,0] neg_hi:[0,1,0]
	v_pk_fma_f32 v[178:179], v[98:99], v[196:197], v[200:201] op_sel_hi:[1,0,1] neg_lo:[0,1,0] neg_hi:[0,1,0]
	v_pk_fma_f32 v[182:183], v[98:99], v[196:197], v[204:205] op_sel:[0,1,0] neg_lo:[0,1,0] neg_hi:[0,1,0]
	v_pk_mul_f32 v[206:207], v[176:177], v[104:105]
	v_pk_mul_f32 v[208:209], v[180:181], v[104:105]
	s_add_i32 s8, s8, s25
	s_add_i32 s9, s9, s30
	v_pk_fma_f32 v[206:207], v[178:179], v[106:107], v[206:207]
	v_pk_fma_f32 v[208:209], v[182:183], v[106:107], v[208:209]
	buffer_load_dwordx4 v[88:91], v216, s[36:39], s8 offen
	buffer_load_dwordx4 v[100:103], v221, s[40:43], s9 offen
	buffer_load_dwordx2 v[108:109], v218, s[36:39], s8 offen
	v_add_f32_e32 v210, v206, v207
	v_add_f32_e32 v211, v208, v209
	buffer_load_dwordx4 v[92:95], v219, s[40:43], s9 offen
	v_cndmask_b32_e64 v212, v210, v211, s[100:101]
	v_cndmask_b32_e64 v213, v211, v210, s[100:101]
	buffer_load_dwordx4 v[96:99], v220, s[40:43], s9 offen
	buffer_load_dwordx4 v[104:107], v217, s[36:39], s8 offen
	s_waitcnt vmcnt(49)
	v_pk_mul_f32 v[192:193], v[176:177], v[110:111]
	v_pk_mul_f32 v[194:195], v[180:181], v[110:111]
	v_pk_fma_f32 v[192:193], v[178:179], v[112:113], v[192:193]
	v_pk_fma_f32 v[194:195], v[182:183], v[112:113], v[194:195]
	v_add_f32_dpp v212, v213, v212 quad_perm:[1,0,3,2] row_mask:0xf bank_mask:0xf bound_ctrl:1
	v_add_f32_e32 v196, v192, v193
	v_add_f32_e32 v197, v194, v195
	v_add_f32_dpp v212, v212, v212 quad_perm:[2,3,0,1] row_mask:0xf bank_mask:0xf bound_ctrl:1
	v_add_f32_dpp v196, v196, v196 quad_perm:[1,0,3,2] row_mask:0xf bank_mask:0xf bound_ctrl:1
	v_add_f32_dpp v197, v197, v197 quad_perm:[1,0,3,2] row_mask:0xf bank_mask:0xf bound_ctrl:1
	v_add_f32_dpp v212, v212, v212 row_ror:4 row_mask:0xf bank_mask:0xf bound_ctrl:1
	v_add_f32_dpp v196, v196, v196 quad_perm:[2,3,0,1] row_mask:0xf bank_mask:0xf bound_ctrl:1
	v_add_f32_dpp v197, v197, v197 quad_perm:[2,3,0,1] row_mask:0xf bank_mask:0xf bound_ctrl:1
	v_add_f32_dpp v212, v212, v212 row_ror:8 row_mask:0xf bank_mask:0xf bound_ctrl:1
	v_add_f32_dpp v196, v196, v196 row_ror:4 row_mask:0xf bank_mask:0xf bound_ctrl:1
	v_add_f32_dpp v197, v197, v197 row_ror:4 row_mask:0xf bank_mask:0xf bound_ctrl:1
	v_pk_mul_f32 v[198:199], v[130:131], v[122:123] op_sel_hi:[0,1]
	v_pk_mul_f32 v[202:203], v[130:131], v[122:123] op_sel:[1,0]
	s_add_i32 s24, s24, s30
	v_pk_mul_f32 v[200:201], v[130:131], v[124:125] op_sel_hi:[0,1]
	v_pk_mul_f32 v[204:205], v[130:131], v[124:125] op_sel:[1,0]
	v_pk_fma_f32 v[198:199], v[176:177], v[114:115], v[198:199]
	v_pk_fma_f32 v[202:203], v[180:181], v[114:115], v[202:203]
	v_add_f32_dpp v196, v196, v196 row_ror:8 row_mask:0xf bank_mask:0xf bound_ctrl:1
	v_add_f32_dpp v197, v197, v197 row_ror:8 row_mask:0xf bank_mask:0xf bound_ctrl:1
	buffer_store_dword v212, v222, s[44:47], s24 offen
	v_pk_fma_f32 v[200:201], v[178:179], v[116:117], v[200:201]
	v_pk_fma_f32 v[204:205], v[182:183], v[116:117], v[204:205]
	v_pk_fma_f32 v[176:177], v[118:119], v[196:197], v[198:199] op_sel_hi:[1,0,1] neg_lo:[0,1,0] neg_hi:[0,1,0]
	v_pk_fma_f32 v[180:181], v[118:119], v[196:197], v[202:203] op_sel:[0,1,0] neg_lo:[0,1,0] neg_hi:[0,1,0]
	v_pk_fma_f32 v[178:179], v[120:121], v[196:197], v[200:201] op_sel_hi:[1,0,1] neg_lo:[0,1,0] neg_hi:[0,1,0]
	v_pk_fma_f32 v[182:183], v[120:121], v[196:197], v[204:205] op_sel:[0,1,0] neg_lo:[0,1,0] neg_hi:[0,1,0]
	v_pk_mul_f32 v[206:207], v[176:177], v[126:127]
	v_pk_mul_f32 v[208:209], v[180:181], v[126:127]
	s_add_i32 s8, s8, s25
	s_add_i32 s9, s9, s30
	v_pk_fma_f32 v[206:207], v[178:179], v[128:129], v[206:207]
	v_pk_fma_f32 v[208:209], v[182:183], v[128:129], v[208:209]
	buffer_load_dwordx4 v[110:113], v216, s[36:39], s8 offen
	buffer_load_dwordx4 v[122:125], v221, s[40:43], s9 offen
	buffer_load_dwordx2 v[130:131], v218, s[36:39], s8 offen
	v_add_f32_e32 v210, v206, v207
	v_add_f32_e32 v211, v208, v209
	buffer_load_dwordx4 v[114:117], v219, s[40:43], s9 offen
	v_cndmask_b32_e64 v212, v210, v211, s[100:101]
	v_cndmask_b32_e64 v213, v211, v210, s[100:101]
	buffer_load_dwordx4 v[118:121], v220, s[40:43], s9 offen
	buffer_load_dwordx4 v[126:129], v217, s[36:39], s8 offen
	s_waitcnt vmcnt(49)
	v_pk_mul_f32 v[192:193], v[176:177], v[132:133]
	v_pk_mul_f32 v[194:195], v[180:181], v[132:133]
	v_pk_fma_f32 v[192:193], v[178:179], v[134:135], v[192:193]
	v_pk_fma_f32 v[194:195], v[182:183], v[134:135], v[194:195]
	v_add_f32_dpp v212, v213, v212 quad_perm:[1,0,3,2] row_mask:0xf bank_mask:0xf bound_ctrl:1
	v_add_f32_e32 v196, v192, v193
	v_add_f32_e32 v197, v194, v195
	v_add_f32_dpp v212, v212, v212 quad_perm:[2,3,0,1] row_mask:0xf bank_mask:0xf bound_ctrl:1
	v_add_f32_dpp v196, v196, v196 quad_perm:[1,0,3,2] row_mask:0xf bank_mask:0xf bound_ctrl:1
	v_add_f32_dpp v197, v197, v197 quad_perm:[1,0,3,2] row_mask:0xf bank_mask:0xf bound_ctrl:1
	v_add_f32_dpp v212, v212, v212 row_ror:4 row_mask:0xf bank_mask:0xf bound_ctrl:1
	v_add_f32_dpp v196, v196, v196 quad_perm:[2,3,0,1] row_mask:0xf bank_mask:0xf bound_ctrl:1
	v_add_f32_dpp v197, v197, v197 quad_perm:[2,3,0,1] row_mask:0xf bank_mask:0xf bound_ctrl:1
	v_add_f32_dpp v212, v212, v212 row_ror:8 row_mask:0xf bank_mask:0xf bound_ctrl:1
	v_add_f32_dpp v196, v196, v196 row_ror:4 row_mask:0xf bank_mask:0xf bound_ctrl:1
	v_add_f32_dpp v197, v197, v197 row_ror:4 row_mask:0xf bank_mask:0xf bound_ctrl:1
	v_pk_mul_f32 v[198:199], v[152:153], v[144:145] op_sel_hi:[0,1]
	v_pk_mul_f32 v[202:203], v[152:153], v[144:145] op_sel:[1,0]
	s_add_i32 s24, s24, s30
	v_pk_mul_f32 v[200:201], v[152:153], v[146:147] op_sel_hi:[0,1]
	v_pk_mul_f32 v[204:205], v[152:153], v[146:147] op_sel:[1,0]
	v_pk_fma_f32 v[198:199], v[176:177], v[136:137], v[198:199]
	v_pk_fma_f32 v[202:203], v[180:181], v[136:137], v[202:203]
	v_add_f32_dpp v196, v196, v196 row_ror:8 row_mask:0xf bank_mask:0xf bound_ctrl:1
	v_add_f32_dpp v197, v197, v197 row_ror:8 row_mask:0xf bank_mask:0xf bound_ctrl:1
	buffer_store_dword v212, v222, s[44:47], s24 offen
	v_pk_fma_f32 v[200:201], v[178:179], v[138:139], v[200:201]
	v_pk_fma_f32 v[204:205], v[182:183], v[138:139], v[204:205]
	v_pk_fma_f32 v[176:177], v[140:141], v[196:197], v[198:199] op_sel_hi:[1,0,1] neg_lo:[0,1,0] neg_hi:[0,1,0]
	v_pk_fma_f32 v[180:181], v[140:141], v[196:197], v[202:203] op_sel:[0,1,0] neg_lo:[0,1,0] neg_hi:[0,1,0]
	v_pk_fma_f32 v[178:179], v[142:143], v[196:197], v[200:201] op_sel_hi:[1,0,1] neg_lo:[0,1,0] neg_hi:[0,1,0]
	v_pk_fma_f32 v[182:183], v[142:143], v[196:197], v[204:205] op_sel:[0,1,0] neg_lo:[0,1,0] neg_hi:[0,1,0]
	v_pk_mul_f32 v[206:207], v[176:177], v[148:149]
	v_pk_mul_f32 v[208:209], v[180:181], v[148:149]
	s_add_i32 s8, s8, s25
	s_add_i32 s9, s9, s30
	v_pk_fma_f32 v[206:207], v[178:179], v[150:151], v[206:207]
	v_pk_fma_f32 v[208:209], v[182:183], v[150:151], v[208:209]
	buffer_load_dwordx4 v[132:135], v216, s[36:39], s8 offen
	buffer_load_dwordx4 v[144:147], v221, s[40:43], s9 offen
	buffer_load_dwordx2 v[152:153], v218, s[36:39], s8 offen
	v_add_f32_e32 v210, v206, v207
	v_add_f32_e32 v211, v208, v209
	buffer_load_dwordx4 v[136:139], v219, s[40:43], s9 offen
	v_cndmask_b32_e64 v212, v210, v211, s[100:101]
	v_cndmask_b32_e64 v213, v211, v210, s[100:101]
	buffer_load_dwordx4 v[140:143], v220, s[40:43], s9 offen
	buffer_load_dwordx4 v[148:151], v217, s[36:39], s8 offen
	s_waitcnt vmcnt(49)
	v_pk_mul_f32 v[192:193], v[176:177], v[154:155]
	v_pk_mul_f32 v[194:195], v[180:181], v[154:155]
	v_pk_fma_f32 v[192:193], v[178:179], v[156:157], v[192:193]
	v_pk_fma_f32 v[194:195], v[182:183], v[156:157], v[194:195]
	v_add_f32_dpp v212, v213, v212 quad_perm:[1,0,3,2] row_mask:0xf bank_mask:0xf bound_ctrl:1
	v_add_f32_e32 v196, v192, v193
	v_add_f32_e32 v197, v194, v195
	v_add_f32_dpp v212, v212, v212 quad_perm:[2,3,0,1] row_mask:0xf bank_mask:0xf bound_ctrl:1
	v_add_f32_dpp v196, v196, v196 quad_perm:[1,0,3,2] row_mask:0xf bank_mask:0xf bound_ctrl:1
	v_add_f32_dpp v197, v197, v197 quad_perm:[1,0,3,2] row_mask:0xf bank_mask:0xf bound_ctrl:1
	v_add_f32_dpp v212, v212, v212 row_ror:4 row_mask:0xf bank_mask:0xf bound_ctrl:1
	v_add_f32_dpp v196, v196, v196 quad_perm:[2,3,0,1] row_mask:0xf bank_mask:0xf bound_ctrl:1
	v_add_f32_dpp v197, v197, v197 quad_perm:[2,3,0,1] row_mask:0xf bank_mask:0xf bound_ctrl:1
	v_add_f32_dpp v212, v212, v212 row_ror:8 row_mask:0xf bank_mask:0xf bound_ctrl:1
	v_add_f32_dpp v196, v196, v196 row_ror:4 row_mask:0xf bank_mask:0xf bound_ctrl:1
	v_add_f32_dpp v197, v197, v197 row_ror:4 row_mask:0xf bank_mask:0xf bound_ctrl:1
	v_pk_mul_f32 v[198:199], v[174:175], v[166:167] op_sel_hi:[0,1]
	v_pk_mul_f32 v[202:203], v[174:175], v[166:167] op_sel:[1,0]
	s_add_i32 s24, s24, s30
	v_pk_mul_f32 v[200:201], v[174:175], v[168:169] op_sel_hi:[0,1]
	v_pk_mul_f32 v[204:205], v[174:175], v[168:169] op_sel:[1,0]
	v_pk_fma_f32 v[198:199], v[176:177], v[158:159], v[198:199]
	v_pk_fma_f32 v[202:203], v[180:181], v[158:159], v[202:203]
	v_add_f32_dpp v196, v196, v196 row_ror:8 row_mask:0xf bank_mask:0xf bound_ctrl:1
	v_add_f32_dpp v197, v197, v197 row_ror:8 row_mask:0xf bank_mask:0xf bound_ctrl:1
	buffer_store_dword v212, v222, s[44:47], s24 offen
	v_pk_fma_f32 v[200:201], v[178:179], v[160:161], v[200:201]
	v_pk_fma_f32 v[204:205], v[182:183], v[160:161], v[204:205]
	v_pk_fma_f32 v[176:177], v[162:163], v[196:197], v[198:199] op_sel_hi:[1,0,1] neg_lo:[0,1,0] neg_hi:[0,1,0]
	v_pk_fma_f32 v[180:181], v[162:163], v[196:197], v[202:203] op_sel:[0,1,0] neg_lo:[0,1,0] neg_hi:[0,1,0]
	v_pk_fma_f32 v[178:179], v[164:165], v[196:197], v[200:201] op_sel_hi:[1,0,1] neg_lo:[0,1,0] neg_hi:[0,1,0]
	v_pk_fma_f32 v[182:183], v[164:165], v[196:197], v[204:205] op_sel:[0,1,0] neg_lo:[0,1,0] neg_hi:[0,1,0]
	v_pk_mul_f32 v[206:207], v[176:177], v[170:171]
	v_pk_mul_f32 v[208:209], v[180:181], v[170:171]
	s_add_i32 s8, s8, s25
	s_add_i32 s9, s9, s30
	v_pk_fma_f32 v[206:207], v[178:179], v[172:173], v[206:207]
	v_pk_fma_f32 v[208:209], v[182:183], v[172:173], v[208:209]
	buffer_load_dwordx4 v[154:157], v216, s[36:39], s8 offen
	buffer_load_dwordx4 v[166:169], v221, s[40:43], s9 offen
	buffer_load_dwordx2 v[174:175], v218, s[36:39], s8 offen
	buffer_load_dwordx4 v[158:161], v219, s[40:43], s9 offen
	v_add_f32_e32 v210, v206, v207
	v_add_f32_e32 v211, v208, v209
	buffer_load_dwordx4 v[162:165], v220, s[40:43], s9 offen
	v_cndmask_b32_e64 v212, v210, v211, s[100:101]
	v_cndmask_b32_e64 v213, v211, v210, s[100:101]
	buffer_load_dwordx4 v[170:173], v217, s[36:39], s8 offen
	s_waitcnt vmcnt(49)
	v_pk_mul_f32 v[192:193], v[176:177], v[0:1]
	v_pk_mul_f32 v[194:195], v[180:181], v[0:1]
	v_pk_fma_f32 v[192:193], v[178:179], v[2:3], v[192:193]
	v_pk_fma_f32 v[194:195], v[182:183], v[2:3], v[194:195]
	v_add_f32_e32 v196, v192, v193
	v_add_f32_e32 v197, v194, v195
	v_add_f32_dpp v212, v213, v212 quad_perm:[1,0,3,2] row_mask:0xf bank_mask:0xf bound_ctrl:1
	v_add_f32_dpp v196, v196, v196 quad_perm:[1,0,3,2] row_mask:0xf bank_mask:0xf bound_ctrl:1
	v_add_f32_dpp v197, v197, v197 quad_perm:[1,0,3,2] row_mask:0xf bank_mask:0xf bound_ctrl:1
	v_add_f32_dpp v212, v212, v212 quad_perm:[2,3,0,1] row_mask:0xf bank_mask:0xf bound_ctrl:1
	v_add_f32_dpp v196, v196, v196 quad_perm:[2,3,0,1] row_mask:0xf bank_mask:0xf bound_ctrl:1
	v_add_f32_dpp v197, v197, v197 quad_perm:[2,3,0,1] row_mask:0xf bank_mask:0xf bound_ctrl:1
	v_add_f32_dpp v212, v212, v212 row_ror:4 row_mask:0xf bank_mask:0xf bound_ctrl:1
	v_add_f32_dpp v196, v196, v196 row_ror:4 row_mask:0xf bank_mask:0xf bound_ctrl:1
	v_add_f32_dpp v197, v197, v197 row_ror:4 row_mask:0xf bank_mask:0xf bound_ctrl:1
	v_pk_mul_f32 v[198:199], v[20:21], v[12:13] op_sel_hi:[0,1]
	v_pk_mul_f32 v[202:203], v[20:21], v[12:13] op_sel:[1,0]
	v_add_f32_dpp v212, v212, v212 row_ror:8 row_mask:0xf bank_mask:0xf bound_ctrl:1
	s_add_i32 s24, s24, s30
	v_pk_mul_f32 v[200:201], v[20:21], v[14:15] op_sel_hi:[0,1]
	v_pk_mul_f32 v[204:205], v[20:21], v[14:15] op_sel:[1,0]
	v_pk_fma_f32 v[198:199], v[176:177], v[4:5], v[198:199]
	v_pk_fma_f32 v[202:203], v[180:181], v[4:5], v[202:203]
	v_add_f32_dpp v196, v196, v196 row_ror:8 row_mask:0xf bank_mask:0xf bound_ctrl:1
	v_add_f32_dpp v197, v197, v197 row_ror:8 row_mask:0xf bank_mask:0xf bound_ctrl:1
	v_pk_fma_f32 v[200:201], v[178:179], v[6:7], v[200:201]
	v_pk_fma_f32 v[204:205], v[182:183], v[6:7], v[204:205]
	v_pk_fma_f32 v[176:177], v[8:9], v[196:197], v[198:199] op_sel_hi:[1,0,1] neg_lo:[0,1,0] neg_hi:[0,1,0]
	v_pk_fma_f32 v[180:181], v[8:9], v[196:197], v[202:203] op_sel:[0,1,0] neg_lo:[0,1,0] neg_hi:[0,1,0]
	buffer_store_dword v212, v222, s[44:47], s24 offen
	v_pk_fma_f32 v[178:179], v[10:11], v[196:197], v[200:201] op_sel_hi:[1,0,1] neg_lo:[0,1,0] neg_hi:[0,1,0]
	v_pk_fma_f32 v[182:183], v[10:11], v[196:197], v[204:205] op_sel:[0,1,0] neg_lo:[0,1,0] neg_hi:[0,1,0]
	v_pk_mul_f32 v[206:207], v[176:177], v[16:17]
	v_pk_mul_f32 v[208:209], v[180:181], v[16:17]
	s_waitcnt vmcnt(43)
	v_pk_fma_f32 v[206:207], v[178:179], v[18:19], v[206:207]
	v_pk_fma_f32 v[208:209], v[182:183], v[18:19], v[208:209]
	v_pk_mul_f32 v[192:193], v[176:177], v[22:23]
	v_pk_mul_f32 v[194:195], v[180:181], v[22:23]
	v_add_f32_e32 v210, v206, v207
	v_add_f32_e32 v211, v208, v209
	v_pk_fma_f32 v[192:193], v[178:179], v[24:25], v[192:193]
	v_pk_fma_f32 v[194:195], v[182:183], v[24:25], v[194:195]
	v_cndmask_b32_e64 v212, v210, v211, s[100:101]
	v_cndmask_b32_e64 v213, v211, v210, s[100:101]
	v_add_f32_e32 v196, v192, v193
	v_add_f32_e32 v197, v194, v195
	v_add_f32_dpp v212, v213, v212 quad_perm:[1,0,3,2] row_mask:0xf bank_mask:0xf bound_ctrl:1
	v_add_f32_dpp v196, v196, v196 quad_perm:[1,0,3,2] row_mask:0xf bank_mask:0xf bound_ctrl:1
	v_add_f32_dpp v197, v197, v197 quad_perm:[1,0,3,2] row_mask:0xf bank_mask:0xf bound_ctrl:1
	v_add_f32_dpp v212, v212, v212 quad_perm:[2,3,0,1] row_mask:0xf bank_mask:0xf bound_ctrl:1
	v_add_f32_dpp v196, v196, v196 quad_perm:[2,3,0,1] row_mask:0xf bank_mask:0xf bound_ctrl:1
	v_add_f32_dpp v197, v197, v197 quad_perm:[2,3,0,1] row_mask:0xf bank_mask:0xf bound_ctrl:1
	v_add_f32_dpp v212, v212, v212 row_ror:4 row_mask:0xf bank_mask:0xf bound_ctrl:1
	v_add_f32_dpp v196, v196, v196 row_ror:4 row_mask:0xf bank_mask:0xf bound_ctrl:1
	v_add_f32_dpp v197, v197, v197 row_ror:4 row_mask:0xf bank_mask:0xf bound_ctrl:1
	v_pk_mul_f32 v[198:199], v[42:43], v[34:35] op_sel_hi:[0,1]
	v_pk_mul_f32 v[202:203], v[42:43], v[34:35] op_sel:[1,0]
	v_add_f32_dpp v212, v212, v212 row_ror:8 row_mask:0xf bank_mask:0xf bound_ctrl:1
	v_pk_mul_f32 v[200:201], v[42:43], v[36:37] op_sel_hi:[0,1]
	v_pk_mul_f32 v[204:205], v[42:43], v[36:37] op_sel:[1,0]
	v_pk_fma_f32 v[198:199], v[176:177], v[26:27], v[198:199]
	v_pk_fma_f32 v[202:203], v[180:181], v[26:27], v[202:203]
	s_add_i32 s24, s24, s30
	v_add_f32_dpp v196, v196, v196 row_ror:8 row_mask:0xf bank_mask:0xf bound_ctrl:1
	v_add_f32_dpp v197, v197, v197 row_ror:8 row_mask:0xf bank_mask:0xf bound_ctrl:1
	v_pk_fma_f32 v[200:201], v[178:179], v[28:29], v[200:201]
	v_pk_fma_f32 v[204:205], v[182:183], v[28:29], v[204:205]
	v_pk_fma_f32 v[176:177], v[30:31], v[196:197], v[198:199] op_sel_hi:[1,0,1] neg_lo:[0,1,0] neg_hi:[0,1,0]
	v_pk_fma_f32 v[180:181], v[30:31], v[196:197], v[202:203] op_sel:[0,1,0] neg_lo:[0,1,0] neg_hi:[0,1,0]
	buffer_store_dword v212, v222, s[44:47], s24 offen
	v_pk_fma_f32 v[178:179], v[32:33], v[196:197], v[200:201] op_sel_hi:[1,0,1] neg_lo:[0,1,0] neg_hi:[0,1,0]
	v_pk_fma_f32 v[182:183], v[32:33], v[196:197], v[204:205] op_sel:[0,1,0] neg_lo:[0,1,0] neg_hi:[0,1,0]
	v_pk_mul_f32 v[206:207], v[176:177], v[38:39]
	v_pk_mul_f32 v[208:209], v[180:181], v[38:39]
	v_pk_fma_f32 v[206:207], v[178:179], v[40:41], v[206:207]
	v_pk_fma_f32 v[208:209], v[182:183], v[40:41], v[208:209]
	s_waitcnt vmcnt(37)
	v_pk_mul_f32 v[192:193], v[176:177], v[44:45]
	v_pk_mul_f32 v[194:195], v[180:181], v[44:45]
	v_add_f32_e32 v210, v206, v207
	v_add_f32_e32 v211, v208, v209
	v_cndmask_b32_e64 v212, v210, v211, s[100:101]
	v_cndmask_b32_e64 v213, v211, v210, s[100:101]
	v_pk_fma_f32 v[192:193], v[178:179], v[46:47], v[192:193]
	v_pk_fma_f32 v[194:195], v[182:183], v[46:47], v[194:195]
	v_add_f32_e32 v196, v192, v193
	v_add_f32_e32 v197, v194, v195
	v_add_f32_dpp v212, v213, v212 quad_perm:[1,0,3,2] row_mask:0xf bank_mask:0xf bound_ctrl:1
	v_add_f32_dpp v196, v196, v196 quad_perm:[1,0,3,2] row_mask:0xf bank_mask:0xf bound_ctrl:1
	v_add_f32_dpp v197, v197, v197 quad_perm:[1,0,3,2] row_mask:0xf bank_mask:0xf bound_ctrl:1
	v_add_f32_dpp v212, v212, v212 quad_perm:[2,3,0,1] row_mask:0xf bank_mask:0xf bound_ctrl:1
	v_add_f32_dpp v196, v196, v196 quad_perm:[2,3,0,1] row_mask:0xf bank_mask:0xf bound_ctrl:1
	v_add_f32_dpp v197, v197, v197 quad_perm:[2,3,0,1] row_mask:0xf bank_mask:0xf bound_ctrl:1
	v_add_f32_dpp v212, v212, v212 row_ror:4 row_mask:0xf bank_mask:0xf bound_ctrl:1
	v_add_f32_dpp v196, v196, v196 row_ror:4 row_mask:0xf bank_mask:0xf bound_ctrl:1
	v_add_f32_dpp v197, v197, v197 row_ror:4 row_mask:0xf bank_mask:0xf bound_ctrl:1
	v_pk_mul_f32 v[198:199], v[64:65], v[56:57] op_sel_hi:[0,1]
	v_pk_mul_f32 v[202:203], v[64:65], v[56:57] op_sel:[1,0]
	v_add_f32_dpp v212, v212, v212 row_ror:8 row_mask:0xf bank_mask:0xf bound_ctrl:1
	s_add_i32 s24, s24, s30
	v_pk_mul_f32 v[200:201], v[64:65], v[58:59] op_sel_hi:[0,1]
	v_pk_mul_f32 v[204:205], v[64:65], v[58:59] op_sel:[1,0]
	v_pk_fma_f32 v[198:199], v[176:177], v[48:49], v[198:199]
	v_pk_fma_f32 v[202:203], v[180:181], v[48:49], v[202:203]
	v_add_f32_dpp v196, v196, v196 row_ror:8 row_mask:0xf bank_mask:0xf bound_ctrl:1
	v_add_f32_dpp v197, v197, v197 row_ror:8 row_mask:0xf bank_mask:0xf bound_ctrl:1
	v_pk_fma_f32 v[200:201], v[178:179], v[50:51], v[200:201]
	v_pk_fma_f32 v[204:205], v[182:183], v[50:51], v[204:205]
	v_pk_fma_f32 v[176:177], v[52:53], v[196:197], v[198:199] op_sel_hi:[1,0,1] neg_lo:[0,1,0] neg_hi:[0,1,0]
	v_pk_fma_f32 v[180:181], v[52:53], v[196:197], v[202:203] op_sel:[0,1,0] neg_lo:[0,1,0] neg_hi:[0,1,0]
	buffer_store_dword v212, v222, s[44:47], s24 offen
	v_pk_fma_f32 v[178:179], v[54:55], v[196:197], v[200:201] op_sel_hi:[1,0,1] neg_lo:[0,1,0] neg_hi:[0,1,0]
	v_pk_fma_f32 v[182:183], v[54:55], v[196:197], v[204:205] op_sel:[0,1,0] neg_lo:[0,1,0] neg_hi:[0,1,0]
	v_pk_mul_f32 v[206:207], v[176:177], v[60:61]
	v_pk_mul_f32 v[208:209], v[180:181], v[60:61]
	s_waitcnt vmcnt(31)
	v_pk_fma_f32 v[206:207], v[178:179], v[62:63], v[206:207]
	v_pk_fma_f32 v[208:209], v[182:183], v[62:63], v[208:209]
	v_pk_mul_f32 v[192:193], v[176:177], v[66:67]
	v_pk_mul_f32 v[194:195], v[180:181], v[66:67]
	v_add_f32_e32 v210, v206, v207
	v_add_f32_e32 v211, v208, v209
	v_pk_fma_f32 v[192:193], v[178:179], v[68:69], v[192:193]
	v_pk_fma_f32 v[194:195], v[182:183], v[68:69], v[194:195]
	v_cndmask_b32_e64 v212, v210, v211, s[100:101]
	v_cndmask_b32_e64 v213, v211, v210, s[100:101]
	v_add_f32_e32 v196, v192, v193
	v_add_f32_e32 v197, v194, v195
	v_add_f32_dpp v212, v213, v212 quad_perm:[1,0,3,2] row_mask:0xf bank_mask:0xf bound_ctrl:1
	v_add_f32_dpp v196, v196, v196 quad_perm:[1,0,3,2] row_mask:0xf bank_mask:0xf bound_ctrl:1
	v_add_f32_dpp v197, v197, v197 quad_perm:[1,0,3,2] row_mask:0xf bank_mask:0xf bound_ctrl:1
	v_add_f32_dpp v212, v212, v212 quad_perm:[2,3,0,1] row_mask:0xf bank_mask:0xf bound_ctrl:1
	v_add_f32_dpp v196, v196, v196 quad_perm:[2,3,0,1] row_mask:0xf bank_mask:0xf bound_ctrl:1
	v_add_f32_dpp v197, v197, v197 quad_perm:[2,3,0,1] row_mask:0xf bank_mask:0xf bound_ctrl:1
	v_add_f32_dpp v212, v212, v212 row_ror:4 row_mask:0xf bank_mask:0xf bound_ctrl:1
	v_add_f32_dpp v196, v196, v196 row_ror:4 row_mask:0xf bank_mask:0xf bound_ctrl:1
	v_add_f32_dpp v197, v197, v197 row_ror:4 row_mask:0xf bank_mask:0xf bound_ctrl:1
	v_pk_mul_f32 v[198:199], v[86:87], v[78:79] op_sel_hi:[0,1]
	v_pk_mul_f32 v[202:203], v[86:87], v[78:79] op_sel:[1,0]
	v_add_f32_dpp v212, v212, v212 row_ror:8 row_mask:0xf bank_mask:0xf bound_ctrl:1
	v_pk_mul_f32 v[200:201], v[86:87], v[80:81] op_sel_hi:[0,1]
	v_pk_mul_f32 v[204:205], v[86:87], v[80:81] op_sel:[1,0]
	v_pk_fma_f32 v[198:199], v[176:177], v[70:71], v[198:199]
	v_pk_fma_f32 v[202:203], v[180:181], v[70:71], v[202:203]
	s_add_i32 s24, s24, s30
	v_add_f32_dpp v196, v196, v196 row_ror:8 row_mask:0xf bank_mask:0xf bound_ctrl:1
	v_add_f32_dpp v197, v197, v197 row_ror:8 row_mask:0xf bank_mask:0xf bound_ctrl:1
	v_pk_fma_f32 v[200:201], v[178:179], v[72:73], v[200:201]
	v_pk_fma_f32 v[204:205], v[182:183], v[72:73], v[204:205]
	v_pk_fma_f32 v[176:177], v[74:75], v[196:197], v[198:199] op_sel_hi:[1,0,1] neg_lo:[0,1,0] neg_hi:[0,1,0]
	v_pk_fma_f32 v[180:181], v[74:75], v[196:197], v[202:203] op_sel:[0,1,0] neg_lo:[0,1,0] neg_hi:[0,1,0]
	buffer_store_dword v212, v222, s[44:47], s24 offen
	v_pk_fma_f32 v[178:179], v[76:77], v[196:197], v[200:201] op_sel_hi:[1,0,1] neg_lo:[0,1,0] neg_hi:[0,1,0]
	v_pk_fma_f32 v[182:183], v[76:77], v[196:197], v[204:205] op_sel:[0,1,0] neg_lo:[0,1,0] neg_hi:[0,1,0]
	v_pk_mul_f32 v[206:207], v[176:177], v[82:83]
	v_pk_mul_f32 v[208:209], v[180:181], v[82:83]
	v_pk_fma_f32 v[206:207], v[178:179], v[84:85], v[206:207]
	v_pk_fma_f32 v[208:209], v[182:183], v[84:85], v[208:209]
	s_waitcnt vmcnt(25)
	v_pk_mul_f32 v[192:193], v[176:177], v[88:89]
	v_pk_mul_f32 v[194:195], v[180:181], v[88:89]
	v_add_f32_e32 v210, v206, v207
	v_add_f32_e32 v211, v208, v209
	v_cndmask_b32_e64 v212, v210, v211, s[100:101]
	v_cndmask_b32_e64 v213, v211, v210, s[100:101]
	v_pk_fma_f32 v[192:193], v[178:179], v[90:91], v[192:193]
	v_pk_fma_f32 v[194:195], v[182:183], v[90:91], v[194:195]
	v_add_f32_e32 v196, v192, v193
	v_add_f32_e32 v197, v194, v195
	v_add_f32_dpp v212, v213, v212 quad_perm:[1,0,3,2] row_mask:0xf bank_mask:0xf bound_ctrl:1
	v_add_f32_dpp v196, v196, v196 quad_perm:[1,0,3,2] row_mask:0xf bank_mask:0xf bound_ctrl:1
	v_add_f32_dpp v197, v197, v197 quad_perm:[1,0,3,2] row_mask:0xf bank_mask:0xf bound_ctrl:1
	v_add_f32_dpp v212, v212, v212 quad_perm:[2,3,0,1] row_mask:0xf bank_mask:0xf bound_ctrl:1
	v_add_f32_dpp v196, v196, v196 quad_perm:[2,3,0,1] row_mask:0xf bank_mask:0xf bound_ctrl:1
	v_add_f32_dpp v197, v197, v197 quad_perm:[2,3,0,1] row_mask:0xf bank_mask:0xf bound_ctrl:1
	v_add_f32_dpp v212, v212, v212 row_ror:4 row_mask:0xf bank_mask:0xf bound_ctrl:1
	v_add_f32_dpp v196, v196, v196 row_ror:4 row_mask:0xf bank_mask:0xf bound_ctrl:1
	v_add_f32_dpp v197, v197, v197 row_ror:4 row_mask:0xf bank_mask:0xf bound_ctrl:1
	v_pk_mul_f32 v[198:199], v[108:109], v[100:101] op_sel_hi:[0,1]
	v_pk_mul_f32 v[202:203], v[108:109], v[100:101] op_sel:[1,0]
	v_add_f32_dpp v212, v212, v212 row_ror:8 row_mask:0xf bank_mask:0xf bound_ctrl:1
	s_add_i32 s24, s24, s30
	v_pk_mul_f32 v[200:201], v[108:109], v[102:103] op_sel_hi:[0,1]
	v_pk_mul_f32 v[204:205], v[108:109], v[102:103] op_sel:[1,0]
	v_pk_fma_f32 v[198:199], v[176:177], v[92:93], v[198:199]
	v_pk_fma_f32 v[202:203], v[180:181], v[92:93], v[202:203]
	v_add_f32_dpp v196, v196, v196 row_ror:8 row_mask:0xf bank_mask:0xf bound_ctrl:1
	v_add_f32_dpp v197, v197, v197 row_ror:8 row_mask:0xf bank_mask:0xf bound_ctrl:1
	v_pk_fma_f32 v[200:201], v[178:179], v[94:95], v[200:201]
	v_pk_fma_f32 v[204:205], v[182:183], v[94:95], v[204:205]
	v_pk_fma_f32 v[176:177], v[96:97], v[196:197], v[198:199] op_sel_hi:[1,0,1] neg_lo:[0,1,0] neg_hi:[0,1,0]
	v_pk_fma_f32 v[180:181], v[96:97], v[196:197], v[202:203] op_sel:[0,1,0] neg_lo:[0,1,0] neg_hi:[0,1,0]
	buffer_store_dword v212, v222, s[44:47], s24 offen
	v_pk_fma_f32 v[178:179], v[98:99], v[196:197], v[200:201] op_sel_hi:[1,0,1] neg_lo:[0,1,0] neg_hi:[0,1,0]
	v_pk_fma_f32 v[182:183], v[98:99], v[196:197], v[204:205] op_sel:[0,1,0] neg_lo:[0,1,0] neg_hi:[0,1,0]
	v_pk_mul_f32 v[206:207], v[176:177], v[104:105]
	v_pk_mul_f32 v[208:209], v[180:181], v[104:105]
	s_waitcnt vmcnt(19)
	v_pk_fma_f32 v[206:207], v[178:179], v[106:107], v[206:207]
	v_pk_fma_f32 v[208:209], v[182:183], v[106:107], v[208:209]
	v_pk_mul_f32 v[192:193], v[176:177], v[110:111]
	v_pk_mul_f32 v[194:195], v[180:181], v[110:111]
	v_add_f32_e32 v210, v206, v207
	v_add_f32_e32 v211, v208, v209
	v_pk_fma_f32 v[192:193], v[178:179], v[112:113], v[192:193]
	v_pk_fma_f32 v[194:195], v[182:183], v[112:113], v[194:195]
	v_cndmask_b32_e64 v212, v210, v211, s[100:101]
	v_cndmask_b32_e64 v213, v211, v210, s[100:101]
	v_add_f32_e32 v196, v192, v193
	v_add_f32_e32 v197, v194, v195
	v_add_f32_dpp v212, v213, v212 quad_perm:[1,0,3,2] row_mask:0xf bank_mask:0xf bound_ctrl:1
	v_add_f32_dpp v196, v196, v196 quad_perm:[1,0,3,2] row_mask:0xf bank_mask:0xf bound_ctrl:1
	v_add_f32_dpp v197, v197, v197 quad_perm:[1,0,3,2] row_mask:0xf bank_mask:0xf bound_ctrl:1
	v_add_f32_dpp v212, v212, v212 quad_perm:[2,3,0,1] row_mask:0xf bank_mask:0xf bound_ctrl:1
	v_add_f32_dpp v196, v196, v196 quad_perm:[2,3,0,1] row_mask:0xf bank_mask:0xf bound_ctrl:1
	v_add_f32_dpp v197, v197, v197 quad_perm:[2,3,0,1] row_mask:0xf bank_mask:0xf bound_ctrl:1
	v_add_f32_dpp v212, v212, v212 row_ror:4 row_mask:0xf bank_mask:0xf bound_ctrl:1
	v_add_f32_dpp v196, v196, v196 row_ror:4 row_mask:0xf bank_mask:0xf bound_ctrl:1
	v_add_f32_dpp v197, v197, v197 row_ror:4 row_mask:0xf bank_mask:0xf bound_ctrl:1
	v_pk_mul_f32 v[198:199], v[130:131], v[122:123] op_sel_hi:[0,1]
	v_pk_mul_f32 v[202:203], v[130:131], v[122:123] op_sel:[1,0]
	v_add_f32_dpp v212, v212, v212 row_ror:8 row_mask:0xf bank_mask:0xf bound_ctrl:1
	v_pk_mul_f32 v[200:201], v[130:131], v[124:125] op_sel_hi:[0,1]
	v_pk_mul_f32 v[204:205], v[130:131], v[124:125] op_sel:[1,0]
	v_pk_fma_f32 v[198:199], v[176:177], v[114:115], v[198:199]
	v_pk_fma_f32 v[202:203], v[180:181], v[114:115], v[202:203]
	s_add_i32 s24, s24, s30
	v_add_f32_dpp v196, v196, v196 row_ror:8 row_mask:0xf bank_mask:0xf bound_ctrl:1
	v_add_f32_dpp v197, v197, v197 row_ror:8 row_mask:0xf bank_mask:0xf bound_ctrl:1
	v_pk_fma_f32 v[200:201], v[178:179], v[116:117], v[200:201]
	v_pk_fma_f32 v[204:205], v[182:183], v[116:117], v[204:205]
	v_pk_fma_f32 v[176:177], v[118:119], v[196:197], v[198:199] op_sel_hi:[1,0,1] neg_lo:[0,1,0] neg_hi:[0,1,0]
	v_pk_fma_f32 v[180:181], v[118:119], v[196:197], v[202:203] op_sel:[0,1,0] neg_lo:[0,1,0] neg_hi:[0,1,0]
	buffer_store_dword v212, v222, s[44:47], s24 offen
	v_pk_fma_f32 v[178:179], v[120:121], v[196:197], v[200:201] op_sel_hi:[1,0,1] neg_lo:[0,1,0] neg_hi:[0,1,0]
	v_pk_fma_f32 v[182:183], v[120:121], v[196:197], v[204:205] op_sel:[0,1,0] neg_lo:[0,1,0] neg_hi:[0,1,0]
	v_pk_mul_f32 v[206:207], v[176:177], v[126:127]
	v_pk_mul_f32 v[208:209], v[180:181], v[126:127]
	v_pk_fma_f32 v[206:207], v[178:179], v[128:129], v[206:207]
	v_pk_fma_f32 v[208:209], v[182:183], v[128:129], v[208:209]
	s_waitcnt vmcnt(13)
	v_pk_mul_f32 v[192:193], v[176:177], v[132:133]
	v_pk_mul_f32 v[194:195], v[180:181], v[132:133]
	v_add_f32_e32 v210, v206, v207
	v_add_f32_e32 v211, v208, v209
	v_cndmask_b32_e64 v212, v210, v211, s[100:101]
	v_cndmask_b32_e64 v213, v211, v210, s[100:101]
	v_pk_fma_f32 v[192:193], v[178:179], v[134:135], v[192:193]
	v_pk_fma_f32 v[194:195], v[182:183], v[134:135], v[194:195]
	v_add_f32_e32 v196, v192, v193
	v_add_f32_e32 v197, v194, v195
	v_add_f32_dpp v212, v213, v212 quad_perm:[1,0,3,2] row_mask:0xf bank_mask:0xf bound_ctrl:1
	v_add_f32_dpp v196, v196, v196 quad_perm:[1,0,3,2] row_mask:0xf bank_mask:0xf bound_ctrl:1
	v_add_f32_dpp v197, v197, v197 quad_perm:[1,0,3,2] row_mask:0xf bank_mask:0xf bound_ctrl:1
	v_add_f32_dpp v212, v212, v212 quad_perm:[2,3,0,1] row_mask:0xf bank_mask:0xf bound_ctrl:1
	v_add_f32_dpp v196, v196, v196 quad_perm:[2,3,0,1] row_mask:0xf bank_mask:0xf bound_ctrl:1
	v_add_f32_dpp v197, v197, v197 quad_perm:[2,3,0,1] row_mask:0xf bank_mask:0xf bound_ctrl:1
	v_add_f32_dpp v212, v212, v212 row_ror:4 row_mask:0xf bank_mask:0xf bound_ctrl:1
	v_add_f32_dpp v196, v196, v196 row_ror:4 row_mask:0xf bank_mask:0xf bound_ctrl:1
	v_add_f32_dpp v197, v197, v197 row_ror:4 row_mask:0xf bank_mask:0xf bound_ctrl:1
	v_pk_mul_f32 v[198:199], v[152:153], v[144:145] op_sel_hi:[0,1]
	v_pk_mul_f32 v[202:203], v[152:153], v[144:145] op_sel:[1,0]
	v_add_f32_dpp v212, v212, v212 row_ror:8 row_mask:0xf bank_mask:0xf bound_ctrl:1
	s_add_i32 s24, s24, s30
	v_pk_mul_f32 v[200:201], v[152:153], v[146:147] op_sel_hi:[0,1]
	v_pk_mul_f32 v[204:205], v[152:153], v[146:147] op_sel:[1,0]
	v_pk_fma_f32 v[198:199], v[176:177], v[136:137], v[198:199]
	v_pk_fma_f32 v[202:203], v[180:181], v[136:137], v[202:203]
	v_add_f32_dpp v196, v196, v196 row_ror:8 row_mask:0xf bank_mask:0xf bound_ctrl:1
	v_add_f32_dpp v197, v197, v197 row_ror:8 row_mask:0xf bank_mask:0xf bound_ctrl:1
	v_pk_fma_f32 v[200:201], v[178:179], v[138:139], v[200:201]
	v_pk_fma_f32 v[204:205], v[182:183], v[138:139], v[204:205]
	v_pk_fma_f32 v[176:177], v[140:141], v[196:197], v[198:199] op_sel_hi:[1,0,1] neg_lo:[0,1,0] neg_hi:[0,1,0]
	v_pk_fma_f32 v[180:181], v[140:141], v[196:197], v[202:203] op_sel:[0,1,0] neg_lo:[0,1,0] neg_hi:[0,1,0]
	buffer_store_dword v212, v222, s[44:47], s24 offen
	v_pk_fma_f32 v[178:179], v[142:143], v[196:197], v[200:201] op_sel_hi:[1,0,1] neg_lo:[0,1,0] neg_hi:[0,1,0]
	v_pk_fma_f32 v[182:183], v[142:143], v[196:197], v[204:205] op_sel:[0,1,0] neg_lo:[0,1,0] neg_hi:[0,1,0]
	s_waitcnt vmcnt(7)
	v_pk_mul_f32 v[192:193], v[176:177], v[154:155]
	v_pk_mul_f32 v[194:195], v[180:181], v[154:155]
	v_pk_fma_f32 v[192:193], v[178:179], v[156:157], v[192:193]
	v_pk_fma_f32 v[194:195], v[182:183], v[156:157], v[194:195]
	v_pk_mul_f32 v[206:207], v[176:177], v[148:149]
	v_pk_mul_f32 v[208:209], v[180:181], v[148:149]
	v_add_f32_e32 v196, v192, v193
	v_add_f32_e32 v197, v194, v195
	v_pk_fma_f32 v[206:207], v[178:179], v[150:151], v[206:207]
	v_pk_fma_f32 v[208:209], v[182:183], v[150:151], v[208:209]
	v_add_f32_e32 v210, v206, v207
	v_add_f32_e32 v211, v208, v209
	v_add_f32_dpp v196, v196, v196 quad_perm:[1,0,3,2] row_mask:0xf bank_mask:0xf bound_ctrl:1
	v_add_f32_dpp v197, v197, v197 quad_perm:[1,0,3,2] row_mask:0xf bank_mask:0xf bound_ctrl:1
	v_cndmask_b32_e64 v212, v210, v211, s[100:101]
	v_cndmask_b32_e64 v213, v211, v210, s[100:101]
	v_add_f32_dpp v196, v196, v196 quad_perm:[2,3,0,1] row_mask:0xf bank_mask:0xf bound_ctrl:1
	v_add_f32_dpp v197, v197, v197 quad_perm:[2,3,0,1] row_mask:0xf bank_mask:0xf bound_ctrl:1
	v_add_f32_dpp v212, v213, v212 quad_perm:[1,0,3,2] row_mask:0xf bank_mask:0xf bound_ctrl:1
	v_add_f32_dpp v196, v196, v196 row_ror:4 row_mask:0xf bank_mask:0xf bound_ctrl:1
	v_add_f32_dpp v197, v197, v197 row_ror:4 row_mask:0xf bank_mask:0xf bound_ctrl:1
	v_pk_mul_f32 v[198:199], v[174:175], v[166:167] op_sel_hi:[0,1]
	v_pk_mul_f32 v[202:203], v[174:175], v[166:167] op_sel:[1,0]
	v_add_f32_dpp v212, v212, v212 quad_perm:[2,3,0,1] row_mask:0xf bank_mask:0xf bound_ctrl:1
	v_pk_mul_f32 v[200:201], v[174:175], v[168:169] op_sel_hi:[0,1]
	v_pk_mul_f32 v[204:205], v[174:175], v[168:169] op_sel:[1,0]
	v_pk_fma_f32 v[198:199], v[176:177], v[158:159], v[198:199]
	v_pk_fma_f32 v[202:203], v[180:181], v[158:159], v[202:203]
	v_add_f32_dpp v196, v196, v196 row_ror:8 row_mask:0xf bank_mask:0xf bound_ctrl:1
	v_add_f32_dpp v197, v197, v197 row_ror:8 row_mask:0xf bank_mask:0xf bound_ctrl:1
	v_add_f32_dpp v212, v212, v212 row_ror:4 row_mask:0xf bank_mask:0xf bound_ctrl:1
	v_pk_fma_f32 v[200:201], v[178:179], v[160:161], v[200:201]
	v_pk_fma_f32 v[204:205], v[182:183], v[160:161], v[204:205]
	v_pk_fma_f32 v[176:177], v[162:163], v[196:197], v[198:199] op_sel_hi:[1,0,1] neg_lo:[0,1,0] neg_hi:[0,1,0]
	v_pk_fma_f32 v[180:181], v[162:163], v[196:197], v[202:203] op_sel:[0,1,0] neg_lo:[0,1,0] neg_hi:[0,1,0]
	v_pk_fma_f32 v[178:179], v[164:165], v[196:197], v[200:201] op_sel_hi:[1,0,1] neg_lo:[0,1,0] neg_hi:[0,1,0]
	v_pk_fma_f32 v[182:183], v[164:165], v[196:197], v[204:205] op_sel:[0,1,0] neg_lo:[0,1,0] neg_hi:[0,1,0]
	v_pk_mul_f32 v[206:207], v[176:177], v[170:171]
	v_pk_mul_f32 v[208:209], v[180:181], v[170:171]
	v_add_f32_dpp v212, v212, v212 row_ror:8 row_mask:0xf bank_mask:0xf bound_ctrl:1
	s_add_i32 s24, s24, s30
	v_pk_fma_f32 v[206:207], v[178:179], v[172:173], v[206:207]
	v_pk_fma_f32 v[208:209], v[182:183], v[172:173], v[208:209]
	v_add_f32_e32 v210, v206, v207
	v_add_f32_e32 v211, v208, v209
	buffer_store_dword v212, v222, s[44:47], s24 offen
	v_cndmask_b32_e64 v212, v210, v211, s[100:101]
	v_cndmask_b32_e64 v213, v211, v210, s[100:101]
	s_add_i32 s8, s8, s25
	s_add_i32 s9, s9, s30
	v_add_f32_dpp v212, v213, v212 quad_perm:[1,0,3,2] row_mask:0xf bank_mask:0xf bound_ctrl:1
	s_add_i32 s24, s24, s30
	s_nop 0
	v_add_f32_dpp v212, v212, v212 quad_perm:[2,3,0,1] row_mask:0xf bank_mask:0xf bound_ctrl:1
	s_nop 0
	s_nop 0
	v_add_f32_dpp v212, v212, v212 row_ror:4 row_mask:0xf bank_mask:0xf bound_ctrl:1
	s_nop 0
	s_nop 0
	v_add_f32_dpp v212, v212, v212 row_ror:8 row_mask:0xf bank_mask:0xf bound_ctrl:1
	buffer_store_dword v212, v222, s[44:47], s24 offen
	s_add_i32 s24, s24, s30
	s_lshl_b32 s3, s94, 1
	s_add_i32 s2, s2, s3
	s_branch .Lss_item
.Lss_done:
	s_setprio 0
	s_branch .LBB0_676

.LBB0_783:
	s_or_b64 exec, exec, s[0:1]
	s_waitcnt lgkmcnt(0)
	v_cndmask_b32_e64 v0, 0, 1, s[12:13]
	v_cmp_ne_u32_e64 s[0:1], 1, v0
	s_andn2_b64 vcc, exec, s[12:13]
	s_nop 0
	v_writelane_b32 v240, s0, 19
	s_barrier
	s_nop 0
	v_writelane_b32 v240, s1, 20
	v_writelane_b32 v240, s83, 21
	s_cbranch_vccnz .LBB0_1301
	s_add_u32 s78, s92, 0x5f44000
	s_addc_u32 s79, s93, 0
	s_add_u32 s0, s92, 0xe224000
	s_addc_u32 s1, s93, 0
	v_writelane_b32 v240, s0, 22
	v_mov_b32_e32 v161, 0
	s_mov_b32 s2, 0x40000
	v_writelane_b32 v240, s1, 23
	s_add_u32 s0, s92, 0x1380000
	s_addc_u32 s1, s93, 0
	v_writelane_b32 v240, s0, 24
	s_mov_b32 s70, 0x80000
	s_waitcnt vmcnt(18)
	v_mov_b32_e32 v172, 0x73f
	v_writelane_b32 v240, s1, 25
	s_add_u32 s0, s92, 0x1440100
	s_addc_u32 s1, s93, 0
	v_writelane_b32 v240, s0, 26
	v_mov_b32_e32 v173, 0x77f
	s_waitcnt vmcnt(12)
	v_mov_b32_e32 v174, 0x7bf
	v_writelane_b32 v240, s1, 27
	s_add_u32 s0, s92, 0x1400100
	s_addc_u32 s1, s93, 0
	v_writelane_b32 v240, s0, 28
	s_movk_i32 s3, 0x2000
	s_movk_i32 s71, 0x1fff
	v_writelane_b32 v240, s1, 29
	s_add_u32 s0, s92, 0x13c0100
	s_addc_u32 s1, s93, 0
	v_writelane_b32 v240, s0, 30
	s_movk_i32 s4, 0x3000
	s_nop 0
	v_writelane_b32 v240, s1, 31
	s_add_u32 s0, s92, 0x1380100
	s_addc_u32 s1, s93, 0
	v_writelane_b32 v240, s0, 32
	s_nop 1
	v_writelane_b32 v240, s1, 33
	s_nop 0
	v_readlane_b32 s6, v240, 10
	s_mov_b32 s5, s6
	v_readlane_b32 s7, v240, 11
	s_branch .LBB0_786
.LBB0_786:
	s_ashr_i32 s6, s5, 31
	s_lshr_b32 s6, s6, 29
	s_add_i32 s6, s5, s6
	s_lshl_b32 s7, s6, 5
	s_and_b32 s6, s6, 0xfffff8
	s_sub_i32 s6, s5, s6
	v_mov_b32_e32 v175, v190
	s_lshl_b32 s8, s6, 8
	s_and_b32 s9, s7, 0xffffff00
	v_ashrrev_i32_e32 v35, 3, v175
	v_add_u32_e32 v34, s8, v35
	v_add_u32_e32 v0, s9, v35
	v_min_i32_e32 v2, 0x7ff, v34
	v_ashrrev_i32_e32 v1, 31, v0
	v_ashrrev_i32_e32 v3, 31, v2
	v_lshlrev_b64 v[32:33], 12, v[0:1]
	v_lshlrev_b32_e32 v0, 4, v175
	v_readlane_b32 s0, v240, 24
	v_lshlrev_b64 v[36:37], 12, v[2:3]
	v_min_i32_e32 v2, 0x7bf, v34
	v_and_b32_e32 v160, 0x70, v0
	v_readlane_b32 s1, v240, 25
	v_ashrrev_i32_e32 v3, 31, v2
	v_lshlrev_b64 v[2:3], 12, v[2:3]
	v_lshl_add_u64 v[0:1], s[0:1], 0, v[160:161]
	v_lshl_add_u64 v[40:41], v[0:1], 0, v[2:3]
	v_min_i32_e32 v2, 0x77f, v34
	v_ashrrev_i32_e32 v3, 31, v2
	v_lshlrev_b64 v[2:3], 12, v[2:3]
	v_lshl_add_u64 v[42:43], v[0:1], 0, v[2:3]
	v_min_i32_e32 v2, 0x73f, v34
	v_ashrrev_i32_e32 v3, 31, v2
	v_readlane_b32 s0, v240, 22
	v_lshlrev_b64 v[2:3], 12, v[2:3]
	v_readlane_b32 s1, v240, 23
	v_lshl_add_u64 v[38:39], v[0:1], 0, v[36:37]
	v_lshl_add_u64 v[44:45], v[0:1], 0, v[2:3]
	v_lshl_add_u64 v[0:1], s[0:1], 0, v[32:33]
	v_lshl_add_u64 v[46:47], v[0:1], 0, v[160:161]
	v_add_co_u32_e32 v48, vcc, s2, v46
	s_mov_b32 s0, 0xc0000
	s_nop 0
	v_addc_co_u32_e32 v49, vcc, 0, v47, vcc
	v_add_co_u32_e32 v50, vcc, s70, v46
	s_nop 1
	v_addc_co_u32_e32 v51, vcc, 0, v47, vcc
	v_add_co_u32_e32 v52, vcc, s0, v46
	s_barrier
	s_nop 0
	v_addc_co_u32_e32 v53, vcc, 0, v47, vcc
	v_add_co_u32_e32 v20, vcc, s2, v40
	s_nop 1
	v_addc_co_u32_e32 v21, vcc, 0, v41, vcc
	v_add_co_u32_e32 v24, vcc, s70, v42
	global_load_dwordx4 v[0:3], v[46:47], off
	global_load_dwordx4 v[4:7], v[48:49], off
	v_addc_co_u32_e32 v25, vcc, 0, v43, vcc
	v_add_co_u32_e32 v28, vcc, s0, v44
	global_load_dwordx4 v[8:11], v[50:51], off
	s_nop 0
	v_addc_co_u32_e32 v29, vcc, 0, v45, vcc
	global_load_dwordx4 v[12:15], v[52:53], off
	global_load_dwordx4 v[16:19], v[38:39], off
	s_mov_b64 s[12:13], 0xc0000
	global_load_dwordx4 v[20:23], v[20:21], off
	s_nop 0
	global_load_dwordx4 v[24:27], v[24:25], off
	s_nop 0
	global_load_dwordx4 v[28:31], v[28:29], off
	s_movk_i32 s0, 0x90
	v_lshl_add_u64 v[44:45], v[44:45], 0, s[12:13]
	global_load_dwordx4 v[140:143], v[46:47], off offset:128
	global_load_dwordx4 v[136:139], v[48:49], off offset:128
	global_load_dwordx4 v[132:135], v[50:51], off offset:128
	global_load_dwordx4 v[128:131], v[38:39], off offset:128
	global_load_dwordx4 v[144:147], v[52:53], off offset:128
	global_load_dwordx4 v[148:151], v[44:45], off offset:128
	v_mul_lo_u32 v35, v35, s0
	s_mov_b64 s[6:7], 0x40000
	v_add_u32_e32 v182, v35, v160
	s_mov_b64 s[10:11], 0x80000
	v_lshl_add_u64 v[40:41], v[40:41], 0, s[6:7]
	v_lshl_add_u64 v[42:43], v[42:43], 0, s[10:11]
	v_and_b32_e32 v176, 31, v175
	v_ashrrev_i32_e32 v35, 31, v34
	s_mov_b64 s[6:7], 0x73f
	v_cmp_gt_i64_e32 vcc, s[6:7], v[34:35]
	s_mov_b64 s[6:7], 0x77f
	v_bfe_u32 v177, v175, 5, 1
	v_or_b32_e32 v36, v36, v160
	v_or_b32_e32 v32, v32, v160
	s_waitcnt vmcnt(20)
	v_lshlrev_b32_e32 v179, 4, v177
	v_lshl_add_u64 v[170:171], s[92:93], 0, v[32:33]
	s_mov_b32 s10, 0
	v_mov_b32_e32 v64, 0
	v_mov_b32_e32 v65, v161
	v_mov_b32_e32 v66, v161
	v_mov_b32_e32 v67, v161
	v_mov_b32_e32 v68, v161
	v_mov_b32_e32 v69, v161
	v_mov_b32_e32 v70, v161
	v_mov_b32_e32 v71, v161
	v_mov_b32_e32 v72, v161
	v_mov_b32_e32 v73, v161
	v_mov_b32_e32 v74, v161
	v_mov_b32_e32 v75, v161
	v_mov_b32_e32 v76, v161
	v_mov_b32_e32 v77, v161
	v_mov_b32_e32 v78, v161
	v_mov_b32_e32 v79, v161
	v_mov_b32_e32 v80, 0
	s_waitcnt vmcnt(13)
	ds_write_b128 v182, v[0:3]
	s_waitcnt vmcnt(12)
	ds_write_b128 v182, v[4:7] offset:9216
	s_waitcnt vmcnt(11)
	ds_write_b128 v182, v[8:11] offset:18432
	s_waitcnt vmcnt(10)
	ds_write_b128 v182, v[12:15] offset:27648
	s_waitcnt vmcnt(9)
	ds_write_b128 v182, v[16:19] offset:36864
	s_waitcnt vmcnt(8)
	ds_write_b128 v182, v[20:23] offset:46080
	s_waitcnt vmcnt(7)
	ds_write_b128 v182, v[24:27] offset:55296
	s_waitcnt vmcnt(6)
	ds_write_b128 v182, v[28:31] offset:64512
	global_load_dwordx4 v[152:155], v[40:41], off offset:128
	global_load_dwordx4 v[156:159], v[42:43], off offset:128
	v_ashrrev_i32_e32 v0, 1, v175
	v_and_b32_e32 v178, 0xffffff80, v0
	v_or_b32_e32 v0, v178, v176
	v_mul_lo_u32 v181, v0, s0
	v_and_b32_e32 v0, 0xdf, v175
	v_mul_u32_u24_e32 v180, 0x90, v0
	v_cndmask_b32_e32 v1, 0, v35, vcc
	v_cndmask_b32_e32 v0, v172, v34, vcc
	v_lshlrev_b64 v[0:1], 12, v[0:1]
	v_readlane_b32 s0, v240, 26
	v_or_b32_e32 v0, v0, v160
	v_readlane_b32 s1, v240, 27
	v_cmp_gt_i64_e32 vcc, s[6:7], v[34:35]
	s_mov_b64 s[6:7], 0x7bf
	v_lshl_add_u64 v[162:163], s[0:1], 0, v[0:1]
	v_cndmask_b32_e32 v1, 0, v35, vcc
	v_cndmask_b32_e32 v0, v173, v34, vcc
	v_lshlrev_b64 v[0:1], 12, v[0:1]
	v_readlane_b32 s0, v240, 28
	v_or_b32_e32 v0, v0, v160
	v_readlane_b32 s1, v240, 29
	v_cmp_gt_i64_e32 vcc, s[6:7], v[34:35]
	s_mov_b64 s[6:7], 0
	v_lshl_add_u64 v[164:165], s[0:1], 0, v[0:1]
	v_cndmask_b32_e32 v1, 0, v35, vcc
	v_cndmask_b32_e32 v0, v174, v34, vcc
	v_lshlrev_b64 v[0:1], 12, v[0:1]
	v_readlane_b32 s0, v240, 30
	v_or_b32_e32 v0, v0, v160
	v_readlane_b32 s1, v240, 31
	v_mov_b32_e32 v81, v161
	v_mov_b32_e32 v82, v161
	v_lshl_add_u64 v[166:167], s[0:1], 0, v[0:1]
	v_readlane_b32 s0, v240, 32
	v_readlane_b32 s1, v240, 33
	v_mov_b32_e32 v83, v161
	v_mov_b32_e32 v84, v161
	v_lshl_add_u64 v[168:169], s[0:1], 0, v[36:37]
	v_mov_b32_e32 v85, v161
	v_mov_b32_e32 v86, v161
	v_mov_b32_e32 v87, v161
	v_mov_b32_e32 v88, v161
	v_mov_b32_e32 v89, v161
	v_mov_b32_e32 v90, v161
	v_mov_b32_e32 v91, v161
	v_mov_b32_e32 v92, v161
	v_mov_b32_e32 v93, v161
	v_mov_b32_e32 v94, v161
	v_mov_b32_e32 v95, v161
	v_mov_b32_e32 v96, 0
	v_mov_b32_e32 v97, v161
	v_mov_b32_e32 v98, v161
	v_mov_b32_e32 v99, v161
	v_mov_b32_e32 v100, v161
	v_mov_b32_e32 v101, v161
	v_mov_b32_e32 v102, v161
	v_mov_b32_e32 v103, v161
	v_mov_b32_e32 v104, v161
	v_mov_b32_e32 v105, v161
	v_mov_b32_e32 v106, v161
	v_mov_b32_e32 v107, v161
	v_mov_b32_e32 v108, v161
	v_mov_b32_e32 v109, v161
	v_mov_b32_e32 v110, v161
	v_mov_b32_e32 v111, v161
	v_mov_b32_e32 v112, 0
	v_mov_b32_e32 v113, v161
	v_mov_b32_e32 v114, v161
	v_mov_b32_e32 v115, v161
	v_mov_b32_e32 v116, v161
	v_mov_b32_e32 v117, v161
	v_mov_b32_e32 v118, v161
	v_mov_b32_e32 v119, v161
	v_mov_b32_e32 v120, v161
	v_mov_b32_e32 v121, v161
	v_mov_b32_e32 v122, v161
	v_mov_b32_e32 v123, v161
	v_mov_b32_e32 v124, v161
	v_mov_b32_e32 v125, v161
	v_mov_b32_e32 v126, v161
	v_mov_b32_e32 v127, v161
	v_mov_b32_e32 v48, 0
	v_mov_b32_e32 v49, v161
	v_mov_b32_e32 v50, v161
	v_mov_b32_e32 v51, v161
	v_mov_b32_e32 v52, v161
	v_mov_b32_e32 v53, v161
	v_mov_b32_e32 v54, v161
	v_mov_b32_e32 v55, v161
	v_mov_b32_e32 v56, v161
	v_mov_b32_e32 v57, v161
	v_mov_b32_e32 v58, v161
	v_mov_b32_e32 v59, v161
	v_mov_b32_e32 v60, v161
	v_mov_b32_e32 v61, v161
	v_mov_b32_e32 v62, v161
	v_mov_b32_e32 v63, v161
	v_mov_b32_e32 v32, 0
	v_mov_b32_e32 v33, v161
	v_mov_b32_e32 v34, v161
	v_mov_b32_e32 v35, v161
	v_mov_b32_e32 v36, v161
	v_mov_b32_e32 v37, v161
	v_mov_b32_e32 v38, v161
	v_mov_b32_e32 v39, v161
	v_mov_b32_e32 v40, v161
	v_mov_b32_e32 v41, v161
	v_mov_b32_e32 v42, v161
	v_mov_b32_e32 v43, v161
	v_mov_b32_e32 v44, v161
	v_mov_b32_e32 v45, v161
	v_mov_b32_e32 v46, v161
	v_mov_b32_e32 v47, v161
	v_mov_b32_e32 v16, 0
	v_mov_b32_e32 v17, v161
	v_mov_b32_e32 v18, v161
	v_mov_b32_e32 v19, v161
	v_mov_b32_e32 v20, v161
	v_mov_b32_e32 v21, v161
	v_mov_b32_e32 v22, v161
	v_mov_b32_e32 v23, v161
	v_mov_b32_e32 v24, v161
	v_mov_b32_e32 v25, v161
	v_mov_b32_e32 v26, v161
	v_mov_b32_e32 v27, v161
	v_mov_b32_e32 v28, v161
	v_mov_b32_e32 v29, v161
	v_mov_b32_e32 v30, v161
	v_mov_b32_e32 v31, v161
	v_mov_b32_e32 v0, 0
	v_mov_b32_e32 v1, v161
	v_mov_b32_e32 v2, v161
	v_mov_b32_e32 v3, v161
	v_mov_b32_e32 v4, v161
	v_mov_b32_e32 v5, v161
	v_mov_b32_e32 v6, v161
	v_mov_b32_e32 v7, v161
	v_mov_b32_e32 v8, v161
	v_mov_b32_e32 v9, v161
	v_mov_b32_e32 v10, v161
	v_mov_b32_e32 v11, v161
	v_mov_b32_e32 v12, v161
	v_mov_b32_e32 v13, v161
	v_mov_b32_e32 v14, v161
	v_mov_b32_e32 v15, v161
	s_waitcnt lgkmcnt(0)
	s_barrier
.LBB0_787:
	s_and_b32 s11, s10, 1
	s_mul_i32 s12, s11, 0x12000
	v_or_b32_e32 v160, s12, v179
	v_add_u32_e32 v183, v160, v181
	v_add_u32_e32 v160, v160, v180
	ds_read_b128 v[184:187], v183
	ds_read_b128 v[192:195], v160 offset:36864
	ds_read_b128 v[196:199], v183 offset:32
	ds_read_b128 v[200:203], v160 offset:36896
	ds_read_b128 v[204:207], v160 offset:41472
	ds_read_b128 v[208:211], v160 offset:41504
	s_waitcnt lgkmcnt(4)
	v_mfma_f32_32x32x16_bf16 v[112:127], v[184:187], v[192:195], v[112:127]
	s_xor_b32 s11, s11, 1
	s_mul_i32 s11, s11, 0x12000
	s_mov_b32 s12, 0xe264000
	s_mov_b32 s13, 0xe2a4000
	s_mov_b32 s14, 0xe2e4000
	v_lshl_add_u64 v[188:189], v[162:163], 0, s[6:7]
	s_add_i32 s10, s10, 1
	s_waitcnt lgkmcnt(1)
	v_mfma_f32_32x32x16_bf16 v[96:111], v[184:187], v[204:207], v[96:111]
	ds_read_b128 v[184:187], v183 offset:4608
	ds_read_b128 v[212:215], v183 offset:4640
	s_waitcnt lgkmcnt(1)
	v_mfma_f32_32x32x16_bf16 v[80:95], v[184:187], v[192:195], v[80:95]
	v_mfma_f32_32x32x16_bf16 v[64:79], v[184:187], v[204:207], v[64:79]
	ds_read_b128 v[184:187], v183 offset:9216
	ds_read_b128 v[216:219], v183 offset:9248
	s_waitcnt lgkmcnt(1)
	v_mfma_f32_32x32x16_bf16 v[48:63], v[184:187], v[192:195], v[48:63]
	v_mfma_f32_32x32x16_bf16 v[32:47], v[184:187], v[204:207], v[32:47]
	ds_read_b128 v[184:187], v183 offset:13824
	ds_read_b128 v[220:223], v183 offset:13856
	v_mfma_f32_32x32x16_bf16 v[112:127], v[196:199], v[200:203], v[112:127]
	v_mfma_f32_32x32x16_bf16 v[96:111], v[196:199], v[208:211], v[96:111]
	s_waitcnt lgkmcnt(1)
	v_mfma_f32_32x32x16_bf16 v[16:31], v[184:187], v[192:195], v[16:31]
	v_mfma_f32_32x32x16_bf16 v[0:15], v[184:187], v[204:207], v[0:15]
	v_add_u32_e32 v184, s11, v182
	s_waitcnt vmcnt(7)
	ds_write_b128 v184, v[140:143]
	s_waitcnt vmcnt(6)
	ds_write_b128 v184, v[136:139] offset:9216
	s_waitcnt vmcnt(5)
	ds_write_b128 v184, v[132:135] offset:18432
	s_waitcnt vmcnt(3)
	ds_write_b128 v184, v[144:147] offset:27648
	ds_write_b128 v184, v[128:131] offset:36864
	s_waitcnt vmcnt(1)
	ds_write_b128 v184, v[152:155] offset:46080
	s_waitcnt vmcnt(0)
	ds_write_b128 v184, v[156:159] offset:55296
	ds_write_b128 v184, v[148:151] offset:64512
	ds_read_b128 v[128:131], v183 offset:64
	ds_read_b128 v[132:135], v160 offset:36928
	ds_read_b128 v[136:139], v183 offset:96
	ds_read_b128 v[148:151], v160 offset:36960
	ds_read_b128 v[140:143], v160 offset:41536
	ds_read_b128 v[184:187], v160 offset:41568
	s_mov_b32 s11, 0xe224000
	v_lshl_add_u64 v[156:157], v[166:167], 0, s[6:7]
	v_mfma_f32_32x32x16_bf16 v[80:95], v[212:215], v[200:203], v[80:95]
	v_lshl_add_u64 v[158:159], v[164:165], 0, s[6:7]
	v_mfma_f32_32x32x16_bf16 v[64:79], v[212:215], v[208:211], v[64:79]
	v_mfma_f32_32x32x16_bf16 v[48:63], v[216:219], v[200:203], v[48:63]
	v_mfma_f32_32x32x16_bf16 v[32:47], v[216:219], v[208:211], v[32:47]
	s_waitcnt lgkmcnt(4)
	v_mfma_f32_32x32x16_bf16 v[112:127], v[128:131], v[132:135], v[112:127]
	s_waitcnt lgkmcnt(1)
	v_mfma_f32_32x32x16_bf16 v[96:111], v[128:131], v[140:143], v[96:111]
	ds_read_b128 v[128:131], v183 offset:4672
	ds_read_b128 v[144:147], v183 offset:4704
	v_mfma_f32_32x32x16_bf16 v[16:31], v[220:223], v[200:203], v[16:31]
	v_mfma_f32_32x32x16_bf16 v[0:15], v[220:223], v[208:211], v[0:15]
	s_waitcnt lgkmcnt(1)
	v_mfma_f32_32x32x16_bf16 v[80:95], v[128:131], v[132:135], v[80:95]
	v_mfma_f32_32x32x16_bf16 v[64:79], v[128:131], v[140:143], v[64:79]
	ds_read_b128 v[128:131], v183 offset:9280
	ds_read_b128 v[152:155], v183 offset:9312
	s_waitcnt lgkmcnt(1)
	v_mfma_f32_32x32x16_bf16 v[48:63], v[128:131], v[132:135], v[48:63]
	v_mfma_f32_32x32x16_bf16 v[32:47], v[128:131], v[140:143], v[32:47]
	ds_read_b128 v[128:131], v183 offset:13888
	ds_read_b128 v[192:195], v183 offset:13920
	s_waitcnt lgkmcnt(1)
	v_mfma_f32_32x32x16_bf16 v[16:31], v[128:131], v[132:135], v[16:31]
	v_mfma_f32_32x32x16_bf16 v[0:15], v[128:131], v[140:143], v[0:15]
	v_lshl_add_u64 v[128:129], v[170:171], 0, s[6:7]
	v_add_co_u32_e32 v132, vcc, s11, v128
	v_lshl_add_u64 v[130:131], v[168:169], 0, s[6:7]
	s_nop 0
	v_addc_co_u32_e32 v133, vcc, 0, v129, vcc
	v_add_co_u32_e32 v134, vcc, s12, v128
	v_mfma_f32_32x32x16_bf16 v[80:95], v[144:147], v[148:151], v[80:95]
	s_nop 0
	v_addc_co_u32_e32 v135, vcc, 0, v129, vcc
	s_add_u32 s6, s6, 0x80
	s_addc_u32 s7, s7, 0
	s_cmpk_eq_i32 s6, 0xf00
	v_mfma_f32_32x32x16_bf16 v[64:79], v[144:147], v[184:187], v[64:79]
	v_add_co_u32_e32 v144, vcc, s13, v128
	s_nop 1
	v_addc_co_u32_e32 v145, vcc, 0, v129, vcc
	v_add_co_u32_e32 v128, vcc, s14, v128
	v_mfma_f32_32x32x16_bf16 v[112:127], v[136:139], v[148:151], v[112:127]
	s_nop 0
	v_addc_co_u32_e32 v129, vcc, 0, v129, vcc
	v_mfma_f32_32x32x16_bf16 v[96:111], v[136:139], v[184:187], v[96:111]
	v_mfma_f32_32x32x16_bf16 v[48:63], v[152:155], v[148:151], v[48:63]
	v_mfma_f32_32x32x16_bf16 v[32:47], v[152:155], v[184:187], v[32:47]
	global_load_dwordx4 v[140:143], v[132:133], off offset:256
	global_load_dwordx4 v[136:139], v[134:135], off offset:256
	s_nop 0
	global_load_dwordx4 v[132:135], v[144:145], off offset:256
	s_nop 0
	global_load_dwordx4 v[144:147], v[128:129], off offset:256
	s_nop 0
	global_load_dwordx4 v[128:131], v[130:131], off
	s_nop 0
	global_load_dwordx4 v[152:155], v[156:157], off
	s_nop 0
	global_load_dwordx4 v[156:159], v[158:159], off
	s_waitcnt lgkmcnt(0)
	v_mfma_f32_32x32x16_bf16 v[16:31], v[192:195], v[148:151], v[16:31]
	global_load_dwordx4 v[148:151], v[188:189], off
	s_barrier
	v_mfma_f32_32x32x16_bf16 v[0:15], v[192:195], v[184:187], v[0:15]
	s_cbranch_scc0 .LBB0_787
	v_add_u32_e32 v160, v179, v181
	ds_read_b128 v[162:165], v160
	v_add_u32_e32 v170, v179, v180
	ds_read_b128 v[166:169], v170 offset:36864
	ds_read_b128 v[184:187], v160 offset:32
	ds_read_b128 v[192:195], v170 offset:36896
	ds_read_b128 v[196:199], v170 offset:41472
	ds_read_b128 v[200:203], v170 offset:41504
	s_waitcnt lgkmcnt(4)
	v_mfma_f32_32x32x16_bf16 v[112:127], v[162:165], v[166:169], v[112:127]
	s_waitcnt lgkmcnt(1)
	v_mfma_f32_32x32x16_bf16 v[96:111], v[162:165], v[196:199], v[96:111]
	ds_read_b128 v[162:165], v160 offset:4608
	ds_read_b128 v[204:207], v160 offset:4640
	s_waitcnt lgkmcnt(1)
	v_mfma_f32_32x32x16_bf16 v[80:95], v[162:165], v[166:169], v[80:95]
	v_mfma_f32_32x32x16_bf16 v[64:79], v[162:165], v[196:199], v[64:79]
	ds_read_b128 v[162:165], v160 offset:9216
	ds_read_b128 v[208:211], v160 offset:9248
	s_waitcnt lgkmcnt(1)
	v_mfma_f32_32x32x16_bf16 v[48:63], v[162:165], v[166:169], v[48:63]
	v_mfma_f32_32x32x16_bf16 v[32:47], v[162:165], v[196:199], v[32:47]
	ds_read_b128 v[162:165], v160 offset:13824
	ds_read_b128 v[212:215], v160 offset:13856
	v_mfma_f32_32x32x16_bf16 v[112:127], v[184:187], v[192:195], v[112:127]
	v_mfma_f32_32x32x16_bf16 v[96:111], v[184:187], v[200:203], v[96:111]
	s_waitcnt lgkmcnt(1)
	v_mfma_f32_32x32x16_bf16 v[16:31], v[162:165], v[166:169], v[16:31]
	v_mfma_f32_32x32x16_bf16 v[0:15], v[162:165], v[196:199], v[0:15]
	v_add_u32_e32 v162, 0x12000, v182
	s_waitcnt vmcnt(7)
	ds_write_b128 v162, v[140:143]
	s_waitcnt vmcnt(6)
	ds_write_b128 v162, v[136:139] offset:9216
	s_waitcnt vmcnt(5)
	ds_write_b128 v162, v[132:135] offset:18432
	s_waitcnt vmcnt(4)
	ds_write_b128 v162, v[144:147] offset:27648
	v_add_u32_e32 v132, 0x1b000, v182
	s_waitcnt vmcnt(3)
	ds_write_b128 v132, v[128:131]
	s_waitcnt vmcnt(2)
	ds_write_b128 v132, v[152:155] offset:9216
	s_waitcnt vmcnt(1)
	ds_write_b128 v132, v[156:159] offset:18432
	s_waitcnt vmcnt(0)
	ds_write_b128 v132, v[148:151] offset:27648
	ds_read_b128 v[128:131], v160 offset:64
	ds_read_b128 v[132:135], v170 offset:36928
	ds_read_b128 v[136:139], v160 offset:96
	ds_read_b128 v[140:143], v170 offset:36960
	ds_read_b128 v[144:147], v170 offset:41536
	ds_read_b128 v[148:151], v170 offset:41568
	v_mfma_f32_32x32x16_bf16 v[80:95], v[204:207], v[192:195], v[80:95]
	v_mfma_f32_32x32x16_bf16 v[64:79], v[204:207], v[200:203], v[64:79]
	v_mfma_f32_32x32x16_bf16 v[48:63], v[208:211], v[192:195], v[48:63]
	v_mfma_f32_32x32x16_bf16 v[32:47], v[208:211], v[200:203], v[32:47]
	s_waitcnt lgkmcnt(4)
	v_mfma_f32_32x32x16_bf16 v[112:127], v[128:131], v[132:135], v[112:127]
	s_waitcnt lgkmcnt(1)
	v_mfma_f32_32x32x16_bf16 v[96:111], v[128:131], v[144:147], v[96:111]
	ds_read_b128 v[128:131], v160 offset:4672
	ds_read_b128 v[152:155], v160 offset:4704
	v_mfma_f32_32x32x16_bf16 v[0:15], v[212:215], v[200:203], v[0:15]
	s_waitcnt lgkmcnt(1)
	v_mfma_f32_32x32x16_bf16 v[80:95], v[128:131], v[132:135], v[80:95]
	v_mfma_f32_32x32x16_bf16 v[64:79], v[128:131], v[144:147], v[64:79]
	ds_read_b128 v[128:131], v160 offset:9280
	ds_read_b128 v[156:159], v160 offset:9312
	v_mfma_f32_32x32x16_bf16 v[16:31], v[212:215], v[192:195], v[16:31]
	s_waitcnt lgkmcnt(1)
	v_mfma_f32_32x32x16_bf16 v[48:63], v[128:131], v[132:135], v[48:63]
	v_mfma_f32_32x32x16_bf16 v[32:47], v[128:131], v[144:147], v[32:47]
	ds_read_b128 v[128:131], v160 offset:13888
	ds_read_b128 v[162:165], v160 offset:13920
	s_waitcnt lgkmcnt(0)
	s_barrier
	v_mfma_f32_32x32x16_bf16 v[0:15], v[128:131], v[144:147], v[0:15]
	v_mfma_f32_32x32x16_bf16 v[16:31], v[128:131], v[132:135], v[16:31]
	v_mfma_f32_32x32x16_bf16 v[80:95], v[152:155], v[140:143], v[80:95]
	v_mfma_f32_32x32x16_bf16 v[64:79], v[152:155], v[148:151], v[64:79]
	v_add_u32_e32 v152, 0x12000, v181
	v_add_u32_e32 v144, v152, v179
	ds_read_b128 v[128:131], v144
	v_mfma_f32_32x32x16_bf16 v[112:127], v[136:139], v[140:143], v[112:127]
	v_mfma_f32_32x32x16_bf16 v[96:111], v[136:139], v[148:151], v[96:111]
	v_mfma_f32_32x32x16_bf16 v[32:47], v[156:159], v[148:151], v[32:47]
	v_mfma_f32_32x32x16_bf16 v[0:15], v[162:165], v[148:151], v[0:15]
	v_add_u32_e32 v148, 0x1b000, v180
	v_mfma_f32_32x32x16_bf16 v[48:63], v[156:159], v[140:143], v[48:63]
	v_mfma_f32_32x32x16_bf16 v[16:31], v[162:165], v[140:143], v[16:31]
	v_add_u32_e32 v140, v148, v179
	ds_read_b128 v[132:135], v140
	ds_read_b128 v[136:139], v144 offset:4608
	ds_read_b128 v[140:143], v140 offset:4608
	s_waitcnt lgkmcnt(2)
	v_mfma_f32_32x32x16_bf16 v[112:127], v[128:131], v[132:135], v[112:127]
	s_waitcnt lgkmcnt(0)
	v_mfma_f32_32x32x16_bf16 v[96:111], v[128:131], v[140:143], v[96:111]
	v_mfma_f32_32x32x16_bf16 v[80:95], v[136:139], v[132:135], v[80:95]
	v_mfma_f32_32x32x16_bf16 v[64:79], v[136:139], v[140:143], v[64:79]
	ds_read_b128 v[128:131], v144 offset:9216
	ds_read_b128 v[136:139], v144 offset:13824
	v_add_u32_e32 v144, 0x12020, v160
	s_waitcnt lgkmcnt(1)
	v_mfma_f32_32x32x16_bf16 v[48:63], v[128:131], v[132:135], v[48:63]
	s_waitcnt lgkmcnt(0)
	v_mfma_f32_32x32x16_bf16 v[16:31], v[136:139], v[132:135], v[16:31]
	v_or_b32_e32 v132, 32, v179
	v_mfma_f32_32x32x16_bf16 v[32:47], v[128:131], v[140:143], v[32:47]
	v_add_u32_e32 v128, v152, v132
	ds_read_b128 v[128:131], v128
	v_add_u32_e32 v132, v148, v132
	ds_read_b128 v[132:135], v132
	v_mfma_f32_32x32x16_bf16 v[0:15], v[136:139], v[140:143], v[0:15]
	ds_read_b128 v[136:139], v144 offset:4608
	v_add_u32_e32 v140, 0x1c220, v170
	ds_read_b128 v[140:143], v140
	s_waitcnt lgkmcnt(2)
	v_mfma_f32_32x32x16_bf16 v[112:127], v[128:131], v[132:135], v[112:127]
	s_waitcnt lgkmcnt(0)
	v_mfma_f32_32x32x16_bf16 v[96:111], v[128:131], v[140:143], v[96:111]
	v_mfma_f32_32x32x16_bf16 v[80:95], v[136:139], v[132:135], v[80:95]
	v_mfma_f32_32x32x16_bf16 v[64:79], v[136:139], v[140:143], v[64:79]
	ds_read_b128 v[128:131], v144 offset:9216
	ds_read_b128 v[136:139], v144 offset:13824
	v_add_u32_e32 v144, 0x12040, v160
	s_waitcnt lgkmcnt(1)
	v_mfma_f32_32x32x16_bf16 v[48:63], v[128:131], v[132:135], v[48:63]
	s_waitcnt lgkmcnt(0)
	v_mfma_f32_32x32x16_bf16 v[16:31], v[136:139], v[132:135], v[16:31]
	v_or_b32_e32 v132, 64, v179
	v_mfma_f32_32x32x16_bf16 v[32:47], v[128:131], v[140:143], v[32:47]
	v_add_u32_e32 v128, v152, v132
	ds_read_b128 v[128:131], v128
	v_add_u32_e32 v132, v148, v132
	ds_read_b128 v[132:135], v132
	v_mfma_f32_32x32x16_bf16 v[0:15], v[136:139], v[140:143], v[0:15]
	v_add_u32_e32 v136, 0x1c240, v170
	ds_read_b128 v[136:139], v136
	ds_read_b128 v[140:143], v144 offset:13824
	s_waitcnt lgkmcnt(2)
	v_mfma_f32_32x32x16_bf16 v[112:127], v[128:131], v[132:135], v[112:127]
	s_waitcnt lgkmcnt(1)
	v_mfma_f32_32x32x16_bf16 v[96:111], v[128:131], v[136:139], v[96:111]
	ds_read_b128 v[128:131], v144 offset:4608
	ds_read_b128 v[144:147], v144 offset:9216
	s_waitcnt lgkmcnt(1)
	v_mfma_f32_32x32x16_bf16 v[80:95], v[128:131], v[132:135], v[80:95]
	s_waitcnt lgkmcnt(0)
	v_mfma_f32_32x32x16_bf16 v[48:63], v[144:147], v[132:135], v[48:63]
	v_mfma_f32_32x32x16_bf16 v[16:31], v[140:143], v[132:135], v[16:31]
	v_or_b32_e32 v132, 0x60, v179
	v_mfma_f32_32x32x16_bf16 v[64:79], v[128:131], v[136:139], v[64:79]
	v_add_u32_e32 v128, v152, v132
	ds_read_b128 v[128:131], v128
	v_add_u32_e32 v132, v148, v132
	ds_read_b128 v[132:135], v132
	v_mfma_f32_32x32x16_bf16 v[32:47], v[144:147], v[136:139], v[32:47]
	v_add_u32_e32 v144, 0x12060, v160
	v_mfma_f32_32x32x16_bf16 v[0:15], v[140:143], v[136:139], v[0:15]
	v_add_u32_e32 v136, 0x1c260, v170
	ds_read_b128 v[136:139], v136
	ds_read_b128 v[140:143], v144 offset:13824
	s_waitcnt lgkmcnt(2)
	v_mfma_f32_32x32x16_bf16 v[112:127], v[128:131], v[132:135], v[112:127]
	s_waitcnt lgkmcnt(1)
	v_mfma_f32_32x32x16_bf16 v[96:111], v[128:131], v[136:139], v[96:111]
	ds_read_b128 v[128:131], v144 offset:4608
	ds_read_b128 v[144:147], v144 offset:9216
	s_waitcnt lgkmcnt(0)
	s_barrier
	v_mfma_f32_32x32x16_bf16 v[80:95], v[128:131], v[132:135], v[80:95]
	v_mfma_f32_32x32x16_bf16 v[64:79], v[128:131], v[136:139], v[64:79]
	v_add_u32_e32 v128, s9, v178
	v_lshl_or_b32 v128, v177, 2, v128
	v_mfma_f32_32x32x16_bf16 v[48:63], v[144:147], v[132:135], v[48:63]
	v_mfma_f32_32x32x16_bf16 v[32:47], v[144:147], v[136:139], v[32:47]
	v_mfma_f32_32x32x16_bf16 v[16:31], v[140:143], v[132:135], v[16:31]
	v_mfma_f32_32x32x16_bf16 v[0:15], v[140:143], v[136:139], v[0:15]
	s_lshr_b32 s6, s5, 3
	s_lshl_b32 s6, s6, 8
	s_and_b32 s7, s5, 7
	s_lshl_b32 s7, s7, 8
	s_cmp_lt_u32 s6, 0x2000
	s_cbranch_scc1 .Lo0_prompt
	s_sub_u32 s10, s6, 0x2000
	s_lshr_b32 s11, s10, 12
	s_add_u32 s11, s11, 1
	v_readlane_b32 s8, v241, 21
	v_readlane_b32 s9, v241, 22
	s_branch .Lo0_join
.Lo0_prompt:
	s_mov_b32 s10, s6
	s_mov_b32 s11, 0
	v_readlane_b32 s8, v241, 19
	v_readlane_b32 s9, v241, 20
.Lo0_join:
	s_nop 0
	s_lshl_b32 s20, s6, 13
	s_add_u32 s16, s90, s20
	s_addc_u32 s17, s91, 0
	s_and_b32 s17, s17, 0xffff
	s_mov_b32 s18, 0x200000
	s_mov_b32 s19, 0x20000
	s_lshl_b32 s20, s10, 13
	s_add_u32 s12, s8, s20
	s_addc_u32 s13, s9, 0
	s_and_b32 s13, s13, 0xffff
	s_mov_b32 s14, 0x200000
	s_mov_b32 s15, 0x20000
	s_mul_i32 s11, s11, 0xc000
	s_add_u32 s22, s92, 0x5f44000
	s_addc_u32 s23, s93, 0
	s_add_u32 s22, s22, s11
	s_addc_u32 s23, s23, 0
	v_and_b32_e32 v168, 31, v190
	v_bfe_u32 v169, v190, 5, 1
	v_bfe_u32 v170, v190, 6, 2
	v_bfe_u32 v171, v190, 8, 1
	v_lshl_add_u32 v168, v170, 6, v168
	v_add_u32_e32 v168, s7, v168
	v_lshlrev_b32_e32 v168, 2, v168
	v_lshlrev_b32_e32 v171, 7, v171
	v_lshl_add_u32 v171, v169, 2, v171
	v_lshl_add_u32 v162, v171, 13, v168
	global_load_dword v166, v168, s[22:23]
	global_load_dword v167, v168, s[22:23] offset:128
	v_add_u32_e32 v163, 0x2000, v162
	v_add_u32_e32 v164, 0x4000, v162
	v_add_u32_e32 v165, 0x6000, v162
	s_mov_b32 s20, 0x0
	buffer_load_dword v129, v162, s[12:15], s20 offen
	buffer_load_dword v130, v163, s[12:15], s20 offen
	buffer_load_dword v131, v164, s[12:15], s20 offen
	buffer_load_dword v132, v165, s[12:15], s20 offen
	s_mov_b32 s20, 0x10000
	buffer_load_dword v133, v162, s[12:15], s20 offen
	buffer_load_dword v134, v163, s[12:15], s20 offen
	buffer_load_dword v135, v164, s[12:15], s20 offen
	buffer_load_dword v136, v165, s[12:15], s20 offen
	s_mov_b32 s20, 0x20000
	buffer_load_dword v137, v162, s[12:15], s20 offen
	buffer_load_dword v138, v163, s[12:15], s20 offen
	buffer_load_dword v139, v164, s[12:15], s20 offen
	buffer_load_dword v140, v165, s[12:15], s20 offen
	s_mov_b32 s20, 0x30000
	buffer_load_dword v141, v162, s[12:15], s20 offen
	buffer_load_dword v142, v163, s[12:15], s20 offen
	buffer_load_dword v143, v164, s[12:15], s20 offen
	buffer_load_dword v144, v165, s[12:15], s20 offen
	s_mov_b32 s20, 0x0
	buffer_load_dword v145, v162, s[12:15], s20 offen offset:128
	buffer_load_dword v146, v163, s[12:15], s20 offen offset:128
	buffer_load_dword v147, v164, s[12:15], s20 offen offset:128
	buffer_load_dword v148, v165, s[12:15], s20 offen offset:128
	s_mov_b32 s20, 0x10000
	buffer_load_dword v149, v162, s[12:15], s20 offen offset:128
	buffer_load_dword v150, v163, s[12:15], s20 offen offset:128
	buffer_load_dword v151, v164, s[12:15], s20 offen offset:128
	buffer_load_dword v152, v165, s[12:15], s20 offen offset:128
	s_mov_b32 s20, 0x20000
	buffer_load_dword v153, v162, s[12:15], s20 offen offset:128
	buffer_load_dword v154, v163, s[12:15], s20 offen offset:128
	buffer_load_dword v155, v164, s[12:15], s20 offen offset:128
	buffer_load_dword v156, v165, s[12:15], s20 offen offset:128
	s_mov_b32 s20, 0x30000
	buffer_load_dword v157, v162, s[12:15], s20 offen offset:128
	buffer_load_dword v158, v163, s[12:15], s20 offen offset:128
	buffer_load_dword v159, v164, s[12:15], s20 offen offset:128
	buffer_load_dword v160, v165, s[12:15], s20 offen offset:128
	s_waitcnt vmcnt(16)
	v_fmac_f32_e32 v129, v166, v112
	v_fmac_f32_e32 v130, v166, v113
	v_fmac_f32_e32 v131, v166, v114
	v_fmac_f32_e32 v132, v166, v115
	v_fmac_f32_e32 v133, v166, v116
	v_fmac_f32_e32 v134, v166, v117
	v_fmac_f32_e32 v135, v166, v118
	v_fmac_f32_e32 v136, v166, v119
	v_fmac_f32_e32 v137, v166, v120
	v_fmac_f32_e32 v138, v166, v121
	v_fmac_f32_e32 v139, v166, v122
	v_fmac_f32_e32 v140, v166, v123
	v_fmac_f32_e32 v141, v166, v124
	v_fmac_f32_e32 v142, v166, v125
	v_fmac_f32_e32 v143, v166, v126
	v_fmac_f32_e32 v144, v166, v127
	s_mov_b32 s21, 0x0
	buffer_store_dword v129, v162, s[16:19], s21 offen
	buffer_store_dword v130, v163, s[16:19], s21 offen
	buffer_store_dword v131, v164, s[16:19], s21 offen
	buffer_store_dword v132, v165, s[16:19], s21 offen
	s_mov_b32 s21, 0x10000
	buffer_store_dword v133, v162, s[16:19], s21 offen
	buffer_store_dword v134, v163, s[16:19], s21 offen
	buffer_store_dword v135, v164, s[16:19], s21 offen
	buffer_store_dword v136, v165, s[16:19], s21 offen
	s_mov_b32 s21, 0x20000
	buffer_store_dword v137, v162, s[16:19], s21 offen
	buffer_store_dword v138, v163, s[16:19], s21 offen
	buffer_store_dword v139, v164, s[16:19], s21 offen
	buffer_store_dword v140, v165, s[16:19], s21 offen
	s_mov_b32 s21, 0x30000
	buffer_store_dword v141, v162, s[16:19], s21 offen
	buffer_store_dword v142, v163, s[16:19], s21 offen
	buffer_store_dword v143, v164, s[16:19], s21 offen
	buffer_store_dword v144, v165, s[16:19], s21 offen
	s_mov_b32 s20, 0x40000
	buffer_load_dword v129, v162, s[12:15], s20 offen
	buffer_load_dword v130, v163, s[12:15], s20 offen
	buffer_load_dword v131, v164, s[12:15], s20 offen
	buffer_load_dword v132, v165, s[12:15], s20 offen
	s_mov_b32 s20, 0x50000
	buffer_load_dword v133, v162, s[12:15], s20 offen
	buffer_load_dword v134, v163, s[12:15], s20 offen
	buffer_load_dword v135, v164, s[12:15], s20 offen
	buffer_load_dword v136, v165, s[12:15], s20 offen
	s_mov_b32 s20, 0x60000
	buffer_load_dword v137, v162, s[12:15], s20 offen
	buffer_load_dword v138, v163, s[12:15], s20 offen
	buffer_load_dword v139, v164, s[12:15], s20 offen
	buffer_load_dword v140, v165, s[12:15], s20 offen
	s_mov_b32 s20, 0x70000
	buffer_load_dword v141, v162, s[12:15], s20 offen
	buffer_load_dword v142, v163, s[12:15], s20 offen
	buffer_load_dword v143, v164, s[12:15], s20 offen
	buffer_load_dword v144, v165, s[12:15], s20 offen
	s_waitcnt vmcnt(32)
	v_fmac_f32_e32 v145, v167, v96
	v_fmac_f32_e32 v146, v167, v97
	v_fmac_f32_e32 v147, v167, v98
	v_fmac_f32_e32 v148, v167, v99
	v_fmac_f32_e32 v149, v167, v100
	v_fmac_f32_e32 v150, v167, v101
	v_fmac_f32_e32 v151, v167, v102
	v_fmac_f32_e32 v152, v167, v103
	v_fmac_f32_e32 v153, v167, v104
	v_fmac_f32_e32 v154, v167, v105
	v_fmac_f32_e32 v155, v167, v106
	v_fmac_f32_e32 v156, v167, v107
	v_fmac_f32_e32 v157, v167, v108
	v_fmac_f32_e32 v158, v167, v109
	v_fmac_f32_e32 v159, v167, v110
	v_fmac_f32_e32 v160, v167, v111
	s_mov_b32 s21, 0x0
	buffer_store_dword v145, v162, s[16:19], s21 offen offset:128
	buffer_store_dword v146, v163, s[16:19], s21 offen offset:128
	buffer_store_dword v147, v164, s[16:19], s21 offen offset:128
	buffer_store_dword v148, v165, s[16:19], s21 offen offset:128
	s_mov_b32 s21, 0x10000
	buffer_store_dword v149, v162, s[16:19], s21 offen offset:128
	buffer_store_dword v150, v163, s[16:19], s21 offen offset:128
	buffer_store_dword v151, v164, s[16:19], s21 offen offset:128
	buffer_store_dword v152, v165, s[16:19], s21 offen offset:128
	s_mov_b32 s21, 0x20000
	buffer_store_dword v153, v162, s[16:19], s21 offen offset:128
	buffer_store_dword v154, v163, s[16:19], s21 offen offset:128
	buffer_store_dword v155, v164, s[16:19], s21 offen offset:128
	buffer_store_dword v156, v165, s[16:19], s21 offen offset:128
	s_mov_b32 s21, 0x30000
	buffer_store_dword v157, v162, s[16:19], s21 offen offset:128
	buffer_store_dword v158, v163, s[16:19], s21 offen offset:128
	buffer_store_dword v159, v164, s[16:19], s21 offen offset:128
	buffer_store_dword v160, v165, s[16:19], s21 offen offset:128
	s_mov_b32 s20, 0x40000
	buffer_load_dword v145, v162, s[12:15], s20 offen offset:128
	buffer_load_dword v146, v163, s[12:15], s20 offen offset:128
	buffer_load_dword v147, v164, s[12:15], s20 offen offset:128
	buffer_load_dword v148, v165, s[12:15], s20 offen offset:128
	s_mov_b32 s20, 0x50000
	buffer_load_dword v149, v162, s[12:15], s20 offen offset:128
	buffer_load_dword v150, v163, s[12:15], s20 offen offset:128
	buffer_load_dword v151, v164, s[12:15], s20 offen offset:128
	buffer_load_dword v152, v165, s[12:15], s20 offen offset:128
	s_mov_b32 s20, 0x60000
	buffer_load_dword v153, v162, s[12:15], s20 offen offset:128
	buffer_load_dword v154, v163, s[12:15], s20 offen offset:128
	buffer_load_dword v155, v164, s[12:15], s20 offen offset:128
	buffer_load_dword v156, v165, s[12:15], s20 offen offset:128
	s_mov_b32 s20, 0x70000
	buffer_load_dword v157, v162, s[12:15], s20 offen offset:128
	buffer_load_dword v158, v163, s[12:15], s20 offen offset:128
	buffer_load_dword v159, v164, s[12:15], s20 offen offset:128
	buffer_load_dword v160, v165, s[12:15], s20 offen offset:128
	s_waitcnt vmcnt(32)
	v_fmac_f32_e32 v129, v166, v80
	v_fmac_f32_e32 v130, v166, v81
	v_fmac_f32_e32 v131, v166, v82
	v_fmac_f32_e32 v132, v166, v83
	v_fmac_f32_e32 v133, v166, v84
	v_fmac_f32_e32 v134, v166, v85
	v_fmac_f32_e32 v135, v166, v86
	v_fmac_f32_e32 v136, v166, v87
	v_fmac_f32_e32 v137, v166, v88
	v_fmac_f32_e32 v138, v166, v89
	v_fmac_f32_e32 v139, v166, v90
	v_fmac_f32_e32 v140, v166, v91
	v_fmac_f32_e32 v141, v166, v92
	v_fmac_f32_e32 v142, v166, v93
	v_fmac_f32_e32 v143, v166, v94
	v_fmac_f32_e32 v144, v166, v95
	s_mov_b32 s21, 0x40000
	buffer_store_dword v129, v162, s[16:19], s21 offen
	buffer_store_dword v130, v163, s[16:19], s21 offen
	buffer_store_dword v131, v164, s[16:19], s21 offen
	buffer_store_dword v132, v165, s[16:19], s21 offen
	s_mov_b32 s21, 0x50000
	buffer_store_dword v133, v162, s[16:19], s21 offen
	buffer_store_dword v134, v163, s[16:19], s21 offen
	buffer_store_dword v135, v164, s[16:19], s21 offen
	buffer_store_dword v136, v165, s[16:19], s21 offen
	s_mov_b32 s21, 0x60000
	buffer_store_dword v137, v162, s[16:19], s21 offen
	buffer_store_dword v138, v163, s[16:19], s21 offen
	buffer_store_dword v139, v164, s[16:19], s21 offen
	buffer_store_dword v140, v165, s[16:19], s21 offen
	s_mov_b32 s21, 0x70000
	buffer_store_dword v141, v162, s[16:19], s21 offen
	buffer_store_dword v142, v163, s[16:19], s21 offen
	buffer_store_dword v143, v164, s[16:19], s21 offen
	buffer_store_dword v144, v165, s[16:19], s21 offen
	s_mov_b32 s20, 0x80000
	buffer_load_dword v129, v162, s[12:15], s20 offen
	buffer_load_dword v130, v163, s[12:15], s20 offen
	buffer_load_dword v131, v164, s[12:15], s20 offen
	buffer_load_dword v132, v165, s[12:15], s20 offen
	s_mov_b32 s20, 0x90000
	buffer_load_dword v133, v162, s[12:15], s20 offen
	buffer_load_dword v134, v163, s[12:15], s20 offen
	buffer_load_dword v135, v164, s[12:15], s20 offen
	buffer_load_dword v136, v165, s[12:15], s20 offen
	s_mov_b32 s20, 0xa0000
	buffer_load_dword v137, v162, s[12:15], s20 offen
	buffer_load_dword v138, v163, s[12:15], s20 offen
	buffer_load_dword v139, v164, s[12:15], s20 offen
	buffer_load_dword v140, v165, s[12:15], s20 offen
	s_mov_b32 s20, 0xb0000
	buffer_load_dword v141, v162, s[12:15], s20 offen
	buffer_load_dword v142, v163, s[12:15], s20 offen
	buffer_load_dword v143, v164, s[12:15], s20 offen
	buffer_load_dword v144, v165, s[12:15], s20 offen
	s_waitcnt vmcnt(32)
	v_fmac_f32_e32 v145, v167, v64
	v_fmac_f32_e32 v146, v167, v65
	v_fmac_f32_e32 v147, v167, v66
	v_fmac_f32_e32 v148, v167, v67
	v_fmac_f32_e32 v149, v167, v68
	v_fmac_f32_e32 v150, v167, v69
	v_fmac_f32_e32 v151, v167, v70
	v_fmac_f32_e32 v152, v167, v71
	v_fmac_f32_e32 v153, v167, v72
	v_fmac_f32_e32 v154, v167, v73
	v_fmac_f32_e32 v155, v167, v74
	v_fmac_f32_e32 v156, v167, v75
	v_fmac_f32_e32 v157, v167, v76
	v_fmac_f32_e32 v158, v167, v77
	v_fmac_f32_e32 v159, v167, v78
	v_fmac_f32_e32 v160, v167, v79
	s_mov_b32 s21, 0x40000
	buffer_store_dword v145, v162, s[16:19], s21 offen offset:128
	buffer_store_dword v146, v163, s[16:19], s21 offen offset:128
	buffer_store_dword v147, v164, s[16:19], s21 offen offset:128
	buffer_store_dword v148, v165, s[16:19], s21 offen offset:128
	s_mov_b32 s21, 0x50000
	buffer_store_dword v149, v162, s[16:19], s21 offen offset:128
	buffer_store_dword v150, v163, s[16:19], s21 offen offset:128
	buffer_store_dword v151, v164, s[16:19], s21 offen offset:128
	buffer_store_dword v152, v165, s[16:19], s21 offen offset:128
	s_mov_b32 s21, 0x60000
	buffer_store_dword v153, v162, s[16:19], s21 offen offset:128
	buffer_store_dword v154, v163, s[16:19], s21 offen offset:128
	buffer_store_dword v155, v164, s[16:19], s21 offen offset:128
	buffer_store_dword v156, v165, s[16:19], s21 offen offset:128
	s_mov_b32 s21, 0x70000
	buffer_store_dword v157, v162, s[16:19], s21 offen offset:128
	buffer_store_dword v158, v163, s[16:19], s21 offen offset:128
	buffer_store_dword v159, v164, s[16:19], s21 offen offset:128
	buffer_store_dword v160, v165, s[16:19], s21 offen offset:128
	s_mov_b32 s20, 0x80000
	buffer_load_dword v145, v162, s[12:15], s20 offen offset:128
	buffer_load_dword v146, v163, s[12:15], s20 offen offset:128
	buffer_load_dword v147, v164, s[12:15], s20 offen offset:128
	buffer_load_dword v148, v165, s[12:15], s20 offen offset:128
	s_mov_b32 s20, 0x90000
	buffer_load_dword v149, v162, s[12:15], s20 offen offset:128
	buffer_load_dword v150, v163, s[12:15], s20 offen offset:128
	buffer_load_dword v151, v164, s[12:15], s20 offen offset:128
	buffer_load_dword v152, v165, s[12:15], s20 offen offset:128
	s_mov_b32 s20, 0xa0000
	buffer_load_dword v153, v162, s[12:15], s20 offen offset:128
	buffer_load_dword v154, v163, s[12:15], s20 offen offset:128
	buffer_load_dword v155, v164, s[12:15], s20 offen offset:128
	buffer_load_dword v156, v165, s[12:15], s20 offen offset:128
	s_mov_b32 s20, 0xb0000
	buffer_load_dword v157, v162, s[12:15], s20 offen offset:128
	buffer_load_dword v158, v163, s[12:15], s20 offen offset:128
	buffer_load_dword v159, v164, s[12:15], s20 offen offset:128
	buffer_load_dword v160, v165, s[12:15], s20 offen offset:128
	s_waitcnt vmcnt(32)
	v_fmac_f32_e32 v129, v166, v48
	v_fmac_f32_e32 v130, v166, v49
	v_fmac_f32_e32 v131, v166, v50
	v_fmac_f32_e32 v132, v166, v51
	v_fmac_f32_e32 v133, v166, v52
	v_fmac_f32_e32 v134, v166, v53
	v_fmac_f32_e32 v135, v166, v54
	v_fmac_f32_e32 v136, v166, v55
	v_fmac_f32_e32 v137, v166, v56
	v_fmac_f32_e32 v138, v166, v57
	v_fmac_f32_e32 v139, v166, v58
	v_fmac_f32_e32 v140, v166, v59
	v_fmac_f32_e32 v141, v166, v60
	v_fmac_f32_e32 v142, v166, v61
	v_fmac_f32_e32 v143, v166, v62
	v_fmac_f32_e32 v144, v166, v63
	s_mov_b32 s21, 0x80000
	buffer_store_dword v129, v162, s[16:19], s21 offen
	buffer_store_dword v130, v163, s[16:19], s21 offen
	buffer_store_dword v131, v164, s[16:19], s21 offen
	buffer_store_dword v132, v165, s[16:19], s21 offen
	s_mov_b32 s21, 0x90000
	buffer_store_dword v133, v162, s[16:19], s21 offen
	buffer_store_dword v134, v163, s[16:19], s21 offen
	buffer_store_dword v135, v164, s[16:19], s21 offen
	buffer_store_dword v136, v165, s[16:19], s21 offen
	s_mov_b32 s21, 0xa0000
	buffer_store_dword v137, v162, s[16:19], s21 offen
	buffer_store_dword v138, v163, s[16:19], s21 offen
	buffer_store_dword v139, v164, s[16:19], s21 offen
	buffer_store_dword v140, v165, s[16:19], s21 offen
	s_mov_b32 s21, 0xb0000
	buffer_store_dword v141, v162, s[16:19], s21 offen
	buffer_store_dword v142, v163, s[16:19], s21 offen
	buffer_store_dword v143, v164, s[16:19], s21 offen
	buffer_store_dword v144, v165, s[16:19], s21 offen
	s_mov_b32 s20, 0xc0000
	buffer_load_dword v129, v162, s[12:15], s20 offen
	buffer_load_dword v130, v163, s[12:15], s20 offen
	buffer_load_dword v131, v164, s[12:15], s20 offen
	buffer_load_dword v132, v165, s[12:15], s20 offen
	s_mov_b32 s20, 0xd0000
	buffer_load_dword v133, v162, s[12:15], s20 offen
	buffer_load_dword v134, v163, s[12:15], s20 offen
	buffer_load_dword v135, v164, s[12:15], s20 offen
	buffer_load_dword v136, v165, s[12:15], s20 offen
	s_mov_b32 s20, 0xe0000
	buffer_load_dword v137, v162, s[12:15], s20 offen
	buffer_load_dword v138, v163, s[12:15], s20 offen
	buffer_load_dword v139, v164, s[12:15], s20 offen
	buffer_load_dword v140, v165, s[12:15], s20 offen
	s_mov_b32 s20, 0xf0000
	buffer_load_dword v141, v162, s[12:15], s20 offen
	buffer_load_dword v142, v163, s[12:15], s20 offen
	buffer_load_dword v143, v164, s[12:15], s20 offen
	buffer_load_dword v144, v165, s[12:15], s20 offen
	s_waitcnt vmcnt(32)
	v_fmac_f32_e32 v145, v167, v32
	v_fmac_f32_e32 v146, v167, v33
	v_fmac_f32_e32 v147, v167, v34
	v_fmac_f32_e32 v148, v167, v35
	v_fmac_f32_e32 v149, v167, v36
	v_fmac_f32_e32 v150, v167, v37
	v_fmac_f32_e32 v151, v167, v38
	v_fmac_f32_e32 v152, v167, v39
	v_fmac_f32_e32 v153, v167, v40
	v_fmac_f32_e32 v154, v167, v41
	v_fmac_f32_e32 v155, v167, v42
	v_fmac_f32_e32 v156, v167, v43
	v_fmac_f32_e32 v157, v167, v44
	v_fmac_f32_e32 v158, v167, v45
	v_fmac_f32_e32 v159, v167, v46
	v_fmac_f32_e32 v160, v167, v47
	s_mov_b32 s21, 0x80000
	buffer_store_dword v145, v162, s[16:19], s21 offen offset:128
	buffer_store_dword v146, v163, s[16:19], s21 offen offset:128
	buffer_store_dword v147, v164, s[16:19], s21 offen offset:128
	buffer_store_dword v148, v165, s[16:19], s21 offen offset:128
	s_mov_b32 s21, 0x90000
	buffer_store_dword v149, v162, s[16:19], s21 offen offset:128
	buffer_store_dword v150, v163, s[16:19], s21 offen offset:128
	buffer_store_dword v151, v164, s[16:19], s21 offen offset:128
	buffer_store_dword v152, v165, s[16:19], s21 offen offset:128
	s_mov_b32 s21, 0xa0000
	buffer_store_dword v153, v162, s[16:19], s21 offen offset:128
	buffer_store_dword v154, v163, s[16:19], s21 offen offset:128
	buffer_store_dword v155, v164, s[16:19], s21 offen offset:128
	buffer_store_dword v156, v165, s[16:19], s21 offen offset:128
	s_mov_b32 s21, 0xb0000
	buffer_store_dword v157, v162, s[16:19], s21 offen offset:128
	buffer_store_dword v158, v163, s[16:19], s21 offen offset:128
	buffer_store_dword v159, v164, s[16:19], s21 offen offset:128
	buffer_store_dword v160, v165, s[16:19], s21 offen offset:128
	s_mov_b32 s20, 0xc0000
	buffer_load_dword v145, v162, s[12:15], s20 offen offset:128
	buffer_load_dword v146, v163, s[12:15], s20 offen offset:128
	buffer_load_dword v147, v164, s[12:15], s20 offen offset:128
	buffer_load_dword v148, v165, s[12:15], s20 offen offset:128
	s_mov_b32 s20, 0xd0000
	buffer_load_dword v149, v162, s[12:15], s20 offen offset:128
	buffer_load_dword v150, v163, s[12:15], s20 offen offset:128
	buffer_load_dword v151, v164, s[12:15], s20 offen offset:128
	buffer_load_dword v152, v165, s[12:15], s20 offen offset:128
	s_mov_b32 s20, 0xe0000
	buffer_load_dword v153, v162, s[12:15], s20 offen offset:128
	buffer_load_dword v154, v163, s[12:15], s20 offen offset:128
	buffer_load_dword v155, v164, s[12:15], s20 offen offset:128
	buffer_load_dword v156, v165, s[12:15], s20 offen offset:128
	s_mov_b32 s20, 0xf0000
	buffer_load_dword v157, v162, s[12:15], s20 offen offset:128
	buffer_load_dword v158, v163, s[12:15], s20 offen offset:128
	buffer_load_dword v159, v164, s[12:15], s20 offen offset:128
	buffer_load_dword v160, v165, s[12:15], s20 offen offset:128
	s_waitcnt vmcnt(32)
	v_fmac_f32_e32 v129, v166, v16
	v_fmac_f32_e32 v130, v166, v17
	v_fmac_f32_e32 v131, v166, v18
	v_fmac_f32_e32 v132, v166, v19
	v_fmac_f32_e32 v133, v166, v20
	v_fmac_f32_e32 v134, v166, v21
	v_fmac_f32_e32 v135, v166, v22
	v_fmac_f32_e32 v136, v166, v23
	v_fmac_f32_e32 v137, v166, v24
	v_fmac_f32_e32 v138, v166, v25
	v_fmac_f32_e32 v139, v166, v26
	v_fmac_f32_e32 v140, v166, v27
	v_fmac_f32_e32 v141, v166, v28
	v_fmac_f32_e32 v142, v166, v29
	v_fmac_f32_e32 v143, v166, v30
	v_fmac_f32_e32 v144, v166, v31
	s_mov_b32 s21, 0xc0000
	buffer_store_dword v129, v162, s[16:19], s21 offen
	buffer_store_dword v130, v163, s[16:19], s21 offen
	buffer_store_dword v131, v164, s[16:19], s21 offen
	buffer_store_dword v132, v165, s[16:19], s21 offen
	s_mov_b32 s21, 0xd0000
	buffer_store_dword v133, v162, s[16:19], s21 offen
	buffer_store_dword v134, v163, s[16:19], s21 offen
	buffer_store_dword v135, v164, s[16:19], s21 offen
	buffer_store_dword v136, v165, s[16:19], s21 offen
	s_mov_b32 s21, 0xe0000
	buffer_store_dword v137, v162, s[16:19], s21 offen
	buffer_store_dword v138, v163, s[16:19], s21 offen
	buffer_store_dword v139, v164, s[16:19], s21 offen
	buffer_store_dword v140, v165, s[16:19], s21 offen
	s_mov_b32 s21, 0xf0000
	buffer_store_dword v141, v162, s[16:19], s21 offen
	buffer_store_dword v142, v163, s[16:19], s21 offen
	buffer_store_dword v143, v164, s[16:19], s21 offen
	buffer_store_dword v144, v165, s[16:19], s21 offen
	s_waitcnt vmcnt(16)
	v_fmac_f32_e32 v145, v167, v0
	v_fmac_f32_e32 v146, v167, v1
	v_fmac_f32_e32 v147, v167, v2
	v_fmac_f32_e32 v148, v167, v3
	v_fmac_f32_e32 v149, v167, v4
	v_fmac_f32_e32 v150, v167, v5
	v_fmac_f32_e32 v151, v167, v6
	v_fmac_f32_e32 v152, v167, v7
	v_fmac_f32_e32 v153, v167, v8
	v_fmac_f32_e32 v154, v167, v9
	v_fmac_f32_e32 v155, v167, v10
	v_fmac_f32_e32 v156, v167, v11
	v_fmac_f32_e32 v157, v167, v12
	v_fmac_f32_e32 v158, v167, v13
	v_fmac_f32_e32 v159, v167, v14
	v_fmac_f32_e32 v160, v167, v15
	s_mov_b32 s21, 0xc0000
	buffer_store_dword v145, v162, s[16:19], s21 offen offset:128
	buffer_store_dword v146, v163, s[16:19], s21 offen offset:128
	buffer_store_dword v147, v164, s[16:19], s21 offen offset:128
	buffer_store_dword v148, v165, s[16:19], s21 offen offset:128
	s_mov_b32 s21, 0xd0000
	buffer_store_dword v149, v162, s[16:19], s21 offen offset:128
	buffer_store_dword v150, v163, s[16:19], s21 offen offset:128
	buffer_store_dword v151, v164, s[16:19], s21 offen offset:128
	buffer_store_dword v152, v165, s[16:19], s21 offen offset:128
	s_mov_b32 s21, 0xe0000
	buffer_store_dword v153, v162, s[16:19], s21 offen offset:128
	buffer_store_dword v154, v163, s[16:19], s21 offen offset:128
	buffer_store_dword v155, v164, s[16:19], s21 offen offset:128
	buffer_store_dword v156, v165, s[16:19], s21 offen offset:128
	s_mov_b32 s21, 0xf0000
	buffer_store_dword v157, v162, s[16:19], s21 offen offset:128
	buffer_store_dword v158, v163, s[16:19], s21 offen offset:128
	buffer_store_dword v159, v164, s[16:19], s21 offen offset:128
	buffer_store_dword v160, v165, s[16:19], s21 offen offset:128
	s_add_i32 s5, s5, s94
	s_cmpk_lt_i32 s5, 0x200
	s_cbranch_scc1 .LBB0_786
	s_branch .LBB0_1300

.LBB0_2001:
	s_or_b64 exec, exec, s[0:1]
	v_readlane_b32 s0, v240, 19
	v_readlane_b32 s1, v240, 20
	s_and_b64 vcc, exec, s[0:1]
	s_waitcnt lgkmcnt(0)
	s_barrier
	s_cbranch_vccnz .LBB0_2519
	s_add_u32 s0, s92, 0x5f68000
	s_addc_u32 s1, s93, 0
	s_add_u32 s76, s92, 0x3380000
	s_addc_u32 s77, s93, 0
	s_add_u32 s4, s92, 0x3440100
	s_addc_u32 s5, s93, 0
	s_add_u32 s70, s92, 0x3400100
	s_addc_u32 s71, s93, 0
	s_add_u32 s80, s92, 0x33c0100
	s_addc_u32 s81, s93, 0
	s_add_u32 s82, s92, 0x3380100
	v_readlane_b32 s6, v240, 10
	s_addc_u32 s83, s93, 0
	v_mov_b32_e32 v161, 0
	s_mov_b32 s2, 0x40000
	s_mov_b32 s3, 0xc0000
	s_movk_i32 s33, 0x90
	v_mov_b32_e32 v172, 0x73f
	v_mov_b32_e32 v173, 0x77f
	v_mov_b32_e32 v174, 0x7bf
	s_movk_i32 s74, 0x2000
	s_movk_i32 s75, 0x1fff
	s_movk_i32 s78, 0x3000
	s_mov_b32 s79, s6
	v_readlane_b32 s7, v240, 11
	s_branch .LBB0_2004
.LBB0_2004:
	s_ashr_i32 s6, s79, 31
	s_lshr_b32 s6, s6, 29
	s_add_i32 s6, s79, s6
	s_lshl_b32 s7, s6, 5
	s_and_b32 s6, s6, 0xfffff8
	s_sub_i32 s6, s79, s6
	v_mov_b32_e32 v175, v190
	s_lshl_b32 s8, s6, 8
	s_and_b32 s9, s7, 0xffffff00
	v_ashrrev_i32_e32 v35, 3, v175
	v_add_u32_e32 v34, s8, v35
	v_add_u32_e32 v0, s9, v35
	v_min_i32_e32 v2, 0x7ff, v34
	v_ashrrev_i32_e32 v1, 31, v0
	v_ashrrev_i32_e32 v3, 31, v2
	v_lshlrev_b64 v[32:33], 12, v[0:1]
	v_lshlrev_b32_e32 v0, 4, v175
	v_lshlrev_b64 v[36:37], 12, v[2:3]
	v_min_i32_e32 v2, 0x7bf, v34
	v_and_b32_e32 v160, 0x70, v0
	v_ashrrev_i32_e32 v3, 31, v2
	v_lshl_add_u64 v[0:1], s[76:77], 0, v[160:161]
	v_lshlrev_b64 v[2:3], 12, v[2:3]
	v_lshl_add_u64 v[40:41], v[0:1], 0, v[2:3]
	v_min_i32_e32 v2, 0x77f, v34
	v_ashrrev_i32_e32 v3, 31, v2
	v_lshlrev_b64 v[2:3], 12, v[2:3]
	v_lshl_add_u64 v[42:43], v[0:1], 0, v[2:3]
	v_min_i32_e32 v2, 0x73f, v34
	v_ashrrev_i32_e32 v3, 31, v2
	v_readlane_b32 s6, v240, 6
	v_lshlrev_b64 v[2:3], 12, v[2:3]
	v_readlane_b32 s7, v240, 7
	v_lshl_add_u64 v[38:39], v[0:1], 0, v[36:37]
	v_lshl_add_u64 v[44:45], v[0:1], 0, v[2:3]
	v_lshl_add_u64 v[0:1], s[6:7], 0, v[32:33]
	v_lshl_add_u64 v[46:47], v[0:1], 0, v[160:161]
	v_add_co_u32_e32 v48, vcc, s2, v46
	s_mov_b32 s6, 0x80000
	s_nop 0
	v_addc_co_u32_e32 v49, vcc, 0, v47, vcc
	v_add_co_u32_e32 v50, vcc, s6, v46
	s_nop 1
	v_addc_co_u32_e32 v51, vcc, 0, v47, vcc
	v_add_co_u32_e32 v52, vcc, s3, v46
	s_barrier
	s_nop 0
	v_addc_co_u32_e32 v53, vcc, 0, v47, vcc
	v_add_co_u32_e32 v20, vcc, s2, v40
	s_nop 1
	v_addc_co_u32_e32 v21, vcc, 0, v41, vcc
	v_add_co_u32_e32 v24, vcc, s6, v42
	global_load_dwordx4 v[0:3], v[46:47], off
	global_load_dwordx4 v[4:7], v[48:49], off
	v_addc_co_u32_e32 v25, vcc, 0, v43, vcc
	v_add_co_u32_e32 v28, vcc, s3, v44
	global_load_dwordx4 v[8:11], v[50:51], off
	s_nop 0
	v_addc_co_u32_e32 v29, vcc, 0, v45, vcc
	global_load_dwordx4 v[12:15], v[52:53], off
	global_load_dwordx4 v[16:19], v[38:39], off
	s_mov_b64 s[12:13], 0xc0000
	global_load_dwordx4 v[20:23], v[20:21], off
	s_nop 0
	global_load_dwordx4 v[24:27], v[24:25], off
	s_nop 0
	global_load_dwordx4 v[28:31], v[28:29], off
	v_lshl_add_u64 v[44:45], v[44:45], 0, s[12:13]
	global_load_dwordx4 v[140:143], v[46:47], off offset:128
	global_load_dwordx4 v[136:139], v[48:49], off offset:128
	global_load_dwordx4 v[132:135], v[50:51], off offset:128
	global_load_dwordx4 v[128:131], v[38:39], off offset:128
	global_load_dwordx4 v[144:147], v[52:53], off offset:128
	global_load_dwordx4 v[148:151], v[44:45], off offset:128
	v_mul_lo_u32 v35, v35, s33
	s_mov_b64 s[6:7], 0x40000
	v_add_u32_e32 v182, v35, v160
	s_mov_b64 s[10:11], 0x80000
	v_lshl_add_u64 v[40:41], v[40:41], 0, s[6:7]
	v_lshl_add_u64 v[42:43], v[42:43], 0, s[10:11]
	v_and_b32_e32 v176, 31, v175
	v_ashrrev_i32_e32 v35, 31, v34
	s_mov_b64 s[6:7], 0x73f
	v_cmp_gt_i64_e32 vcc, s[6:7], v[34:35]
	s_mov_b64 s[6:7], 0x77f
	v_bfe_u32 v177, v175, 5, 1
	v_or_b32_e32 v36, v36, v160
	v_or_b32_e32 v32, v32, v160
	s_waitcnt vmcnt(20)
	v_lshlrev_b32_e32 v179, 4, v177
	v_lshl_add_u64 v[168:169], s[82:83], 0, v[36:37]
	v_lshl_add_u64 v[170:171], s[92:93], 0, v[32:33]
	s_mov_b32 s10, 0
	v_mov_b32_e32 v64, 0
	v_mov_b32_e32 v65, v161
	v_mov_b32_e32 v66, v161
	v_mov_b32_e32 v67, v161
	v_mov_b32_e32 v68, v161
	v_mov_b32_e32 v69, v161
	v_mov_b32_e32 v70, v161
	v_mov_b32_e32 v71, v161
	v_mov_b32_e32 v72, v161
	v_mov_b32_e32 v73, v161
	v_mov_b32_e32 v74, v161
	v_mov_b32_e32 v75, v161
	v_mov_b32_e32 v76, v161
	v_mov_b32_e32 v77, v161
	v_mov_b32_e32 v78, v161
	v_mov_b32_e32 v79, v161
	v_mov_b32_e32 v80, 0
	v_mov_b32_e32 v81, v161
	v_mov_b32_e32 v82, v161
	s_waitcnt vmcnt(13)
	ds_write_b128 v182, v[0:3]
	s_waitcnt vmcnt(12)
	ds_write_b128 v182, v[4:7] offset:9216
	s_waitcnt vmcnt(11)
	ds_write_b128 v182, v[8:11] offset:18432
	s_waitcnt vmcnt(10)
	ds_write_b128 v182, v[12:15] offset:27648
	s_waitcnt vmcnt(9)
	ds_write_b128 v182, v[16:19] offset:36864
	s_waitcnt vmcnt(8)
	ds_write_b128 v182, v[20:23] offset:46080
	s_waitcnt vmcnt(7)
	ds_write_b128 v182, v[24:27] offset:55296
	s_waitcnt vmcnt(6)
	ds_write_b128 v182, v[28:31] offset:64512
	global_load_dwordx4 v[152:155], v[40:41], off offset:128
	global_load_dwordx4 v[156:159], v[42:43], off offset:128
	v_ashrrev_i32_e32 v0, 1, v175
	v_and_b32_e32 v178, 0xffffff80, v0
	v_or_b32_e32 v0, v178, v176
	v_mul_lo_u32 v181, v0, s33
	v_and_b32_e32 v0, 0xdf, v175
	v_mul_u32_u24_e32 v180, 0x90, v0
	v_cndmask_b32_e32 v1, 0, v35, vcc
	v_cndmask_b32_e32 v0, v172, v34, vcc
	v_lshlrev_b64 v[0:1], 12, v[0:1]
	v_or_b32_e32 v0, v0, v160
	v_cmp_gt_i64_e32 vcc, s[6:7], v[34:35]
	v_lshl_add_u64 v[162:163], s[4:5], 0, v[0:1]
	s_mov_b64 s[6:7], 0x7bf
	v_cndmask_b32_e32 v1, 0, v35, vcc
	v_cndmask_b32_e32 v0, v173, v34, vcc
	v_lshlrev_b64 v[0:1], 12, v[0:1]
	v_or_b32_e32 v0, v0, v160
	v_cmp_gt_i64_e32 vcc, s[6:7], v[34:35]
	v_lshl_add_u64 v[164:165], s[70:71], 0, v[0:1]
	s_mov_b64 s[6:7], 0
	v_cndmask_b32_e32 v1, 0, v35, vcc
	v_cndmask_b32_e32 v0, v174, v34, vcc
	v_lshlrev_b64 v[0:1], 12, v[0:1]
	v_or_b32_e32 v0, v0, v160
	v_lshl_add_u64 v[166:167], s[80:81], 0, v[0:1]
	v_mov_b32_e32 v83, v161
	v_mov_b32_e32 v84, v161
	v_mov_b32_e32 v85, v161
	v_mov_b32_e32 v86, v161
	v_mov_b32_e32 v87, v161
	v_mov_b32_e32 v88, v161
	v_mov_b32_e32 v89, v161
	v_mov_b32_e32 v90, v161
	v_mov_b32_e32 v91, v161
	v_mov_b32_e32 v92, v161
	v_mov_b32_e32 v93, v161
	v_mov_b32_e32 v94, v161
	v_mov_b32_e32 v95, v161
	v_mov_b32_e32 v96, 0
	v_mov_b32_e32 v97, v161
	v_mov_b32_e32 v98, v161
	v_mov_b32_e32 v99, v161
	v_mov_b32_e32 v100, v161
	v_mov_b32_e32 v101, v161
	v_mov_b32_e32 v102, v161
	v_mov_b32_e32 v103, v161
	v_mov_b32_e32 v104, v161
	v_mov_b32_e32 v105, v161
	v_mov_b32_e32 v106, v161
	v_mov_b32_e32 v107, v161
	v_mov_b32_e32 v108, v161
	v_mov_b32_e32 v109, v161
	v_mov_b32_e32 v110, v161
	v_mov_b32_e32 v111, v161
	v_mov_b32_e32 v112, 0
	v_mov_b32_e32 v113, v161
	v_mov_b32_e32 v114, v161
	v_mov_b32_e32 v115, v161
	v_mov_b32_e32 v116, v161
	v_mov_b32_e32 v117, v161
	v_mov_b32_e32 v118, v161
	v_mov_b32_e32 v119, v161
	v_mov_b32_e32 v120, v161
	v_mov_b32_e32 v121, v161
	v_mov_b32_e32 v122, v161
	v_mov_b32_e32 v123, v161
	v_mov_b32_e32 v124, v161
	v_mov_b32_e32 v125, v161
	v_mov_b32_e32 v126, v161
	v_mov_b32_e32 v127, v161
	v_mov_b32_e32 v48, 0
	v_mov_b32_e32 v49, v161
	v_mov_b32_e32 v50, v161
	v_mov_b32_e32 v51, v161
	v_mov_b32_e32 v52, v161
	v_mov_b32_e32 v53, v161
	v_mov_b32_e32 v54, v161
	v_mov_b32_e32 v55, v161
	v_mov_b32_e32 v56, v161
	v_mov_b32_e32 v57, v161
	v_mov_b32_e32 v58, v161
	v_mov_b32_e32 v59, v161
	v_mov_b32_e32 v60, v161
	v_mov_b32_e32 v61, v161
	v_mov_b32_e32 v62, v161
	v_mov_b32_e32 v63, v161
	v_mov_b32_e32 v32, 0
	v_mov_b32_e32 v33, v161
	v_mov_b32_e32 v34, v161
	v_mov_b32_e32 v35, v161
	v_mov_b32_e32 v36, v161
	v_mov_b32_e32 v37, v161
	v_mov_b32_e32 v38, v161
	v_mov_b32_e32 v39, v161
	v_mov_b32_e32 v40, v161
	v_mov_b32_e32 v41, v161
	v_mov_b32_e32 v42, v161
	v_mov_b32_e32 v43, v161
	v_mov_b32_e32 v44, v161
	v_mov_b32_e32 v45, v161
	v_mov_b32_e32 v46, v161
	v_mov_b32_e32 v47, v161
	v_mov_b32_e32 v16, 0
	v_mov_b32_e32 v17, v161
	v_mov_b32_e32 v18, v161
	v_mov_b32_e32 v19, v161
	v_mov_b32_e32 v20, v161
	v_mov_b32_e32 v21, v161
	v_mov_b32_e32 v22, v161
	v_mov_b32_e32 v23, v161
	v_mov_b32_e32 v24, v161
	v_mov_b32_e32 v25, v161
	v_mov_b32_e32 v26, v161
	v_mov_b32_e32 v27, v161
	v_mov_b32_e32 v28, v161
	v_mov_b32_e32 v29, v161
	v_mov_b32_e32 v30, v161
	v_mov_b32_e32 v31, v161
	v_mov_b32_e32 v0, 0
	v_mov_b32_e32 v1, v161
	v_mov_b32_e32 v2, v161
	v_mov_b32_e32 v3, v161
	v_mov_b32_e32 v4, v161
	v_mov_b32_e32 v5, v161
	v_mov_b32_e32 v6, v161
	v_mov_b32_e32 v7, v161
	v_mov_b32_e32 v8, v161
	v_mov_b32_e32 v9, v161
	v_mov_b32_e32 v10, v161
	v_mov_b32_e32 v11, v161
	v_mov_b32_e32 v12, v161
	v_mov_b32_e32 v13, v161
	v_mov_b32_e32 v14, v161
	v_mov_b32_e32 v15, v161
	s_waitcnt lgkmcnt(0)
	s_barrier
.LBB0_2005:
	s_and_b32 s11, s10, 1
	s_mul_i32 s12, s11, 0x12000
	v_or_b32_e32 v160, s12, v179
	v_add_u32_e32 v183, v160, v181
	v_add_u32_e32 v160, v160, v180
	ds_read_b128 v[184:187], v183
	ds_read_b128 v[192:195], v160 offset:36864
	ds_read_b128 v[196:199], v183 offset:32
	ds_read_b128 v[200:203], v160 offset:36896
	ds_read_b128 v[204:207], v160 offset:41472
	ds_read_b128 v[208:211], v160 offset:41504
	s_waitcnt lgkmcnt(4)
	v_mfma_f32_32x32x16_bf16 v[112:127], v[184:187], v[192:195], v[112:127]
	s_xor_b32 s11, s11, 1
	s_mul_i32 s11, s11, 0x12000
	s_mov_b32 s12, 0x6264000
	s_mov_b32 s13, 0x62a4000
	s_mov_b32 s14, 0x62e4000
	v_lshl_add_u64 v[188:189], v[162:163], 0, s[6:7]
	s_add_i32 s10, s10, 1
	s_waitcnt lgkmcnt(1)
	v_mfma_f32_32x32x16_bf16 v[96:111], v[184:187], v[204:207], v[96:111]
	ds_read_b128 v[184:187], v183 offset:4608
	ds_read_b128 v[212:215], v183 offset:4640
	s_waitcnt lgkmcnt(1)
	v_mfma_f32_32x32x16_bf16 v[80:95], v[184:187], v[192:195], v[80:95]
	v_mfma_f32_32x32x16_bf16 v[64:79], v[184:187], v[204:207], v[64:79]
	ds_read_b128 v[184:187], v183 offset:9216
	ds_read_b128 v[216:219], v183 offset:9248
	s_waitcnt lgkmcnt(1)
	v_mfma_f32_32x32x16_bf16 v[48:63], v[184:187], v[192:195], v[48:63]
	v_mfma_f32_32x32x16_bf16 v[32:47], v[184:187], v[204:207], v[32:47]
	ds_read_b128 v[184:187], v183 offset:13824
	ds_read_b128 v[220:223], v183 offset:13856
	v_mfma_f32_32x32x16_bf16 v[112:127], v[196:199], v[200:203], v[112:127]
	v_mfma_f32_32x32x16_bf16 v[96:111], v[196:199], v[208:211], v[96:111]
	s_waitcnt lgkmcnt(1)
	v_mfma_f32_32x32x16_bf16 v[16:31], v[184:187], v[192:195], v[16:31]
	v_mfma_f32_32x32x16_bf16 v[0:15], v[184:187], v[204:207], v[0:15]
	v_add_u32_e32 v184, s11, v182
	s_waitcnt vmcnt(7)
	ds_write_b128 v184, v[140:143]
	s_waitcnt vmcnt(6)
	ds_write_b128 v184, v[136:139] offset:9216
	s_waitcnt vmcnt(5)
	ds_write_b128 v184, v[132:135] offset:18432
	s_waitcnt vmcnt(3)
	ds_write_b128 v184, v[144:147] offset:27648
	ds_write_b128 v184, v[128:131] offset:36864
	s_waitcnt vmcnt(1)
	ds_write_b128 v184, v[152:155] offset:46080
	s_waitcnt vmcnt(0)
	ds_write_b128 v184, v[156:159] offset:55296
	ds_write_b128 v184, v[148:151] offset:64512
	ds_read_b128 v[128:131], v183 offset:64
	ds_read_b128 v[132:135], v160 offset:36928
	ds_read_b128 v[136:139], v183 offset:96
	ds_read_b128 v[148:151], v160 offset:36960
	ds_read_b128 v[140:143], v160 offset:41536
	ds_read_b128 v[184:187], v160 offset:41568
	s_mov_b32 s11, 0x6224000
	v_lshl_add_u64 v[156:157], v[166:167], 0, s[6:7]
	v_mfma_f32_32x32x16_bf16 v[80:95], v[212:215], v[200:203], v[80:95]
	v_lshl_add_u64 v[158:159], v[164:165], 0, s[6:7]
	v_mfma_f32_32x32x16_bf16 v[64:79], v[212:215], v[208:211], v[64:79]
	v_mfma_f32_32x32x16_bf16 v[48:63], v[216:219], v[200:203], v[48:63]
	v_mfma_f32_32x32x16_bf16 v[32:47], v[216:219], v[208:211], v[32:47]
	s_waitcnt lgkmcnt(4)
	v_mfma_f32_32x32x16_bf16 v[112:127], v[128:131], v[132:135], v[112:127]
	s_waitcnt lgkmcnt(1)
	v_mfma_f32_32x32x16_bf16 v[96:111], v[128:131], v[140:143], v[96:111]
	ds_read_b128 v[128:131], v183 offset:4672
	ds_read_b128 v[144:147], v183 offset:4704
	v_mfma_f32_32x32x16_bf16 v[16:31], v[220:223], v[200:203], v[16:31]
	v_mfma_f32_32x32x16_bf16 v[0:15], v[220:223], v[208:211], v[0:15]
	s_waitcnt lgkmcnt(1)
	v_mfma_f32_32x32x16_bf16 v[80:95], v[128:131], v[132:135], v[80:95]
	v_mfma_f32_32x32x16_bf16 v[64:79], v[128:131], v[140:143], v[64:79]
	ds_read_b128 v[128:131], v183 offset:9280
	ds_read_b128 v[152:155], v183 offset:9312
	s_waitcnt lgkmcnt(1)
	v_mfma_f32_32x32x16_bf16 v[48:63], v[128:131], v[132:135], v[48:63]
	v_mfma_f32_32x32x16_bf16 v[32:47], v[128:131], v[140:143], v[32:47]
	ds_read_b128 v[128:131], v183 offset:13888
	ds_read_b128 v[192:195], v183 offset:13920
	s_waitcnt lgkmcnt(1)
	v_mfma_f32_32x32x16_bf16 v[16:31], v[128:131], v[132:135], v[16:31]
	v_mfma_f32_32x32x16_bf16 v[0:15], v[128:131], v[140:143], v[0:15]
	v_lshl_add_u64 v[128:129], v[170:171], 0, s[6:7]
	v_add_co_u32_e32 v132, vcc, s11, v128
	v_lshl_add_u64 v[130:131], v[168:169], 0, s[6:7]
	s_nop 0
	v_addc_co_u32_e32 v133, vcc, 0, v129, vcc
	v_add_co_u32_e32 v134, vcc, s12, v128
	v_mfma_f32_32x32x16_bf16 v[80:95], v[144:147], v[148:151], v[80:95]
	s_nop 0
	v_addc_co_u32_e32 v135, vcc, 0, v129, vcc
	s_add_u32 s6, s6, 0x80
	s_addc_u32 s7, s7, 0
	s_cmpk_eq_i32 s6, 0xf00
	v_mfma_f32_32x32x16_bf16 v[64:79], v[144:147], v[184:187], v[64:79]
	v_add_co_u32_e32 v144, vcc, s13, v128
	s_nop 1
	v_addc_co_u32_e32 v145, vcc, 0, v129, vcc
	v_add_co_u32_e32 v128, vcc, s14, v128
	v_mfma_f32_32x32x16_bf16 v[112:127], v[136:139], v[148:151], v[112:127]
	s_nop 0
	v_addc_co_u32_e32 v129, vcc, 0, v129, vcc
	v_mfma_f32_32x32x16_bf16 v[96:111], v[136:139], v[184:187], v[96:111]
	v_mfma_f32_32x32x16_bf16 v[48:63], v[152:155], v[148:151], v[48:63]
	v_mfma_f32_32x32x16_bf16 v[32:47], v[152:155], v[184:187], v[32:47]
	global_load_dwordx4 v[140:143], v[132:133], off offset:256
	global_load_dwordx4 v[136:139], v[134:135], off offset:256
	s_nop 0
	global_load_dwordx4 v[132:135], v[144:145], off offset:256
	s_nop 0
	global_load_dwordx4 v[144:147], v[128:129], off offset:256
	s_nop 0
	global_load_dwordx4 v[128:131], v[130:131], off
	s_nop 0
	global_load_dwordx4 v[152:155], v[156:157], off
	s_nop 0
	global_load_dwordx4 v[156:159], v[158:159], off
	s_waitcnt lgkmcnt(0)
	v_mfma_f32_32x32x16_bf16 v[16:31], v[192:195], v[148:151], v[16:31]
	global_load_dwordx4 v[148:151], v[188:189], off
	s_barrier
	v_mfma_f32_32x32x16_bf16 v[0:15], v[192:195], v[184:187], v[0:15]
	s_cbranch_scc0 .LBB0_2005
	v_add_u32_e32 v160, v179, v181
	ds_read_b128 v[162:165], v160
	v_add_u32_e32 v170, v179, v180
	ds_read_b128 v[166:169], v170 offset:36864
	ds_read_b128 v[184:187], v160 offset:32
	ds_read_b128 v[192:195], v170 offset:36896
	ds_read_b128 v[196:199], v170 offset:41472
	ds_read_b128 v[200:203], v170 offset:41504
	s_waitcnt lgkmcnt(4)
	v_mfma_f32_32x32x16_bf16 v[112:127], v[162:165], v[166:169], v[112:127]
	s_waitcnt lgkmcnt(1)
	v_mfma_f32_32x32x16_bf16 v[96:111], v[162:165], v[196:199], v[96:111]
	ds_read_b128 v[162:165], v160 offset:4608
	ds_read_b128 v[204:207], v160 offset:4640
	s_waitcnt lgkmcnt(1)
	v_mfma_f32_32x32x16_bf16 v[80:95], v[162:165], v[166:169], v[80:95]
	v_mfma_f32_32x32x16_bf16 v[64:79], v[162:165], v[196:199], v[64:79]
	ds_read_b128 v[162:165], v160 offset:9216
	ds_read_b128 v[208:211], v160 offset:9248
	s_waitcnt lgkmcnt(1)
	v_mfma_f32_32x32x16_bf16 v[48:63], v[162:165], v[166:169], v[48:63]
	v_mfma_f32_32x32x16_bf16 v[32:47], v[162:165], v[196:199], v[32:47]
	ds_read_b128 v[162:165], v160 offset:13824
	ds_read_b128 v[212:215], v160 offset:13856
	v_mfma_f32_32x32x16_bf16 v[112:127], v[184:187], v[192:195], v[112:127]
	v_mfma_f32_32x32x16_bf16 v[96:111], v[184:187], v[200:203], v[96:111]
	s_waitcnt lgkmcnt(1)
	v_mfma_f32_32x32x16_bf16 v[16:31], v[162:165], v[166:169], v[16:31]
	v_mfma_f32_32x32x16_bf16 v[0:15], v[162:165], v[196:199], v[0:15]
	v_add_u32_e32 v162, 0x12000, v182
	s_waitcnt vmcnt(7)
	ds_write_b128 v162, v[140:143]
	s_waitcnt vmcnt(6)
	ds_write_b128 v162, v[136:139] offset:9216
	s_waitcnt vmcnt(5)
	ds_write_b128 v162, v[132:135] offset:18432
	s_waitcnt vmcnt(4)
	ds_write_b128 v162, v[144:147] offset:27648
	v_add_u32_e32 v132, 0x1b000, v182
	s_waitcnt vmcnt(3)
	ds_write_b128 v132, v[128:131]
	s_waitcnt vmcnt(2)
	ds_write_b128 v132, v[152:155] offset:9216
	s_waitcnt vmcnt(1)
	ds_write_b128 v132, v[156:159] offset:18432
	s_waitcnt vmcnt(0)
	ds_write_b128 v132, v[148:151] offset:27648
	ds_read_b128 v[128:131], v160 offset:64
	ds_read_b128 v[132:135], v170 offset:36928
	ds_read_b128 v[136:139], v160 offset:96
	ds_read_b128 v[140:143], v170 offset:36960
	ds_read_b128 v[144:147], v170 offset:41536
	ds_read_b128 v[148:151], v170 offset:41568
	v_mfma_f32_32x32x16_bf16 v[80:95], v[204:207], v[192:195], v[80:95]
	v_mfma_f32_32x32x16_bf16 v[64:79], v[204:207], v[200:203], v[64:79]
	v_mfma_f32_32x32x16_bf16 v[48:63], v[208:211], v[192:195], v[48:63]
	v_mfma_f32_32x32x16_bf16 v[32:47], v[208:211], v[200:203], v[32:47]
	s_waitcnt lgkmcnt(4)
	v_mfma_f32_32x32x16_bf16 v[112:127], v[128:131], v[132:135], v[112:127]
	s_waitcnt lgkmcnt(1)
	v_mfma_f32_32x32x16_bf16 v[96:111], v[128:131], v[144:147], v[96:111]
	ds_read_b128 v[128:131], v160 offset:4672
	ds_read_b128 v[152:155], v160 offset:4704
	v_mfma_f32_32x32x16_bf16 v[0:15], v[212:215], v[200:203], v[0:15]
	s_waitcnt lgkmcnt(1)
	v_mfma_f32_32x32x16_bf16 v[80:95], v[128:131], v[132:135], v[80:95]
	v_mfma_f32_32x32x16_bf16 v[64:79], v[128:131], v[144:147], v[64:79]
	ds_read_b128 v[128:131], v160 offset:9280
	ds_read_b128 v[156:159], v160 offset:9312
	v_mfma_f32_32x32x16_bf16 v[16:31], v[212:215], v[192:195], v[16:31]
	s_waitcnt lgkmcnt(1)
	v_mfma_f32_32x32x16_bf16 v[48:63], v[128:131], v[132:135], v[48:63]
	v_mfma_f32_32x32x16_bf16 v[32:47], v[128:131], v[144:147], v[32:47]
	ds_read_b128 v[128:131], v160 offset:13888
	ds_read_b128 v[162:165], v160 offset:13920
	s_waitcnt lgkmcnt(0)
	s_barrier
	v_mfma_f32_32x32x16_bf16 v[0:15], v[128:131], v[144:147], v[0:15]
	v_mfma_f32_32x32x16_bf16 v[16:31], v[128:131], v[132:135], v[16:31]
	v_mfma_f32_32x32x16_bf16 v[80:95], v[152:155], v[140:143], v[80:95]
	v_mfma_f32_32x32x16_bf16 v[64:79], v[152:155], v[148:151], v[64:79]
	v_add_u32_e32 v152, 0x12000, v181
	v_add_u32_e32 v144, v152, v179
	ds_read_b128 v[128:131], v144
	v_mfma_f32_32x32x16_bf16 v[112:127], v[136:139], v[140:143], v[112:127]
	v_mfma_f32_32x32x16_bf16 v[96:111], v[136:139], v[148:151], v[96:111]
	v_mfma_f32_32x32x16_bf16 v[32:47], v[156:159], v[148:151], v[32:47]
	v_mfma_f32_32x32x16_bf16 v[0:15], v[162:165], v[148:151], v[0:15]
	v_add_u32_e32 v148, 0x1b000, v180
	v_mfma_f32_32x32x16_bf16 v[48:63], v[156:159], v[140:143], v[48:63]
	v_mfma_f32_32x32x16_bf16 v[16:31], v[162:165], v[140:143], v[16:31]
	v_add_u32_e32 v140, v148, v179
	ds_read_b128 v[132:135], v140
	ds_read_b128 v[136:139], v144 offset:4608
	ds_read_b128 v[140:143], v140 offset:4608
	s_waitcnt lgkmcnt(2)
	v_mfma_f32_32x32x16_bf16 v[112:127], v[128:131], v[132:135], v[112:127]
	s_waitcnt lgkmcnt(0)
	v_mfma_f32_32x32x16_bf16 v[96:111], v[128:131], v[140:143], v[96:111]
	v_mfma_f32_32x32x16_bf16 v[80:95], v[136:139], v[132:135], v[80:95]
	v_mfma_f32_32x32x16_bf16 v[64:79], v[136:139], v[140:143], v[64:79]
	ds_read_b128 v[128:131], v144 offset:9216
	ds_read_b128 v[136:139], v144 offset:13824
	v_add_u32_e32 v144, 0x12020, v160
	s_waitcnt lgkmcnt(1)
	v_mfma_f32_32x32x16_bf16 v[48:63], v[128:131], v[132:135], v[48:63]
	s_waitcnt lgkmcnt(0)
	v_mfma_f32_32x32x16_bf16 v[16:31], v[136:139], v[132:135], v[16:31]
	v_or_b32_e32 v132, 32, v179
	v_mfma_f32_32x32x16_bf16 v[32:47], v[128:131], v[140:143], v[32:47]
	v_add_u32_e32 v128, v152, v132
	ds_read_b128 v[128:131], v128
	v_add_u32_e32 v132, v148, v132
	ds_read_b128 v[132:135], v132
	v_mfma_f32_32x32x16_bf16 v[0:15], v[136:139], v[140:143], v[0:15]
	ds_read_b128 v[136:139], v144 offset:4608
	v_add_u32_e32 v140, 0x1c220, v170
	ds_read_b128 v[140:143], v140
	s_waitcnt lgkmcnt(2)
	v_mfma_f32_32x32x16_bf16 v[112:127], v[128:131], v[132:135], v[112:127]
	s_waitcnt lgkmcnt(0)
	v_mfma_f32_32x32x16_bf16 v[96:111], v[128:131], v[140:143], v[96:111]
	v_mfma_f32_32x32x16_bf16 v[80:95], v[136:139], v[132:135], v[80:95]
	v_mfma_f32_32x32x16_bf16 v[64:79], v[136:139], v[140:143], v[64:79]
	ds_read_b128 v[128:131], v144 offset:9216
	ds_read_b128 v[136:139], v144 offset:13824
	v_add_u32_e32 v144, 0x12040, v160
	s_waitcnt lgkmcnt(1)
	v_mfma_f32_32x32x16_bf16 v[48:63], v[128:131], v[132:135], v[48:63]
	s_waitcnt lgkmcnt(0)
	v_mfma_f32_32x32x16_bf16 v[16:31], v[136:139], v[132:135], v[16:31]
	v_or_b32_e32 v132, 64, v179
	v_mfma_f32_32x32x16_bf16 v[32:47], v[128:131], v[140:143], v[32:47]
	v_add_u32_e32 v128, v152, v132
	ds_read_b128 v[128:131], v128
	v_add_u32_e32 v132, v148, v132
	ds_read_b128 v[132:135], v132
	v_mfma_f32_32x32x16_bf16 v[0:15], v[136:139], v[140:143], v[0:15]
	v_add_u32_e32 v136, 0x1c240, v170
	ds_read_b128 v[136:139], v136
	ds_read_b128 v[140:143], v144 offset:13824
	s_waitcnt lgkmcnt(2)
	v_mfma_f32_32x32x16_bf16 v[112:127], v[128:131], v[132:135], v[112:127]
	s_waitcnt lgkmcnt(1)
	v_mfma_f32_32x32x16_bf16 v[96:111], v[128:131], v[136:139], v[96:111]
	ds_read_b128 v[128:131], v144 offset:4608
	ds_read_b128 v[144:147], v144 offset:9216
	s_waitcnt lgkmcnt(1)
	v_mfma_f32_32x32x16_bf16 v[80:95], v[128:131], v[132:135], v[80:95]
	s_waitcnt lgkmcnt(0)
	v_mfma_f32_32x32x16_bf16 v[48:63], v[144:147], v[132:135], v[48:63]
	v_mfma_f32_32x32x16_bf16 v[16:31], v[140:143], v[132:135], v[16:31]
	v_or_b32_e32 v132, 0x60, v179
	v_mfma_f32_32x32x16_bf16 v[64:79], v[128:131], v[136:139], v[64:79]
	v_add_u32_e32 v128, v152, v132
	ds_read_b128 v[128:131], v128
	v_add_u32_e32 v132, v148, v132
	ds_read_b128 v[132:135], v132
	v_mfma_f32_32x32x16_bf16 v[32:47], v[144:147], v[136:139], v[32:47]
	v_add_u32_e32 v144, 0x12060, v160
	v_mfma_f32_32x32x16_bf16 v[0:15], v[140:143], v[136:139], v[0:15]
	v_add_u32_e32 v136, 0x1c260, v170
	ds_read_b128 v[136:139], v136
	ds_read_b128 v[140:143], v144 offset:13824
	s_waitcnt lgkmcnt(2)
	v_mfma_f32_32x32x16_bf16 v[112:127], v[128:131], v[132:135], v[112:127]
	s_waitcnt lgkmcnt(1)
	v_mfma_f32_32x32x16_bf16 v[96:111], v[128:131], v[136:139], v[96:111]
	ds_read_b128 v[128:131], v144 offset:4608
	ds_read_b128 v[144:147], v144 offset:9216
	s_waitcnt lgkmcnt(0)
	s_barrier
	v_mfma_f32_32x32x16_bf16 v[80:95], v[128:131], v[132:135], v[80:95]
	v_mfma_f32_32x32x16_bf16 v[64:79], v[128:131], v[136:139], v[64:79]
	v_add_u32_e32 v128, s9, v178
	v_lshl_or_b32 v128, v177, 2, v128
	v_mfma_f32_32x32x16_bf16 v[48:63], v[144:147], v[132:135], v[48:63]
	v_mfma_f32_32x32x16_bf16 v[32:47], v[144:147], v[136:139], v[32:47]
	v_mfma_f32_32x32x16_bf16 v[16:31], v[140:143], v[132:135], v[16:31]
	v_mfma_f32_32x32x16_bf16 v[0:15], v[140:143], v[136:139], v[0:15]
	s_lshr_b32 s6, s79, 3
	s_lshl_b32 s6, s6, 8
	s_and_b32 s7, s79, 7
	s_lshl_b32 s7, s7, 8
	s_cmp_lt_u32 s6, 0x2000
	s_cbranch_scc1 .Lo1_prompt
	s_sub_u32 s10, s6, 0x2000
	s_lshr_b32 s11, s10, 12
	s_add_u32 s11, s11, 1
	s_branch .Lo1_join
.Lo1_prompt:
	s_mov_b32 s10, s6
	s_mov_b32 s11, 0
.Lo1_join:
	s_nop 0
	s_lshl_b32 s20, s6, 13
	s_add_u32 s16, s90, s20
	s_addc_u32 s17, s91, 0
	s_and_b32 s17, s17, 0xffff
	s_mov_b32 s18, 0x200000
	s_mov_b32 s19, 0x20000
	s_mov_b32 s12, s16
	s_mov_b32 s13, s17
	s_mov_b32 s14, s18
	s_mov_b32 s15, s19
	s_mul_i32 s11, s11, 0xc000
	s_add_u32 s22, s92, 0x5f68000
	s_addc_u32 s23, s93, 0
	s_add_u32 s22, s22, s11
	s_addc_u32 s23, s23, 0
	v_and_b32_e32 v168, 31, v190
	v_bfe_u32 v169, v190, 5, 1
	v_bfe_u32 v170, v190, 6, 2
	v_bfe_u32 v171, v190, 8, 1
	v_lshl_add_u32 v168, v170, 6, v168
	v_add_u32_e32 v168, s7, v168
	v_lshlrev_b32_e32 v168, 2, v168
	v_lshlrev_b32_e32 v171, 7, v171
	v_lshl_add_u32 v171, v169, 2, v171
	v_lshl_add_u32 v162, v171, 13, v168
	global_load_dword v166, v168, s[22:23]
	global_load_dword v167, v168, s[22:23] offset:128
	v_add_u32_e32 v163, 0x2000, v162
	v_add_u32_e32 v164, 0x4000, v162
	v_add_u32_e32 v165, 0x6000, v162
	s_mov_b32 s20, 0x0
	buffer_load_dword v129, v162, s[12:15], s20 offen
	buffer_load_dword v130, v163, s[12:15], s20 offen
	buffer_load_dword v131, v164, s[12:15], s20 offen
	buffer_load_dword v132, v165, s[12:15], s20 offen
	s_mov_b32 s20, 0x10000
	buffer_load_dword v133, v162, s[12:15], s20 offen
	buffer_load_dword v134, v163, s[12:15], s20 offen
	buffer_load_dword v135, v164, s[12:15], s20 offen
	buffer_load_dword v136, v165, s[12:15], s20 offen
	s_mov_b32 s20, 0x20000
	buffer_load_dword v137, v162, s[12:15], s20 offen
	buffer_load_dword v138, v163, s[12:15], s20 offen
	buffer_load_dword v139, v164, s[12:15], s20 offen
	buffer_load_dword v140, v165, s[12:15], s20 offen
	s_mov_b32 s20, 0x30000
	buffer_load_dword v141, v162, s[12:15], s20 offen
	buffer_load_dword v142, v163, s[12:15], s20 offen
	buffer_load_dword v143, v164, s[12:15], s20 offen
	buffer_load_dword v144, v165, s[12:15], s20 offen
	s_mov_b32 s20, 0x0
	buffer_load_dword v145, v162, s[12:15], s20 offen offset:128
	buffer_load_dword v146, v163, s[12:15], s20 offen offset:128
	buffer_load_dword v147, v164, s[12:15], s20 offen offset:128
	buffer_load_dword v148, v165, s[12:15], s20 offen offset:128
	s_mov_b32 s20, 0x10000
	buffer_load_dword v149, v162, s[12:15], s20 offen offset:128
	buffer_load_dword v150, v163, s[12:15], s20 offen offset:128
	buffer_load_dword v151, v164, s[12:15], s20 offen offset:128
	buffer_load_dword v152, v165, s[12:15], s20 offen offset:128
	s_mov_b32 s20, 0x20000
	buffer_load_dword v153, v162, s[12:15], s20 offen offset:128
	buffer_load_dword v154, v163, s[12:15], s20 offen offset:128
	buffer_load_dword v155, v164, s[12:15], s20 offen offset:128
	buffer_load_dword v156, v165, s[12:15], s20 offen offset:128
	s_mov_b32 s20, 0x30000
	buffer_load_dword v157, v162, s[12:15], s20 offen offset:128
	buffer_load_dword v158, v163, s[12:15], s20 offen offset:128
	buffer_load_dword v159, v164, s[12:15], s20 offen offset:128
	buffer_load_dword v160, v165, s[12:15], s20 offen offset:128
	s_waitcnt vmcnt(16)
	v_fmac_f32_e32 v129, v166, v112
	v_fmac_f32_e32 v130, v166, v113
	v_fmac_f32_e32 v131, v166, v114
	v_fmac_f32_e32 v132, v166, v115
	v_fmac_f32_e32 v133, v166, v116
	v_fmac_f32_e32 v134, v166, v117
	v_fmac_f32_e32 v135, v166, v118
	v_fmac_f32_e32 v136, v166, v119
	v_fmac_f32_e32 v137, v166, v120
	v_fmac_f32_e32 v138, v166, v121
	v_fmac_f32_e32 v139, v166, v122
	v_fmac_f32_e32 v140, v166, v123
	v_fmac_f32_e32 v141, v166, v124
	v_fmac_f32_e32 v142, v166, v125
	v_fmac_f32_e32 v143, v166, v126
	v_fmac_f32_e32 v144, v166, v127
	s_mov_b32 s21, 0x0
	buffer_store_dword v129, v162, s[16:19], s21 offen
	buffer_store_dword v130, v163, s[16:19], s21 offen
	buffer_store_dword v131, v164, s[16:19], s21 offen
	buffer_store_dword v132, v165, s[16:19], s21 offen
	s_mov_b32 s21, 0x10000
	buffer_store_dword v133, v162, s[16:19], s21 offen
	buffer_store_dword v134, v163, s[16:19], s21 offen
	buffer_store_dword v135, v164, s[16:19], s21 offen
	buffer_store_dword v136, v165, s[16:19], s21 offen
	s_mov_b32 s21, 0x20000
	buffer_store_dword v137, v162, s[16:19], s21 offen
	buffer_store_dword v138, v163, s[16:19], s21 offen
	buffer_store_dword v139, v164, s[16:19], s21 offen
	buffer_store_dword v140, v165, s[16:19], s21 offen
	s_mov_b32 s21, 0x30000
	buffer_store_dword v141, v162, s[16:19], s21 offen
	buffer_store_dword v142, v163, s[16:19], s21 offen
	buffer_store_dword v143, v164, s[16:19], s21 offen
	buffer_store_dword v144, v165, s[16:19], s21 offen
	s_mov_b32 s20, 0x40000
	buffer_load_dword v129, v162, s[12:15], s20 offen
	buffer_load_dword v130, v163, s[12:15], s20 offen
	buffer_load_dword v131, v164, s[12:15], s20 offen
	buffer_load_dword v132, v165, s[12:15], s20 offen
	s_mov_b32 s20, 0x50000
	buffer_load_dword v133, v162, s[12:15], s20 offen
	buffer_load_dword v134, v163, s[12:15], s20 offen
	buffer_load_dword v135, v164, s[12:15], s20 offen
	buffer_load_dword v136, v165, s[12:15], s20 offen
	s_mov_b32 s20, 0x60000
	buffer_load_dword v137, v162, s[12:15], s20 offen
	buffer_load_dword v138, v163, s[12:15], s20 offen
	buffer_load_dword v139, v164, s[12:15], s20 offen
	buffer_load_dword v140, v165, s[12:15], s20 offen
	s_mov_b32 s20, 0x70000
	buffer_load_dword v141, v162, s[12:15], s20 offen
	buffer_load_dword v142, v163, s[12:15], s20 offen
	buffer_load_dword v143, v164, s[12:15], s20 offen
	buffer_load_dword v144, v165, s[12:15], s20 offen
	s_waitcnt vmcnt(32)
	v_fmac_f32_e32 v145, v167, v96
	v_fmac_f32_e32 v146, v167, v97
	v_fmac_f32_e32 v147, v167, v98
	v_fmac_f32_e32 v148, v167, v99
	v_fmac_f32_e32 v149, v167, v100
	v_fmac_f32_e32 v150, v167, v101
	v_fmac_f32_e32 v151, v167, v102
	v_fmac_f32_e32 v152, v167, v103
	v_fmac_f32_e32 v153, v167, v104
	v_fmac_f32_e32 v154, v167, v105
	v_fmac_f32_e32 v155, v167, v106
	v_fmac_f32_e32 v156, v167, v107
	v_fmac_f32_e32 v157, v167, v108
	v_fmac_f32_e32 v158, v167, v109
	v_fmac_f32_e32 v159, v167, v110
	v_fmac_f32_e32 v160, v167, v111
	s_mov_b32 s21, 0x0
	buffer_store_dword v145, v162, s[16:19], s21 offen offset:128
	buffer_store_dword v146, v163, s[16:19], s21 offen offset:128
	buffer_store_dword v147, v164, s[16:19], s21 offen offset:128
	buffer_store_dword v148, v165, s[16:19], s21 offen offset:128
	s_mov_b32 s21, 0x10000
	buffer_store_dword v149, v162, s[16:19], s21 offen offset:128
	buffer_store_dword v150, v163, s[16:19], s21 offen offset:128
	buffer_store_dword v151, v164, s[16:19], s21 offen offset:128
	buffer_store_dword v152, v165, s[16:19], s21 offen offset:128
	s_mov_b32 s21, 0x20000
	buffer_store_dword v153, v162, s[16:19], s21 offen offset:128
	buffer_store_dword v154, v163, s[16:19], s21 offen offset:128
	buffer_store_dword v155, v164, s[16:19], s21 offen offset:128
	buffer_store_dword v156, v165, s[16:19], s21 offen offset:128
	s_mov_b32 s21, 0x30000
	buffer_store_dword v157, v162, s[16:19], s21 offen offset:128
	buffer_store_dword v158, v163, s[16:19], s21 offen offset:128
	buffer_store_dword v159, v164, s[16:19], s21 offen offset:128
	buffer_store_dword v160, v165, s[16:19], s21 offen offset:128
	s_mov_b32 s20, 0x40000
	buffer_load_dword v145, v162, s[12:15], s20 offen offset:128
	buffer_load_dword v146, v163, s[12:15], s20 offen offset:128
	buffer_load_dword v147, v164, s[12:15], s20 offen offset:128
	buffer_load_dword v148, v165, s[12:15], s20 offen offset:128
	s_mov_b32 s20, 0x50000
	buffer_load_dword v149, v162, s[12:15], s20 offen offset:128
	buffer_load_dword v150, v163, s[12:15], s20 offen offset:128
	buffer_load_dword v151, v164, s[12:15], s20 offen offset:128
	buffer_load_dword v152, v165, s[12:15], s20 offen offset:128
	s_mov_b32 s20, 0x60000
	buffer_load_dword v153, v162, s[12:15], s20 offen offset:128
	buffer_load_dword v154, v163, s[12:15], s20 offen offset:128
	buffer_load_dword v155, v164, s[12:15], s20 offen offset:128
	buffer_load_dword v156, v165, s[12:15], s20 offen offset:128
	s_mov_b32 s20, 0x70000
	buffer_load_dword v157, v162, s[12:15], s20 offen offset:128
	buffer_load_dword v158, v163, s[12:15], s20 offen offset:128
	buffer_load_dword v159, v164, s[12:15], s20 offen offset:128
	buffer_load_dword v160, v165, s[12:15], s20 offen offset:128
	s_waitcnt vmcnt(32)
	v_fmac_f32_e32 v129, v166, v80
	v_fmac_f32_e32 v130, v166, v81
	v_fmac_f32_e32 v131, v166, v82
	v_fmac_f32_e32 v132, v166, v83
	v_fmac_f32_e32 v133, v166, v84
	v_fmac_f32_e32 v134, v166, v85
	v_fmac_f32_e32 v135, v166, v86
	v_fmac_f32_e32 v136, v166, v87
	v_fmac_f32_e32 v137, v166, v88
	v_fmac_f32_e32 v138, v166, v89
	v_fmac_f32_e32 v139, v166, v90
	v_fmac_f32_e32 v140, v166, v91
	v_fmac_f32_e32 v141, v166, v92
	v_fmac_f32_e32 v142, v166, v93
	v_fmac_f32_e32 v143, v166, v94
	v_fmac_f32_e32 v144, v166, v95
	s_mov_b32 s21, 0x40000
	buffer_store_dword v129, v162, s[16:19], s21 offen
	buffer_store_dword v130, v163, s[16:19], s21 offen
	buffer_store_dword v131, v164, s[16:19], s21 offen
	buffer_store_dword v132, v165, s[16:19], s21 offen
	s_mov_b32 s21, 0x50000
	buffer_store_dword v133, v162, s[16:19], s21 offen
	buffer_store_dword v134, v163, s[16:19], s21 offen
	buffer_store_dword v135, v164, s[16:19], s21 offen
	buffer_store_dword v136, v165, s[16:19], s21 offen
	s_mov_b32 s21, 0x60000
	buffer_store_dword v137, v162, s[16:19], s21 offen
	buffer_store_dword v138, v163, s[16:19], s21 offen
	buffer_store_dword v139, v164, s[16:19], s21 offen
	buffer_store_dword v140, v165, s[16:19], s21 offen
	s_mov_b32 s21, 0x70000
	buffer_store_dword v141, v162, s[16:19], s21 offen
	buffer_store_dword v142, v163, s[16:19], s21 offen
	buffer_store_dword v143, v164, s[16:19], s21 offen
	buffer_store_dword v144, v165, s[16:19], s21 offen
	s_mov_b32 s20, 0x80000
	buffer_load_dword v129, v162, s[12:15], s20 offen
	buffer_load_dword v130, v163, s[12:15], s20 offen
	buffer_load_dword v131, v164, s[12:15], s20 offen
	buffer_load_dword v132, v165, s[12:15], s20 offen
	s_mov_b32 s20, 0x90000
	buffer_load_dword v133, v162, s[12:15], s20 offen
	buffer_load_dword v134, v163, s[12:15], s20 offen
	buffer_load_dword v135, v164, s[12:15], s20 offen
	buffer_load_dword v136, v165, s[12:15], s20 offen
	s_mov_b32 s20, 0xa0000
	buffer_load_dword v137, v162, s[12:15], s20 offen
	buffer_load_dword v138, v163, s[12:15], s20 offen
	buffer_load_dword v139, v164, s[12:15], s20 offen
	buffer_load_dword v140, v165, s[12:15], s20 offen
	s_mov_b32 s20, 0xb0000
	buffer_load_dword v141, v162, s[12:15], s20 offen
	buffer_load_dword v142, v163, s[12:15], s20 offen
	buffer_load_dword v143, v164, s[12:15], s20 offen
	buffer_load_dword v144, v165, s[12:15], s20 offen
	s_waitcnt vmcnt(32)
	v_fmac_f32_e32 v145, v167, v64
	v_fmac_f32_e32 v146, v167, v65
	v_fmac_f32_e32 v147, v167, v66
	v_fmac_f32_e32 v148, v167, v67
	v_fmac_f32_e32 v149, v167, v68
	v_fmac_f32_e32 v150, v167, v69
	v_fmac_f32_e32 v151, v167, v70
	v_fmac_f32_e32 v152, v167, v71
	v_fmac_f32_e32 v153, v167, v72
	v_fmac_f32_e32 v154, v167, v73
	v_fmac_f32_e32 v155, v167, v74
	v_fmac_f32_e32 v156, v167, v75
	v_fmac_f32_e32 v157, v167, v76
	v_fmac_f32_e32 v158, v167, v77
	v_fmac_f32_e32 v159, v167, v78
	v_fmac_f32_e32 v160, v167, v79
	s_mov_b32 s21, 0x40000
	buffer_store_dword v145, v162, s[16:19], s21 offen offset:128
	buffer_store_dword v146, v163, s[16:19], s21 offen offset:128
	buffer_store_dword v147, v164, s[16:19], s21 offen offset:128
	buffer_store_dword v148, v165, s[16:19], s21 offen offset:128
	s_mov_b32 s21, 0x50000
	buffer_store_dword v149, v162, s[16:19], s21 offen offset:128
	buffer_store_dword v150, v163, s[16:19], s21 offen offset:128
	buffer_store_dword v151, v164, s[16:19], s21 offen offset:128
	buffer_store_dword v152, v165, s[16:19], s21 offen offset:128
	s_mov_b32 s21, 0x60000
	buffer_store_dword v153, v162, s[16:19], s21 offen offset:128
	buffer_store_dword v154, v163, s[16:19], s21 offen offset:128
	buffer_store_dword v155, v164, s[16:19], s21 offen offset:128
	buffer_store_dword v156, v165, s[16:19], s21 offen offset:128
	s_mov_b32 s21, 0x70000
	buffer_store_dword v157, v162, s[16:19], s21 offen offset:128
	buffer_store_dword v158, v163, s[16:19], s21 offen offset:128
	buffer_store_dword v159, v164, s[16:19], s21 offen offset:128
	buffer_store_dword v160, v165, s[16:19], s21 offen offset:128
	s_mov_b32 s20, 0x80000
	buffer_load_dword v145, v162, s[12:15], s20 offen offset:128
	buffer_load_dword v146, v163, s[12:15], s20 offen offset:128
	buffer_load_dword v147, v164, s[12:15], s20 offen offset:128
	buffer_load_dword v148, v165, s[12:15], s20 offen offset:128
	s_mov_b32 s20, 0x90000
	buffer_load_dword v149, v162, s[12:15], s20 offen offset:128
	buffer_load_dword v150, v163, s[12:15], s20 offen offset:128
	buffer_load_dword v151, v164, s[12:15], s20 offen offset:128
	buffer_load_dword v152, v165, s[12:15], s20 offen offset:128
	s_mov_b32 s20, 0xa0000
	buffer_load_dword v153, v162, s[12:15], s20 offen offset:128
	buffer_load_dword v154, v163, s[12:15], s20 offen offset:128
	buffer_load_dword v155, v164, s[12:15], s20 offen offset:128
	buffer_load_dword v156, v165, s[12:15], s20 offen offset:128
	s_mov_b32 s20, 0xb0000
	buffer_load_dword v157, v162, s[12:15], s20 offen offset:128
	buffer_load_dword v158, v163, s[12:15], s20 offen offset:128
	buffer_load_dword v159, v164, s[12:15], s20 offen offset:128
	buffer_load_dword v160, v165, s[12:15], s20 offen offset:128
	s_waitcnt vmcnt(32)
	v_fmac_f32_e32 v129, v166, v48
	v_fmac_f32_e32 v130, v166, v49
	v_fmac_f32_e32 v131, v166, v50
	v_fmac_f32_e32 v132, v166, v51
	v_fmac_f32_e32 v133, v166, v52
	v_fmac_f32_e32 v134, v166, v53
	v_fmac_f32_e32 v135, v166, v54
	v_fmac_f32_e32 v136, v166, v55
	v_fmac_f32_e32 v137, v166, v56
	v_fmac_f32_e32 v138, v166, v57
	v_fmac_f32_e32 v139, v166, v58
	v_fmac_f32_e32 v140, v166, v59
	v_fmac_f32_e32 v141, v166, v60
	v_fmac_f32_e32 v142, v166, v61
	v_fmac_f32_e32 v143, v166, v62
	v_fmac_f32_e32 v144, v166, v63
	s_mov_b32 s21, 0x80000
	buffer_store_dword v129, v162, s[16:19], s21 offen
	buffer_store_dword v130, v163, s[16:19], s21 offen
	buffer_store_dword v131, v164, s[16:19], s21 offen
	buffer_store_dword v132, v165, s[16:19], s21 offen
	s_mov_b32 s21, 0x90000
	buffer_store_dword v133, v162, s[16:19], s21 offen
	buffer_store_dword v134, v163, s[16:19], s21 offen
	buffer_store_dword v135, v164, s[16:19], s21 offen
	buffer_store_dword v136, v165, s[16:19], s21 offen
	s_mov_b32 s21, 0xa0000
	buffer_store_dword v137, v162, s[16:19], s21 offen
	buffer_store_dword v138, v163, s[16:19], s21 offen
	buffer_store_dword v139, v164, s[16:19], s21 offen
	buffer_store_dword v140, v165, s[16:19], s21 offen
	s_mov_b32 s21, 0xb0000
	buffer_store_dword v141, v162, s[16:19], s21 offen
	buffer_store_dword v142, v163, s[16:19], s21 offen
	buffer_store_dword v143, v164, s[16:19], s21 offen
	buffer_store_dword v144, v165, s[16:19], s21 offen
	s_mov_b32 s20, 0xc0000
	buffer_load_dword v129, v162, s[12:15], s20 offen
	buffer_load_dword v130, v163, s[12:15], s20 offen
	buffer_load_dword v131, v164, s[12:15], s20 offen
	buffer_load_dword v132, v165, s[12:15], s20 offen
	s_mov_b32 s20, 0xd0000
	buffer_load_dword v133, v162, s[12:15], s20 offen
	buffer_load_dword v134, v163, s[12:15], s20 offen
	buffer_load_dword v135, v164, s[12:15], s20 offen
	buffer_load_dword v136, v165, s[12:15], s20 offen
	s_mov_b32 s20, 0xe0000
	buffer_load_dword v137, v162, s[12:15], s20 offen
	buffer_load_dword v138, v163, s[12:15], s20 offen
	buffer_load_dword v139, v164, s[12:15], s20 offen
	buffer_load_dword v140, v165, s[12:15], s20 offen
	s_mov_b32 s20, 0xf0000
	buffer_load_dword v141, v162, s[12:15], s20 offen
	buffer_load_dword v142, v163, s[12:15], s20 offen
	buffer_load_dword v143, v164, s[12:15], s20 offen
	buffer_load_dword v144, v165, s[12:15], s20 offen
	s_waitcnt vmcnt(32)
	v_fmac_f32_e32 v145, v167, v32
	v_fmac_f32_e32 v146, v167, v33
	v_fmac_f32_e32 v147, v167, v34
	v_fmac_f32_e32 v148, v167, v35
	v_fmac_f32_e32 v149, v167, v36
	v_fmac_f32_e32 v150, v167, v37
	v_fmac_f32_e32 v151, v167, v38
	v_fmac_f32_e32 v152, v167, v39
	v_fmac_f32_e32 v153, v167, v40
	v_fmac_f32_e32 v154, v167, v41
	v_fmac_f32_e32 v155, v167, v42
	v_fmac_f32_e32 v156, v167, v43
	v_fmac_f32_e32 v157, v167, v44
	v_fmac_f32_e32 v158, v167, v45
	v_fmac_f32_e32 v159, v167, v46
	v_fmac_f32_e32 v160, v167, v47
	s_mov_b32 s21, 0x80000
	buffer_store_dword v145, v162, s[16:19], s21 offen offset:128
	buffer_store_dword v146, v163, s[16:19], s21 offen offset:128
	buffer_store_dword v147, v164, s[16:19], s21 offen offset:128
	buffer_store_dword v148, v165, s[16:19], s21 offen offset:128
	s_mov_b32 s21, 0x90000
	buffer_store_dword v149, v162, s[16:19], s21 offen offset:128
	buffer_store_dword v150, v163, s[16:19], s21 offen offset:128
	buffer_store_dword v151, v164, s[16:19], s21 offen offset:128
	buffer_store_dword v152, v165, s[16:19], s21 offen offset:128
	s_mov_b32 s21, 0xa0000
	buffer_store_dword v153, v162, s[16:19], s21 offen offset:128
	buffer_store_dword v154, v163, s[16:19], s21 offen offset:128
	buffer_store_dword v155, v164, s[16:19], s21 offen offset:128
	buffer_store_dword v156, v165, s[16:19], s21 offen offset:128
	s_mov_b32 s21, 0xb0000
	buffer_store_dword v157, v162, s[16:19], s21 offen offset:128
	buffer_store_dword v158, v163, s[16:19], s21 offen offset:128
	buffer_store_dword v159, v164, s[16:19], s21 offen offset:128
	buffer_store_dword v160, v165, s[16:19], s21 offen offset:128
	s_mov_b32 s20, 0xc0000
	buffer_load_dword v145, v162, s[12:15], s20 offen offset:128
	buffer_load_dword v146, v163, s[12:15], s20 offen offset:128
	buffer_load_dword v147, v164, s[12:15], s20 offen offset:128
	buffer_load_dword v148, v165, s[12:15], s20 offen offset:128
	s_mov_b32 s20, 0xd0000
	buffer_load_dword v149, v162, s[12:15], s20 offen offset:128
	buffer_load_dword v150, v163, s[12:15], s20 offen offset:128
	buffer_load_dword v151, v164, s[12:15], s20 offen offset:128
	buffer_load_dword v152, v165, s[12:15], s20 offen offset:128
	s_mov_b32 s20, 0xe0000
	buffer_load_dword v153, v162, s[12:15], s20 offen offset:128
	buffer_load_dword v154, v163, s[12:15], s20 offen offset:128
	buffer_load_dword v155, v164, s[12:15], s20 offen offset:128
	buffer_load_dword v156, v165, s[12:15], s20 offen offset:128
	s_mov_b32 s20, 0xf0000
	buffer_load_dword v157, v162, s[12:15], s20 offen offset:128
	buffer_load_dword v158, v163, s[12:15], s20 offen offset:128
	buffer_load_dword v159, v164, s[12:15], s20 offen offset:128
	buffer_load_dword v160, v165, s[12:15], s20 offen offset:128
	s_waitcnt vmcnt(32)
	v_fmac_f32_e32 v129, v166, v16
	v_fmac_f32_e32 v130, v166, v17
	v_fmac_f32_e32 v131, v166, v18
	v_fmac_f32_e32 v132, v166, v19
	v_fmac_f32_e32 v133, v166, v20
	v_fmac_f32_e32 v134, v166, v21
	v_fmac_f32_e32 v135, v166, v22
	v_fmac_f32_e32 v136, v166, v23
	v_fmac_f32_e32 v137, v166, v24
	v_fmac_f32_e32 v138, v166, v25
	v_fmac_f32_e32 v139, v166, v26
	v_fmac_f32_e32 v140, v166, v27
	v_fmac_f32_e32 v141, v166, v28
	v_fmac_f32_e32 v142, v166, v29
	v_fmac_f32_e32 v143, v166, v30
	v_fmac_f32_e32 v144, v166, v31
	s_mov_b32 s21, 0xc0000
	buffer_store_dword v129, v162, s[16:19], s21 offen
	buffer_store_dword v130, v163, s[16:19], s21 offen
	buffer_store_dword v131, v164, s[16:19], s21 offen
	buffer_store_dword v132, v165, s[16:19], s21 offen
	s_mov_b32 s21, 0xd0000
	buffer_store_dword v133, v162, s[16:19], s21 offen
	buffer_store_dword v134, v163, s[16:19], s21 offen
	buffer_store_dword v135, v164, s[16:19], s21 offen
	buffer_store_dword v136, v165, s[16:19], s21 offen
	s_mov_b32 s21, 0xe0000
	buffer_store_dword v137, v162, s[16:19], s21 offen
	buffer_store_dword v138, v163, s[16:19], s21 offen
	buffer_store_dword v139, v164, s[16:19], s21 offen
	buffer_store_dword v140, v165, s[16:19], s21 offen
	s_mov_b32 s21, 0xf0000
	buffer_store_dword v141, v162, s[16:19], s21 offen
	buffer_store_dword v142, v163, s[16:19], s21 offen
	buffer_store_dword v143, v164, s[16:19], s21 offen
	buffer_store_dword v144, v165, s[16:19], s21 offen
	s_waitcnt vmcnt(16)
	v_fmac_f32_e32 v145, v167, v0
	v_fmac_f32_e32 v146, v167, v1
	v_fmac_f32_e32 v147, v167, v2
	v_fmac_f32_e32 v148, v167, v3
	v_fmac_f32_e32 v149, v167, v4
	v_fmac_f32_e32 v150, v167, v5
	v_fmac_f32_e32 v151, v167, v6
	v_fmac_f32_e32 v152, v167, v7
	v_fmac_f32_e32 v153, v167, v8
	v_fmac_f32_e32 v154, v167, v9
	v_fmac_f32_e32 v155, v167, v10
	v_fmac_f32_e32 v156, v167, v11
	v_fmac_f32_e32 v157, v167, v12
	v_fmac_f32_e32 v158, v167, v13
	v_fmac_f32_e32 v159, v167, v14
	v_fmac_f32_e32 v160, v167, v15
	s_mov_b32 s21, 0xc0000
	buffer_store_dword v145, v162, s[16:19], s21 offen offset:128
	buffer_store_dword v146, v163, s[16:19], s21 offen offset:128
	buffer_store_dword v147, v164, s[16:19], s21 offen offset:128
	buffer_store_dword v148, v165, s[16:19], s21 offen offset:128
	s_mov_b32 s21, 0xd0000
	buffer_store_dword v149, v162, s[16:19], s21 offen offset:128
	buffer_store_dword v150, v163, s[16:19], s21 offen offset:128
	buffer_store_dword v151, v164, s[16:19], s21 offen offset:128
	buffer_store_dword v152, v165, s[16:19], s21 offen offset:128
	s_mov_b32 s21, 0xe0000
	buffer_store_dword v153, v162, s[16:19], s21 offen offset:128
	buffer_store_dword v154, v163, s[16:19], s21 offen offset:128
	buffer_store_dword v155, v164, s[16:19], s21 offen offset:128
	buffer_store_dword v156, v165, s[16:19], s21 offen offset:128
	s_mov_b32 s21, 0xf0000
	buffer_store_dword v157, v162, s[16:19], s21 offen offset:128
	buffer_store_dword v158, v163, s[16:19], s21 offen offset:128
	buffer_store_dword v159, v164, s[16:19], s21 offen offset:128
	buffer_store_dword v160, v165, s[16:19], s21 offen offset:128
	s_add_i32 s79, s79, s94
	s_cmpk_lt_i32 s79, 0x200
	s_cbranch_scc1 .LBB0_2004
	s_branch .LBB0_2518
